# S5: S4 + K-loop load segments issue all ds_read_b128 first, SALU pointer/m0 work and LDS-DMAs after (42 segments)
# baseline (speedup 1.0000x reference)
.Ldefbar_skip_0:
	v_add_u32_e32 v250, 0x10000, v141
	ds_read_b128 v[144:147], v250
	ds_read_b128 v[148:151], v250 offset:1024
	ds_read_b128 v[152:155], v250 offset:2048
	ds_read_b128 v[156:159], v250 offset:3072
	ds_read_b128 v[160:163], v250 offset:16384
	ds_read_b128 v[164:167], v250 offset:17408
	ds_read_b128 v[168:171], v250 offset:18432
	ds_read_b128 v[172:175], v250 offset:19456
	ds_read_b128 v[176:179], v143
	ds_read_b128 v[180:183], v143 offset:1024
	ds_read_b128 v[184:187], v143 offset:2048
	ds_read_b128 v[188:191], v143 offset:3072
	ds_read_b128 v[192:195], v143 offset:4096
	ds_read_b128 v[202:205], v143 offset:5120
	ds_read_b128 v[206:209], v143 offset:6144
	ds_read_b128 v[210:213], v143 offset:7168
	s_add_i32 s69, s8, 2
	s_add_u32 s0, s52, 0xfff80080
	s_addc_u32 s1, s53, -1
	s_add_i32 s70, 0, 0x10000
	s_cmp_eq_u32 s66, s8
	s_cselect_b32 s59, s41, s1
	s_cselect_b32 s58, s45, s0
	s_cselect_b32 s9, s43, s68
	s_cselect_b32 s8, s65, s67
	s_add_i32 s0, 0, 0x14000
	s_add_i32 m0, s27, 0xc000
	s_nop 0
	global_load_lds_dwordx4 v138, s[52:53]
	s_add_i32 m0, s27, 0xe000
	s_nop 0
	global_load_lds_dwordx4 v136, s[52:53]
	s_waitcnt vmcnt(8)
	s_waitcnt lgkmcnt(0)
	s_setprio 1
	s_barrier
	v_mfma_f32_16x16x32_bf16 v[126:129], v[144:147], v[176:179], 0
	v_mfma_f32_16x16x32_bf16 v[118:121], v[152:155], v[176:179], 0
	v_mfma_f32_16x16x32_bf16 v[110:113], v[144:147], v[184:187], 0
	v_mfma_f32_16x16x32_bf16 v[102:105], v[152:155], v[184:187], 0
	v_mfma_f32_16x16x32_bf16 v[94:97], v[144:147], v[192:195], 0
	v_mfma_f32_16x16x32_bf16 v[86:89], v[152:155], v[192:195], 0
	v_mfma_f32_16x16x32_bf16 v[78:81], v[144:147], v[206:209], 0
	v_mfma_f32_16x16x32_bf16 v[70:73], v[152:155], v[206:209], 0
	v_mfma_f32_16x16x32_bf16 v[126:129], v[148:151], v[180:183], v[126:129]
	v_mfma_f32_16x16x32_bf16 v[118:121], v[156:159], v[180:183], v[118:121]
	v_mfma_f32_16x16x32_bf16 v[110:113], v[148:151], v[188:191], v[110:113]
	v_mfma_f32_16x16x32_bf16 v[102:105], v[156:159], v[188:191], v[102:105]
	v_mfma_f32_16x16x32_bf16 v[94:97], v[148:151], v[202:205], v[94:97]
	v_mfma_f32_16x16x32_bf16 v[86:89], v[156:159], v[202:205], v[86:89]
	v_mfma_f32_16x16x32_bf16 v[78:81], v[148:151], v[210:213], v[78:81]
	v_mfma_f32_16x16x32_bf16 v[70:73], v[156:159], v[210:213], v[70:73]
	v_mfma_f32_16x16x32_bf16 v[122:125], v[160:163], v[176:179], 0
	v_mfma_f32_16x16x32_bf16 v[114:117], v[168:171], v[176:179], 0
	v_mfma_f32_16x16x32_bf16 v[106:109], v[160:163], v[184:187], 0
	v_mfma_f32_16x16x32_bf16 v[98:101], v[168:171], v[184:187], 0
	v_mfma_f32_16x16x32_bf16 v[90:93], v[160:163], v[192:195], 0
	v_mfma_f32_16x16x32_bf16 v[82:85], v[168:171], v[192:195], 0
	v_mfma_f32_16x16x32_bf16 v[74:77], v[160:163], v[206:209], 0
	v_mfma_f32_16x16x32_bf16 v[66:69], v[168:171], v[206:209], 0
	v_mfma_f32_16x16x32_bf16 v[122:125], v[164:167], v[180:183], v[122:125]
	v_mfma_f32_16x16x32_bf16 v[114:117], v[172:175], v[180:183], v[114:117]
	v_mfma_f32_16x16x32_bf16 v[106:109], v[164:167], v[188:191], v[106:109]
	v_mfma_f32_16x16x32_bf16 v[98:101], v[172:175], v[188:191], v[98:101]
	v_mfma_f32_16x16x32_bf16 v[90:93], v[164:167], v[202:205], v[90:93]
	v_mfma_f32_16x16x32_bf16 v[82:85], v[172:175], v[202:205], v[82:85]
	v_mfma_f32_16x16x32_bf16 v[74:77], v[164:167], v[210:213], v[74:77]
	v_mfma_f32_16x16x32_bf16 v[66:69], v[172:175], v[210:213], v[66:69]
	s_barrier
	s_setprio 0
	ds_read_b128 v[176:179], v143 offset:16384
	ds_read_b128 v[180:183], v143 offset:17408
	ds_read_b128 v[184:187], v143 offset:18432
	ds_read_b128 v[188:191], v143 offset:19456
	ds_read_b128 v[192:195], v143 offset:20480
	ds_read_b128 v[202:205], v143 offset:21504
	ds_read_b128 v[206:209], v143 offset:22528
	ds_read_b128 v[210:213], v143 offset:23552
	s_add_i32 s1, s70, s26
	s_add_u32 s98, s8, s16
	s_addc_u32 s99, s9, s17
	s_mov_b32 m0, s1
	s_nop 0
	global_load_lds_dwordx4 v196, s[8:9]
	s_add_i32 m0, s1, 0x2000
	s_add_u32 s70, s8, 0x80000
	s_addc_u32 s71, s9, 0
	s_add_i32 s0, s0, s26
	global_load_lds_dwordx4 v130, s[8:9]
	s_mov_b32 m0, s0
	s_nop 0
	global_load_lds_dwordx4 v196, s[70:71]
	s_add_i32 m0, s0, 0x2000
	s_nop 0
	global_load_lds_dwordx4 v130, s[70:71]
	s_add_u32 s78, s58, s16
	s_addc_u32 s79, s59, s17
	s_mov_b32 m0, s27
	s_nop 0
	global_load_lds_dwordx4 v134, s[58:59]
	s_mov_b32 m0, s28
	s_nop 0
	global_load_lds_dwordx4 v132, s[58:59]
	s_waitcnt vmcnt(8)
	s_waitcnt lgkmcnt(0)
	s_setprio 1
	s_barrier
	v_mfma_f32_16x16x32_bf16 v[62:65], v[144:147], v[176:179], 0
	v_mfma_f32_16x16x32_bf16 v[54:57], v[152:155], v[176:179], 0
	v_mfma_f32_16x16x32_bf16 v[46:49], v[144:147], v[184:187], 0
	v_mfma_f32_16x16x32_bf16 v[38:41], v[152:155], v[184:187], 0
	v_mfma_f32_16x16x32_bf16 v[30:33], v[144:147], v[192:195], 0
	v_mfma_f32_16x16x32_bf16 v[22:25], v[152:155], v[192:195], 0
	v_mfma_f32_16x16x32_bf16 v[14:17], v[144:147], v[206:209], 0
	v_mfma_f32_16x16x32_bf16 v[6:9], v[152:155], v[206:209], 0
	v_mfma_f32_16x16x32_bf16 v[62:65], v[148:151], v[180:183], v[62:65]
	v_mfma_f32_16x16x32_bf16 v[54:57], v[156:159], v[180:183], v[54:57]
	v_mfma_f32_16x16x32_bf16 v[46:49], v[148:151], v[188:191], v[46:49]
	v_mfma_f32_16x16x32_bf16 v[38:41], v[156:159], v[188:191], v[38:41]
	v_mfma_f32_16x16x32_bf16 v[30:33], v[148:151], v[202:205], v[30:33]
	v_mfma_f32_16x16x32_bf16 v[22:25], v[156:159], v[202:205], v[22:25]
	v_mfma_f32_16x16x32_bf16 v[14:17], v[148:151], v[210:213], v[14:17]
	v_mfma_f32_16x16x32_bf16 v[6:9], v[156:159], v[210:213], v[6:9]
	v_mfma_f32_16x16x32_bf16 v[58:61], v[160:163], v[176:179], 0
	v_mfma_f32_16x16x32_bf16 v[50:53], v[168:171], v[176:179], 0
	v_mfma_f32_16x16x32_bf16 v[42:45], v[160:163], v[184:187], 0
	v_mfma_f32_16x16x32_bf16 v[34:37], v[168:171], v[184:187], 0
	v_mfma_f32_16x16x32_bf16 v[26:29], v[160:163], v[192:195], 0
	v_mfma_f32_16x16x32_bf16 v[18:21], v[168:171], v[192:195], 0
	v_mfma_f32_16x16x32_bf16 v[10:13], v[160:163], v[206:209], 0
	v_mfma_f32_16x16x32_bf16 v[2:5], v[168:171], v[206:209], 0
	v_mfma_f32_16x16x32_bf16 v[58:61], v[164:167], v[180:183], v[58:61]
	v_mfma_f32_16x16x32_bf16 v[50:53], v[172:175], v[180:183], v[50:53]
	v_mfma_f32_16x16x32_bf16 v[42:45], v[164:167], v[188:191], v[42:45]
	v_mfma_f32_16x16x32_bf16 v[34:37], v[172:175], v[188:191], v[34:37]
	v_mfma_f32_16x16x32_bf16 v[26:29], v[164:167], v[202:205], v[26:29]
	v_mfma_f32_16x16x32_bf16 v[18:21], v[172:175], v[202:205], v[18:21]
	v_mfma_f32_16x16x32_bf16 v[10:13], v[164:167], v[210:213], v[10:13]
	v_mfma_f32_16x16x32_bf16 v[2:5], v[172:175], v[210:213], v[2:5]
	s_barrier
	s_setprio 0
	s_branch .Lkmid_0
.LBB0_904:
	ds_read_b128 v[144:147], v250
	ds_read_b128 v[148:151], v250 offset:1024
	ds_read_b128 v[152:155], v250 offset:2048
	ds_read_b128 v[156:159], v250 offset:3072
	ds_read_b128 v[160:163], v250 offset:16384
	ds_read_b128 v[164:167], v250 offset:17408
	ds_read_b128 v[168:171], v250 offset:18432
	ds_read_b128 v[172:175], v250 offset:19456
	ds_read_b128 v[176:179], v143
	ds_read_b128 v[180:183], v143 offset:1024
	ds_read_b128 v[184:187], v143 offset:2048
	ds_read_b128 v[188:191], v143 offset:3072
	ds_read_b128 v[192:195], v143 offset:4096
	ds_read_b128 v[202:205], v143 offset:5120
	ds_read_b128 v[206:209], v143 offset:6144
	ds_read_b128 v[210:213], v143 offset:7168
	s_add_i32 s69, s8, 2
	s_add_u32 s0, s52, 0xfff80080
	s_addc_u32 s1, s53, -1
	s_add_i32 s70, 0, 0x10000
	s_cmp_eq_u32 s66, s8
	s_cselect_b32 s59, s41, s1
	s_cselect_b32 s58, s45, s0
	s_cselect_b32 s9, s43, s68
	s_cselect_b32 s8, s65, s67
	s_add_i32 s0, 0, 0x14000
	s_add_i32 m0, s27, 0xc000
	s_nop 0
	global_load_lds_dwordx4 v138, s[52:53]
	s_add_i32 m0, s27, 0xe000
	s_nop 0
	global_load_lds_dwordx4 v136, s[52:53]
	s_waitcnt vmcnt(8)
	s_waitcnt lgkmcnt(0)
	s_setprio 1
	s_barrier
	v_mfma_f32_16x16x32_bf16 v[126:129], v[144:147], v[176:179], v[126:129]
	v_mfma_f32_16x16x32_bf16 v[118:121], v[152:155], v[176:179], v[118:121]
	v_mfma_f32_16x16x32_bf16 v[110:113], v[144:147], v[184:187], v[110:113]
	v_mfma_f32_16x16x32_bf16 v[102:105], v[152:155], v[184:187], v[102:105]
	v_mfma_f32_16x16x32_bf16 v[94:97], v[144:147], v[192:195], v[94:97]
	v_mfma_f32_16x16x32_bf16 v[86:89], v[152:155], v[192:195], v[86:89]
	v_mfma_f32_16x16x32_bf16 v[78:81], v[144:147], v[206:209], v[78:81]
	v_mfma_f32_16x16x32_bf16 v[70:73], v[152:155], v[206:209], v[70:73]
	v_mfma_f32_16x16x32_bf16 v[126:129], v[148:151], v[180:183], v[126:129]
	v_mfma_f32_16x16x32_bf16 v[118:121], v[156:159], v[180:183], v[118:121]
	v_mfma_f32_16x16x32_bf16 v[110:113], v[148:151], v[188:191], v[110:113]
	v_mfma_f32_16x16x32_bf16 v[102:105], v[156:159], v[188:191], v[102:105]
	v_mfma_f32_16x16x32_bf16 v[94:97], v[148:151], v[202:205], v[94:97]
	v_mfma_f32_16x16x32_bf16 v[86:89], v[156:159], v[202:205], v[86:89]
	v_mfma_f32_16x16x32_bf16 v[78:81], v[148:151], v[210:213], v[78:81]
	v_mfma_f32_16x16x32_bf16 v[70:73], v[156:159], v[210:213], v[70:73]
	v_mfma_f32_16x16x32_bf16 v[122:125], v[160:163], v[176:179], v[122:125]
	v_mfma_f32_16x16x32_bf16 v[114:117], v[168:171], v[176:179], v[114:117]
	v_mfma_f32_16x16x32_bf16 v[106:109], v[160:163], v[184:187], v[106:109]
	v_mfma_f32_16x16x32_bf16 v[98:101], v[168:171], v[184:187], v[98:101]
	v_mfma_f32_16x16x32_bf16 v[90:93], v[160:163], v[192:195], v[90:93]
	v_mfma_f32_16x16x32_bf16 v[82:85], v[168:171], v[192:195], v[82:85]
	v_mfma_f32_16x16x32_bf16 v[74:77], v[160:163], v[206:209], v[74:77]
	v_mfma_f32_16x16x32_bf16 v[66:69], v[168:171], v[206:209], v[66:69]
	v_mfma_f32_16x16x32_bf16 v[122:125], v[164:167], v[180:183], v[122:125]
	v_mfma_f32_16x16x32_bf16 v[114:117], v[172:175], v[180:183], v[114:117]
	v_mfma_f32_16x16x32_bf16 v[106:109], v[164:167], v[188:191], v[106:109]
	v_mfma_f32_16x16x32_bf16 v[98:101], v[172:175], v[188:191], v[98:101]
	v_mfma_f32_16x16x32_bf16 v[90:93], v[164:167], v[202:205], v[90:93]
	v_mfma_f32_16x16x32_bf16 v[82:85], v[172:175], v[202:205], v[82:85]
	v_mfma_f32_16x16x32_bf16 v[74:77], v[164:167], v[210:213], v[74:77]
	v_mfma_f32_16x16x32_bf16 v[66:69], v[172:175], v[210:213], v[66:69]
	s_barrier
	s_setprio 0
	ds_read_b128 v[176:179], v143 offset:16384
	ds_read_b128 v[180:183], v143 offset:17408
	ds_read_b128 v[184:187], v143 offset:18432
	ds_read_b128 v[188:191], v143 offset:19456
	ds_read_b128 v[192:195], v143 offset:20480
	ds_read_b128 v[202:205], v143 offset:21504
	ds_read_b128 v[206:209], v143 offset:22528
	ds_read_b128 v[210:213], v143 offset:23552
	s_add_i32 s1, s70, s26
	s_add_u32 s98, s8, s16
	s_addc_u32 s99, s9, s17
	s_mov_b32 m0, s1
	s_nop 0
	global_load_lds_dwordx4 v196, s[8:9]
	s_add_i32 m0, s1, 0x2000
	s_add_u32 s70, s8, 0x80000
	s_addc_u32 s71, s9, 0
	s_add_i32 s0, s0, s26
	global_load_lds_dwordx4 v130, s[8:9]
	s_mov_b32 m0, s0
	s_nop 0
	global_load_lds_dwordx4 v196, s[70:71]
	s_add_i32 m0, s0, 0x2000
	s_nop 0
	global_load_lds_dwordx4 v130, s[70:71]
	s_add_u32 s78, s58, s16
	s_addc_u32 s79, s59, s17
	s_mov_b32 m0, s27
	s_nop 0
	global_load_lds_dwordx4 v134, s[58:59]
	s_mov_b32 m0, s28
	s_nop 0
	global_load_lds_dwordx4 v132, s[58:59]
	s_waitcnt vmcnt(8)
	s_waitcnt lgkmcnt(0)
	s_setprio 1
	s_barrier
	v_mfma_f32_16x16x32_bf16 v[62:65], v[144:147], v[176:179], v[62:65]
	v_mfma_f32_16x16x32_bf16 v[54:57], v[152:155], v[176:179], v[54:57]
	v_mfma_f32_16x16x32_bf16 v[46:49], v[144:147], v[184:187], v[46:49]
	v_mfma_f32_16x16x32_bf16 v[38:41], v[152:155], v[184:187], v[38:41]
	v_mfma_f32_16x16x32_bf16 v[30:33], v[144:147], v[192:195], v[30:33]
	v_mfma_f32_16x16x32_bf16 v[22:25], v[152:155], v[192:195], v[22:25]
	v_mfma_f32_16x16x32_bf16 v[14:17], v[144:147], v[206:209], v[14:17]
	v_mfma_f32_16x16x32_bf16 v[6:9], v[152:155], v[206:209], v[6:9]
	v_mfma_f32_16x16x32_bf16 v[62:65], v[148:151], v[180:183], v[62:65]
	v_mfma_f32_16x16x32_bf16 v[54:57], v[156:159], v[180:183], v[54:57]
	v_mfma_f32_16x16x32_bf16 v[46:49], v[148:151], v[188:191], v[46:49]
	v_mfma_f32_16x16x32_bf16 v[38:41], v[156:159], v[188:191], v[38:41]
	v_mfma_f32_16x16x32_bf16 v[30:33], v[148:151], v[202:205], v[30:33]
	v_mfma_f32_16x16x32_bf16 v[22:25], v[156:159], v[202:205], v[22:25]
	v_mfma_f32_16x16x32_bf16 v[14:17], v[148:151], v[210:213], v[14:17]
	v_mfma_f32_16x16x32_bf16 v[6:9], v[156:159], v[210:213], v[6:9]
	v_mfma_f32_16x16x32_bf16 v[58:61], v[160:163], v[176:179], v[58:61]
	v_mfma_f32_16x16x32_bf16 v[50:53], v[168:171], v[176:179], v[50:53]
	v_mfma_f32_16x16x32_bf16 v[42:45], v[160:163], v[184:187], v[42:45]
	v_mfma_f32_16x16x32_bf16 v[34:37], v[168:171], v[184:187], v[34:37]
	v_mfma_f32_16x16x32_bf16 v[26:29], v[160:163], v[192:195], v[26:29]
	v_mfma_f32_16x16x32_bf16 v[18:21], v[168:171], v[192:195], v[18:21]
	v_mfma_f32_16x16x32_bf16 v[10:13], v[160:163], v[206:209], v[10:13]
	v_mfma_f32_16x16x32_bf16 v[2:5], v[168:171], v[206:209], v[2:5]
	v_mfma_f32_16x16x32_bf16 v[58:61], v[164:167], v[180:183], v[58:61]
	v_mfma_f32_16x16x32_bf16 v[50:53], v[172:175], v[180:183], v[50:53]
	v_mfma_f32_16x16x32_bf16 v[42:45], v[164:167], v[188:191], v[42:45]
	v_mfma_f32_16x16x32_bf16 v[34:37], v[172:175], v[188:191], v[34:37]
	v_mfma_f32_16x16x32_bf16 v[26:29], v[164:167], v[202:205], v[26:29]
	v_mfma_f32_16x16x32_bf16 v[18:21], v[172:175], v[202:205], v[18:21]
	v_mfma_f32_16x16x32_bf16 v[10:13], v[164:167], v[210:213], v[10:13]
	v_mfma_f32_16x16x32_bf16 v[2:5], v[172:175], v[210:213], v[2:5]
	s_barrier
	s_setprio 0
.Lkmid_0:
	ds_read_b128 v[144:147], v250 offset:32768
	ds_read_b128 v[148:151], v250 offset:33792
	ds_read_b128 v[152:155], v250 offset:34816
	ds_read_b128 v[156:159], v250 offset:35840
	ds_read_b128 v[160:163], v250 offset:49152
	ds_read_b128 v[164:167], v250 offset:50176
	ds_read_b128 v[168:171], v250 offset:51200
	ds_read_b128 v[172:175], v250 offset:52224
	ds_read_b128 v[176:179], v143 offset:32768
	ds_read_b128 v[180:183], v143 offset:33792
	ds_read_b128 v[184:187], v143 offset:34816
	ds_read_b128 v[188:191], v143 offset:35840
	ds_read_b128 v[192:195], v143 offset:36864
	ds_read_b128 v[202:205], v143 offset:37888
	ds_read_b128 v[206:209], v143 offset:38912
	ds_read_b128 v[210:213], v143 offset:39936
	s_add_i32 s0, 0, 0x18000
	s_add_i32 s1, 0, 0x1c000
	s_add_u32 s58, s58, 0x80000
	s_addc_u32 s59, s59, 0
	s_mov_b32 m0, s29
	s_nop 0
	global_load_lds_dwordx4 v134, s[58:59]
	s_mov_b32 m0, s30
	s_nop 0
	global_load_lds_dwordx4 v132, s[58:59]
	s_waitcnt vmcnt(8)
	s_waitcnt lgkmcnt(0)
	s_setprio 1
	s_barrier
	v_mfma_f32_16x16x32_bf16 v[126:129], v[144:147], v[176:179], v[126:129]
	v_mfma_f32_16x16x32_bf16 v[118:121], v[152:155], v[176:179], v[118:121]
	v_mfma_f32_16x16x32_bf16 v[110:113], v[144:147], v[184:187], v[110:113]
	v_mfma_f32_16x16x32_bf16 v[102:105], v[152:155], v[184:187], v[102:105]
	v_mfma_f32_16x16x32_bf16 v[94:97], v[144:147], v[192:195], v[94:97]
	v_mfma_f32_16x16x32_bf16 v[86:89], v[152:155], v[192:195], v[86:89]
	v_mfma_f32_16x16x32_bf16 v[78:81], v[144:147], v[206:209], v[78:81]
	v_mfma_f32_16x16x32_bf16 v[70:73], v[152:155], v[206:209], v[70:73]
	v_mfma_f32_16x16x32_bf16 v[126:129], v[148:151], v[180:183], v[126:129]
	v_mfma_f32_16x16x32_bf16 v[118:121], v[156:159], v[180:183], v[118:121]
	v_mfma_f32_16x16x32_bf16 v[110:113], v[148:151], v[188:191], v[110:113]
	v_mfma_f32_16x16x32_bf16 v[102:105], v[156:159], v[188:191], v[102:105]
	v_mfma_f32_16x16x32_bf16 v[94:97], v[148:151], v[202:205], v[94:97]
	v_mfma_f32_16x16x32_bf16 v[86:89], v[156:159], v[202:205], v[86:89]
	v_mfma_f32_16x16x32_bf16 v[78:81], v[148:151], v[210:213], v[78:81]
	v_mfma_f32_16x16x32_bf16 v[70:73], v[156:159], v[210:213], v[70:73]
	v_mfma_f32_16x16x32_bf16 v[122:125], v[160:163], v[176:179], v[122:125]
	v_mfma_f32_16x16x32_bf16 v[114:117], v[168:171], v[176:179], v[114:117]
	v_mfma_f32_16x16x32_bf16 v[106:109], v[160:163], v[184:187], v[106:109]
	v_mfma_f32_16x16x32_bf16 v[98:101], v[168:171], v[184:187], v[98:101]
	v_mfma_f32_16x16x32_bf16 v[90:93], v[160:163], v[192:195], v[90:93]
	v_mfma_f32_16x16x32_bf16 v[82:85], v[168:171], v[192:195], v[82:85]
	v_mfma_f32_16x16x32_bf16 v[74:77], v[160:163], v[206:209], v[74:77]
	v_mfma_f32_16x16x32_bf16 v[66:69], v[168:171], v[206:209], v[66:69]
	v_mfma_f32_16x16x32_bf16 v[122:125], v[164:167], v[180:183], v[122:125]
	v_mfma_f32_16x16x32_bf16 v[114:117], v[172:175], v[180:183], v[114:117]
	v_mfma_f32_16x16x32_bf16 v[106:109], v[164:167], v[188:191], v[106:109]
	v_mfma_f32_16x16x32_bf16 v[98:101], v[172:175], v[188:191], v[98:101]
	v_mfma_f32_16x16x32_bf16 v[90:93], v[164:167], v[202:205], v[90:93]
	v_mfma_f32_16x16x32_bf16 v[82:85], v[172:175], v[202:205], v[82:85]
	v_mfma_f32_16x16x32_bf16 v[74:77], v[164:167], v[210:213], v[74:77]
	v_mfma_f32_16x16x32_bf16 v[66:69], v[172:175], v[210:213], v[66:69]
	s_barrier
	s_setprio 0
	ds_read_b128 v[176:179], v143 offset:49152
	ds_read_b128 v[180:183], v143 offset:50176
	ds_read_b128 v[184:187], v143 offset:51200
	ds_read_b128 v[188:191], v143 offset:52224
	ds_read_b128 v[192:195], v143 offset:53248
	ds_read_b128 v[202:205], v143 offset:54272
	ds_read_b128 v[206:209], v143 offset:55296
	ds_read_b128 v[210:213], v143 offset:56320
	s_add_i32 s0, s0, s26
	s_mov_b32 m0, s0
	s_nop 0
	global_load_lds_dwordx4 v196, s[98:99]
	s_add_i32 m0, s0, 0x2000
	s_add_u32 s8, s8, 0x80080
	s_addc_u32 s9, s9, 0
	s_add_i32 s0, s1, s26
	global_load_lds_dwordx4 v130, s[98:99]
	s_mov_b32 m0, s0
	s_nop 0
	global_load_lds_dwordx4 v196, s[8:9]
	s_add_i32 m0, s0, 0x2000
	s_nop 0
	global_load_lds_dwordx4 v130, s[8:9]
	s_mov_b32 m0, s31
	s_nop 0
	global_load_lds_dwordx4 v134, s[78:79]
	s_mov_b32 m0, s34
	s_nop 0
	global_load_lds_dwordx4 v132, s[78:79]
	s_waitcnt vmcnt(8)
	s_waitcnt lgkmcnt(0)
	s_setprio 1
	s_barrier
	v_mfma_f32_16x16x32_bf16 v[62:65], v[144:147], v[176:179], v[62:65]
	v_mfma_f32_16x16x32_bf16 v[54:57], v[152:155], v[176:179], v[54:57]
	v_mfma_f32_16x16x32_bf16 v[46:49], v[144:147], v[184:187], v[46:49]
	v_mfma_f32_16x16x32_bf16 v[38:41], v[152:155], v[184:187], v[38:41]
	v_mfma_f32_16x16x32_bf16 v[30:33], v[144:147], v[192:195], v[30:33]
	v_mfma_f32_16x16x32_bf16 v[22:25], v[152:155], v[192:195], v[22:25]
	v_mfma_f32_16x16x32_bf16 v[14:17], v[144:147], v[206:209], v[14:17]
	v_mfma_f32_16x16x32_bf16 v[6:9], v[152:155], v[206:209], v[6:9]
	v_mfma_f32_16x16x32_bf16 v[62:65], v[148:151], v[180:183], v[62:65]
	v_mfma_f32_16x16x32_bf16 v[54:57], v[156:159], v[180:183], v[54:57]
	v_mfma_f32_16x16x32_bf16 v[46:49], v[148:151], v[188:191], v[46:49]
	v_mfma_f32_16x16x32_bf16 v[38:41], v[156:159], v[188:191], v[38:41]
	v_mfma_f32_16x16x32_bf16 v[30:33], v[148:151], v[202:205], v[30:33]
	v_mfma_f32_16x16x32_bf16 v[22:25], v[156:159], v[202:205], v[22:25]
	v_mfma_f32_16x16x32_bf16 v[14:17], v[148:151], v[210:213], v[14:17]
	v_mfma_f32_16x16x32_bf16 v[6:9], v[156:159], v[210:213], v[6:9]
	v_mfma_f32_16x16x32_bf16 v[58:61], v[160:163], v[176:179], v[58:61]
	v_mfma_f32_16x16x32_bf16 v[50:53], v[168:171], v[176:179], v[50:53]
	v_mfma_f32_16x16x32_bf16 v[42:45], v[160:163], v[184:187], v[42:45]
	v_mfma_f32_16x16x32_bf16 v[34:37], v[168:171], v[184:187], v[34:37]
	v_mfma_f32_16x16x32_bf16 v[26:29], v[160:163], v[192:195], v[26:29]
	v_mfma_f32_16x16x32_bf16 v[18:21], v[168:171], v[192:195], v[18:21]
	v_mfma_f32_16x16x32_bf16 v[10:13], v[160:163], v[206:209], v[10:13]
	v_mfma_f32_16x16x32_bf16 v[2:5], v[168:171], v[206:209], v[2:5]
	v_mfma_f32_16x16x32_bf16 v[58:61], v[164:167], v[180:183], v[58:61]
	v_mfma_f32_16x16x32_bf16 v[50:53], v[172:175], v[180:183], v[50:53]
	v_mfma_f32_16x16x32_bf16 v[42:45], v[164:167], v[188:191], v[42:45]
	v_mfma_f32_16x16x32_bf16 v[34:37], v[172:175], v[188:191], v[34:37]
	v_mfma_f32_16x16x32_bf16 v[26:29], v[164:167], v[202:205], v[26:29]
	v_mfma_f32_16x16x32_bf16 v[18:21], v[172:175], v[202:205], v[18:21]
	v_mfma_f32_16x16x32_bf16 v[10:13], v[164:167], v[210:213], v[10:13]
	v_mfma_f32_16x16x32_bf16 v[2:5], v[172:175], v[210:213], v[2:5]
	s_barrier
	s_setprio 0
	s_add_u32 s67, s67, 0x100
	s_addc_u32 s68, s68, 0
	s_add_u32 s52, s52, 0x100
	s_addc_u32 s53, s53, 0
	s_cmp_ge_i32 s69, s62
	s_mov_b32 s8, s69
	s_cbranch_scc0 .LBB0_904
	s_and_b64 vcc, exec, s[38:39]
	s_cbranch_vccz .LBB0_907
	s_barrier

.Ldefbar_skip_1:
	v_add_u32_e32 v250, 0x10000, v188
	ds_read_b128 v[130:133], v250
	ds_read_b128 v[134:137], v250 offset:1024
	ds_read_b128 v[138:141], v250 offset:2048
	ds_read_b128 v[142:145], v250 offset:3072
	ds_read_b128 v[146:149], v250 offset:16384
	ds_read_b128 v[164:167], v250 offset:17408
	ds_read_b128 v[168:171], v250 offset:18432
	ds_read_b128 v[172:175], v250 offset:19456
	ds_read_b128 v[176:179], v189
	ds_read_b128 v[180:183], v189 offset:1024
	ds_read_b128 v[184:187], v189 offset:2048
	ds_read_b128 v[190:193], v189 offset:3072
	ds_read_b128 v[202:205], v189 offset:4096
	ds_read_b128 v[206:209], v189 offset:5120
	ds_read_b128 v[210:213], v189 offset:6144
	ds_read_b128 v[214:217], v189 offset:7168
	s_add_i32 s72, s50, 2
	s_add_u32 s8, s48, 0x100
	s_addc_u32 s9, s49, 0
	s_add_i32 s0, 0, 0x10000
	s_cmp_eq_u32 s41, s50
	s_cselect_b32 s53, s45, s9
	s_cselect_b32 s52, s44, s8
	s_cselect_b32 s51, s47, s71
	s_cselect_b32 s50, s46, s70
	s_add_i32 s1, 0, 0x14000
	v_lshl_add_u64 v[194:195], s[48:49], 0, v[162:163]
	s_add_i32 m0, s27, 0xc000
	s_nop 0
	global_load_lds_dwordx4 v[194:195], off
	v_lshl_add_u64 v[194:195], s[48:49], 0, v[160:161]
	s_add_i32 m0, s27, 0xe000
	s_nop 0
	global_load_lds_dwordx4 v[194:195], off
	s_waitcnt vmcnt(8)
	s_waitcnt lgkmcnt(0)
	s_setprio 1
	s_barrier
	v_mfma_f32_16x16x32_bf16 v[126:129], v[130:133], v[176:179], 0
	v_mfma_f32_16x16x32_bf16 v[122:125], v[138:141], v[176:179], 0
	v_mfma_f32_16x16x32_bf16 v[110:113], v[130:133], v[184:187], 0
	v_mfma_f32_16x16x32_bf16 v[106:109], v[138:141], v[184:187], 0
	v_mfma_f32_16x16x32_bf16 v[98:101], v[130:133], v[202:205], 0
	v_mfma_f32_16x16x32_bf16 v[90:93], v[138:141], v[202:205], 0
	v_mfma_f32_16x16x32_bf16 v[82:85], v[130:133], v[210:213], 0
	v_mfma_f32_16x16x32_bf16 v[74:77], v[138:141], v[210:213], 0
	v_mfma_f32_16x16x32_bf16 v[126:129], v[134:137], v[180:183], v[126:129]
	v_mfma_f32_16x16x32_bf16 v[122:125], v[142:145], v[180:183], v[122:125]
	v_mfma_f32_16x16x32_bf16 v[110:113], v[134:137], v[190:193], v[110:113]
	v_mfma_f32_16x16x32_bf16 v[106:109], v[142:145], v[190:193], v[106:109]
	v_mfma_f32_16x16x32_bf16 v[98:101], v[134:137], v[206:209], v[98:101]
	v_mfma_f32_16x16x32_bf16 v[90:93], v[142:145], v[206:209], v[90:93]
	v_mfma_f32_16x16x32_bf16 v[82:85], v[134:137], v[214:217], v[82:85]
	v_mfma_f32_16x16x32_bf16 v[74:77], v[142:145], v[214:217], v[74:77]
	v_mfma_f32_16x16x32_bf16 v[118:121], v[146:149], v[176:179], 0
	v_mfma_f32_16x16x32_bf16 v[114:117], v[168:171], v[176:179], 0
	v_mfma_f32_16x16x32_bf16 v[102:105], v[146:149], v[184:187], 0
	v_mfma_f32_16x16x32_bf16 v[94:97], v[168:171], v[184:187], 0
	v_mfma_f32_16x16x32_bf16 v[86:89], v[146:149], v[202:205], 0
	v_mfma_f32_16x16x32_bf16 v[78:81], v[168:171], v[202:205], 0
	v_mfma_f32_16x16x32_bf16 v[70:73], v[146:149], v[210:213], 0
	v_mfma_f32_16x16x32_bf16 v[66:69], v[168:171], v[210:213], 0
	v_mfma_f32_16x16x32_bf16 v[118:121], v[164:167], v[180:183], v[118:121]
	v_mfma_f32_16x16x32_bf16 v[114:117], v[172:175], v[180:183], v[114:117]
	v_mfma_f32_16x16x32_bf16 v[102:105], v[164:167], v[190:193], v[102:105]
	v_mfma_f32_16x16x32_bf16 v[94:97], v[172:175], v[190:193], v[94:97]
	v_mfma_f32_16x16x32_bf16 v[86:89], v[164:167], v[206:209], v[86:89]
	v_mfma_f32_16x16x32_bf16 v[78:81], v[172:175], v[206:209], v[78:81]
	v_mfma_f32_16x16x32_bf16 v[70:73], v[164:167], v[214:217], v[70:73]
	v_mfma_f32_16x16x32_bf16 v[66:69], v[172:175], v[214:217], v[66:69]
	s_barrier
	s_setprio 0
	ds_read_b128 v[176:179], v189 offset:16384
	ds_read_b128 v[180:183], v189 offset:17408
	ds_read_b128 v[184:187], v189 offset:18432
	ds_read_b128 v[190:193], v189 offset:19456
	ds_read_b128 v[202:205], v189 offset:20480
	ds_read_b128 v[206:209], v189 offset:21504
	ds_read_b128 v[210:213], v189 offset:22528
	ds_read_b128 v[214:217], v189 offset:23552
	s_add_i32 s0, s0, s26
	s_add_u32 s98, s50, s16
	s_addc_u32 s99, s51, s17
	s_mov_b32 m0, s0
	s_nop 0
	global_load_lds_dwordx4 v196, s[50:51]
	s_add_i32 m0, s0, 0x2000
	s_add_u32 s48, s50, 0x158000
	s_addc_u32 s49, s51, 0
	s_add_i32 s0, s1, s26
	global_load_lds_dwordx4 v154, s[50:51]
	s_mov_b32 m0, s0
	s_nop 0
	global_load_lds_dwordx4 v196, s[48:49]
	s_add_i32 m0, s0, 0x2000
	s_nop 0
	global_load_lds_dwordx4 v154, s[48:49]
	s_add_u32 s78, s52, s16
	s_addc_u32 s79, s53, s17
	s_mov_b32 m0, s27
	s_nop 0
	global_load_lds_dwordx4 v150, s[52:53]
	s_mov_b32 m0, s28
	s_nop 0
	global_load_lds_dwordx4 v152, s[52:53]
	s_waitcnt vmcnt(8)
	s_waitcnt lgkmcnt(0)
	s_setprio 1
	s_barrier
	v_mfma_f32_16x16x32_bf16 v[62:65], v[130:133], v[176:179], 0
	v_mfma_f32_16x16x32_bf16 v[58:61], v[138:141], v[176:179], 0
	v_mfma_f32_16x16x32_bf16 v[50:53], v[130:133], v[184:187], 0
	v_mfma_f32_16x16x32_bf16 v[42:45], v[138:141], v[184:187], 0
	v_mfma_f32_16x16x32_bf16 v[34:37], v[130:133], v[202:205], 0
	v_mfma_f32_16x16x32_bf16 v[26:29], v[138:141], v[202:205], 0
	v_mfma_f32_16x16x32_bf16 v[18:21], v[130:133], v[210:213], 0
	v_mfma_f32_16x16x32_bf16 v[10:13], v[138:141], v[210:213], 0
	v_mfma_f32_16x16x32_bf16 v[62:65], v[134:137], v[180:183], v[62:65]
	v_mfma_f32_16x16x32_bf16 v[58:61], v[142:145], v[180:183], v[58:61]
	v_mfma_f32_16x16x32_bf16 v[50:53], v[134:137], v[190:193], v[50:53]
	v_mfma_f32_16x16x32_bf16 v[42:45], v[142:145], v[190:193], v[42:45]
	v_mfma_f32_16x16x32_bf16 v[34:37], v[134:137], v[206:209], v[34:37]
	v_mfma_f32_16x16x32_bf16 v[26:29], v[142:145], v[206:209], v[26:29]
	v_mfma_f32_16x16x32_bf16 v[18:21], v[134:137], v[214:217], v[18:21]
	v_mfma_f32_16x16x32_bf16 v[10:13], v[142:145], v[214:217], v[10:13]
	v_mfma_f32_16x16x32_bf16 v[54:57], v[146:149], v[176:179], 0
	v_mfma_f32_16x16x32_bf16 v[46:49], v[168:171], v[176:179], 0
	v_mfma_f32_16x16x32_bf16 v[38:41], v[146:149], v[184:187], 0
	v_mfma_f32_16x16x32_bf16 v[30:33], v[168:171], v[184:187], 0
	v_mfma_f32_16x16x32_bf16 v[22:25], v[146:149], v[202:205], 0
	v_mfma_f32_16x16x32_bf16 v[14:17], v[168:171], v[202:205], 0
	v_mfma_f32_16x16x32_bf16 v[6:9], v[146:149], v[210:213], 0
	v_mfma_f32_16x16x32_bf16 v[2:5], v[168:171], v[210:213], 0
	v_mfma_f32_16x16x32_bf16 v[54:57], v[164:167], v[180:183], v[54:57]
	v_mfma_f32_16x16x32_bf16 v[46:49], v[172:175], v[180:183], v[46:49]
	v_mfma_f32_16x16x32_bf16 v[38:41], v[164:167], v[190:193], v[38:41]
	v_mfma_f32_16x16x32_bf16 v[30:33], v[172:175], v[190:193], v[30:33]
	v_mfma_f32_16x16x32_bf16 v[22:25], v[164:167], v[206:209], v[22:25]
	v_mfma_f32_16x16x32_bf16 v[14:17], v[172:175], v[206:209], v[14:17]
	v_mfma_f32_16x16x32_bf16 v[6:9], v[164:167], v[214:217], v[6:9]
	v_mfma_f32_16x16x32_bf16 v[2:5], v[172:175], v[214:217], v[2:5]
	s_barrier
	s_setprio 0
	s_branch .Lkmid_1
.LBB0_987:
	ds_read_b128 v[130:133], v250
	ds_read_b128 v[134:137], v250 offset:1024
	ds_read_b128 v[138:141], v250 offset:2048
	ds_read_b128 v[142:145], v250 offset:3072
	ds_read_b128 v[146:149], v250 offset:16384
	ds_read_b128 v[164:167], v250 offset:17408
	ds_read_b128 v[168:171], v250 offset:18432
	ds_read_b128 v[172:175], v250 offset:19456
	ds_read_b128 v[176:179], v189
	ds_read_b128 v[180:183], v189 offset:1024
	ds_read_b128 v[184:187], v189 offset:2048
	ds_read_b128 v[190:193], v189 offset:3072
	ds_read_b128 v[202:205], v189 offset:4096
	ds_read_b128 v[206:209], v189 offset:5120
	ds_read_b128 v[210:213], v189 offset:6144
	ds_read_b128 v[214:217], v189 offset:7168
	s_add_i32 s72, s50, 2
	s_add_u32 s8, s48, 0x100
	s_addc_u32 s9, s49, 0
	s_add_i32 s0, 0, 0x10000
	s_cmp_eq_u32 s41, s50
	s_cselect_b32 s53, s45, s9
	s_cselect_b32 s52, s44, s8
	s_cselect_b32 s51, s47, s71
	s_cselect_b32 s50, s46, s70
	s_add_i32 s1, 0, 0x14000
	v_lshl_add_u64 v[194:195], s[48:49], 0, v[162:163]
	s_add_i32 m0, s27, 0xc000
	s_nop 0
	global_load_lds_dwordx4 v[194:195], off
	v_lshl_add_u64 v[194:195], s[48:49], 0, v[160:161]
	s_add_i32 m0, s27, 0xe000
	s_nop 0
	global_load_lds_dwordx4 v[194:195], off
	s_waitcnt vmcnt(8)
	s_waitcnt lgkmcnt(0)
	s_setprio 1
	s_barrier
	v_mfma_f32_16x16x32_bf16 v[126:129], v[130:133], v[176:179], v[126:129]
	v_mfma_f32_16x16x32_bf16 v[122:125], v[138:141], v[176:179], v[122:125]
	v_mfma_f32_16x16x32_bf16 v[110:113], v[130:133], v[184:187], v[110:113]
	v_mfma_f32_16x16x32_bf16 v[106:109], v[138:141], v[184:187], v[106:109]
	v_mfma_f32_16x16x32_bf16 v[98:101], v[130:133], v[202:205], v[98:101]
	v_mfma_f32_16x16x32_bf16 v[90:93], v[138:141], v[202:205], v[90:93]
	v_mfma_f32_16x16x32_bf16 v[82:85], v[130:133], v[210:213], v[82:85]
	v_mfma_f32_16x16x32_bf16 v[74:77], v[138:141], v[210:213], v[74:77]
	v_mfma_f32_16x16x32_bf16 v[126:129], v[134:137], v[180:183], v[126:129]
	v_mfma_f32_16x16x32_bf16 v[122:125], v[142:145], v[180:183], v[122:125]
	v_mfma_f32_16x16x32_bf16 v[110:113], v[134:137], v[190:193], v[110:113]
	v_mfma_f32_16x16x32_bf16 v[106:109], v[142:145], v[190:193], v[106:109]
	v_mfma_f32_16x16x32_bf16 v[98:101], v[134:137], v[206:209], v[98:101]
	v_mfma_f32_16x16x32_bf16 v[90:93], v[142:145], v[206:209], v[90:93]
	v_mfma_f32_16x16x32_bf16 v[82:85], v[134:137], v[214:217], v[82:85]
	v_mfma_f32_16x16x32_bf16 v[74:77], v[142:145], v[214:217], v[74:77]
	v_mfma_f32_16x16x32_bf16 v[118:121], v[146:149], v[176:179], v[118:121]
	v_mfma_f32_16x16x32_bf16 v[114:117], v[168:171], v[176:179], v[114:117]
	v_mfma_f32_16x16x32_bf16 v[102:105], v[146:149], v[184:187], v[102:105]
	v_mfma_f32_16x16x32_bf16 v[94:97], v[168:171], v[184:187], v[94:97]
	v_mfma_f32_16x16x32_bf16 v[86:89], v[146:149], v[202:205], v[86:89]
	v_mfma_f32_16x16x32_bf16 v[78:81], v[168:171], v[202:205], v[78:81]
	v_mfma_f32_16x16x32_bf16 v[70:73], v[146:149], v[210:213], v[70:73]
	v_mfma_f32_16x16x32_bf16 v[66:69], v[168:171], v[210:213], v[66:69]
	v_mfma_f32_16x16x32_bf16 v[118:121], v[164:167], v[180:183], v[118:121]
	v_mfma_f32_16x16x32_bf16 v[114:117], v[172:175], v[180:183], v[114:117]
	v_mfma_f32_16x16x32_bf16 v[102:105], v[164:167], v[190:193], v[102:105]
	v_mfma_f32_16x16x32_bf16 v[94:97], v[172:175], v[190:193], v[94:97]
	v_mfma_f32_16x16x32_bf16 v[86:89], v[164:167], v[206:209], v[86:89]
	v_mfma_f32_16x16x32_bf16 v[78:81], v[172:175], v[206:209], v[78:81]
	v_mfma_f32_16x16x32_bf16 v[70:73], v[164:167], v[214:217], v[70:73]
	v_mfma_f32_16x16x32_bf16 v[66:69], v[172:175], v[214:217], v[66:69]
	s_barrier
	s_setprio 0
	ds_read_b128 v[176:179], v189 offset:16384
	ds_read_b128 v[180:183], v189 offset:17408
	ds_read_b128 v[184:187], v189 offset:18432
	ds_read_b128 v[190:193], v189 offset:19456
	ds_read_b128 v[202:205], v189 offset:20480
	ds_read_b128 v[206:209], v189 offset:21504
	ds_read_b128 v[210:213], v189 offset:22528
	ds_read_b128 v[214:217], v189 offset:23552
	s_add_i32 s0, s0, s26
	s_add_u32 s98, s50, s16
	s_addc_u32 s99, s51, s17
	s_mov_b32 m0, s0
	s_nop 0
	global_load_lds_dwordx4 v196, s[50:51]
	s_add_i32 m0, s0, 0x2000
	s_add_u32 s48, s50, 0x158000
	s_addc_u32 s49, s51, 0
	s_add_i32 s0, s1, s26
	global_load_lds_dwordx4 v154, s[50:51]
	s_mov_b32 m0, s0
	s_nop 0
	global_load_lds_dwordx4 v196, s[48:49]
	s_add_i32 m0, s0, 0x2000
	s_nop 0
	global_load_lds_dwordx4 v154, s[48:49]
	s_add_u32 s78, s52, s16
	s_addc_u32 s79, s53, s17
	s_mov_b32 m0, s27
	s_nop 0
	global_load_lds_dwordx4 v150, s[52:53]
	s_mov_b32 m0, s28
	s_nop 0
	global_load_lds_dwordx4 v152, s[52:53]
	s_waitcnt vmcnt(8)
	s_waitcnt lgkmcnt(0)
	s_setprio 1
	s_barrier
	v_mfma_f32_16x16x32_bf16 v[62:65], v[130:133], v[176:179], v[62:65]
	v_mfma_f32_16x16x32_bf16 v[58:61], v[138:141], v[176:179], v[58:61]
	v_mfma_f32_16x16x32_bf16 v[50:53], v[130:133], v[184:187], v[50:53]
	v_mfma_f32_16x16x32_bf16 v[42:45], v[138:141], v[184:187], v[42:45]
	v_mfma_f32_16x16x32_bf16 v[34:37], v[130:133], v[202:205], v[34:37]
	v_mfma_f32_16x16x32_bf16 v[26:29], v[138:141], v[202:205], v[26:29]
	v_mfma_f32_16x16x32_bf16 v[18:21], v[130:133], v[210:213], v[18:21]
	v_mfma_f32_16x16x32_bf16 v[10:13], v[138:141], v[210:213], v[10:13]
	v_mfma_f32_16x16x32_bf16 v[62:65], v[134:137], v[180:183], v[62:65]
	v_mfma_f32_16x16x32_bf16 v[58:61], v[142:145], v[180:183], v[58:61]
	v_mfma_f32_16x16x32_bf16 v[50:53], v[134:137], v[190:193], v[50:53]
	v_mfma_f32_16x16x32_bf16 v[42:45], v[142:145], v[190:193], v[42:45]
	v_mfma_f32_16x16x32_bf16 v[34:37], v[134:137], v[206:209], v[34:37]
	v_mfma_f32_16x16x32_bf16 v[26:29], v[142:145], v[206:209], v[26:29]
	v_mfma_f32_16x16x32_bf16 v[18:21], v[134:137], v[214:217], v[18:21]
	v_mfma_f32_16x16x32_bf16 v[10:13], v[142:145], v[214:217], v[10:13]
	v_mfma_f32_16x16x32_bf16 v[54:57], v[146:149], v[176:179], v[54:57]
	v_mfma_f32_16x16x32_bf16 v[46:49], v[168:171], v[176:179], v[46:49]
	v_mfma_f32_16x16x32_bf16 v[38:41], v[146:149], v[184:187], v[38:41]
	v_mfma_f32_16x16x32_bf16 v[30:33], v[168:171], v[184:187], v[30:33]
	v_mfma_f32_16x16x32_bf16 v[22:25], v[146:149], v[202:205], v[22:25]
	v_mfma_f32_16x16x32_bf16 v[14:17], v[168:171], v[202:205], v[14:17]
	v_mfma_f32_16x16x32_bf16 v[6:9], v[146:149], v[210:213], v[6:9]
	v_mfma_f32_16x16x32_bf16 v[2:5], v[168:171], v[210:213], v[2:5]
	v_mfma_f32_16x16x32_bf16 v[54:57], v[164:167], v[180:183], v[54:57]
	v_mfma_f32_16x16x32_bf16 v[46:49], v[172:175], v[180:183], v[46:49]
	v_mfma_f32_16x16x32_bf16 v[38:41], v[164:167], v[190:193], v[38:41]
	v_mfma_f32_16x16x32_bf16 v[30:33], v[172:175], v[190:193], v[30:33]
	v_mfma_f32_16x16x32_bf16 v[22:25], v[164:167], v[206:209], v[22:25]
	v_mfma_f32_16x16x32_bf16 v[14:17], v[172:175], v[206:209], v[14:17]
	v_mfma_f32_16x16x32_bf16 v[6:9], v[164:167], v[214:217], v[6:9]
	v_mfma_f32_16x16x32_bf16 v[2:5], v[172:175], v[214:217], v[2:5]
	s_barrier
	s_setprio 0
.Lkmid_1:
	ds_read_b128 v[130:133], v250 offset:32768
	ds_read_b128 v[134:137], v250 offset:33792
	ds_read_b128 v[138:141], v250 offset:34816
	ds_read_b128 v[142:145], v250 offset:35840
	ds_read_b128 v[146:149], v250 offset:49152
	ds_read_b128 v[164:167], v250 offset:50176
	ds_read_b128 v[168:171], v250 offset:51200
	ds_read_b128 v[172:175], v250 offset:52224
	ds_read_b128 v[176:179], v189 offset:32768
	ds_read_b128 v[180:183], v189 offset:33792
	ds_read_b128 v[184:187], v189 offset:34816
	ds_read_b128 v[190:193], v189 offset:35840
	ds_read_b128 v[202:205], v189 offset:36864
	ds_read_b128 v[206:209], v189 offset:37888
	ds_read_b128 v[210:213], v189 offset:38912
	ds_read_b128 v[214:217], v189 offset:39936
	s_add_i32 s0, 0, 0x18000
	s_add_i32 s1, 0, 0x1c000
	s_add_u32 s48, s52, 0x158000
	s_addc_u32 s49, s53, 0
	s_mov_b32 m0, s29
	s_nop 0
	global_load_lds_dwordx4 v150, s[48:49]
	s_mov_b32 m0, s30
	s_nop 0
	global_load_lds_dwordx4 v152, s[48:49]
	s_waitcnt vmcnt(8)
	s_waitcnt lgkmcnt(0)
	s_setprio 1
	s_barrier
	v_mfma_f32_16x16x32_bf16 v[126:129], v[130:133], v[176:179], v[126:129]
	v_mfma_f32_16x16x32_bf16 v[122:125], v[138:141], v[176:179], v[122:125]
	v_mfma_f32_16x16x32_bf16 v[110:113], v[130:133], v[184:187], v[110:113]
	v_mfma_f32_16x16x32_bf16 v[106:109], v[138:141], v[184:187], v[106:109]
	v_mfma_f32_16x16x32_bf16 v[98:101], v[130:133], v[202:205], v[98:101]
	v_mfma_f32_16x16x32_bf16 v[90:93], v[138:141], v[202:205], v[90:93]
	v_mfma_f32_16x16x32_bf16 v[82:85], v[130:133], v[210:213], v[82:85]
	v_mfma_f32_16x16x32_bf16 v[74:77], v[138:141], v[210:213], v[74:77]
	v_mfma_f32_16x16x32_bf16 v[126:129], v[134:137], v[180:183], v[126:129]
	v_mfma_f32_16x16x32_bf16 v[122:125], v[142:145], v[180:183], v[122:125]
	v_mfma_f32_16x16x32_bf16 v[110:113], v[134:137], v[190:193], v[110:113]
	v_mfma_f32_16x16x32_bf16 v[106:109], v[142:145], v[190:193], v[106:109]
	v_mfma_f32_16x16x32_bf16 v[98:101], v[134:137], v[206:209], v[98:101]
	v_mfma_f32_16x16x32_bf16 v[90:93], v[142:145], v[206:209], v[90:93]
	v_mfma_f32_16x16x32_bf16 v[82:85], v[134:137], v[214:217], v[82:85]
	v_mfma_f32_16x16x32_bf16 v[74:77], v[142:145], v[214:217], v[74:77]
	v_mfma_f32_16x16x32_bf16 v[118:121], v[146:149], v[176:179], v[118:121]
	v_mfma_f32_16x16x32_bf16 v[114:117], v[168:171], v[176:179], v[114:117]
	v_mfma_f32_16x16x32_bf16 v[102:105], v[146:149], v[184:187], v[102:105]
	v_mfma_f32_16x16x32_bf16 v[94:97], v[168:171], v[184:187], v[94:97]
	v_mfma_f32_16x16x32_bf16 v[86:89], v[146:149], v[202:205], v[86:89]
	v_mfma_f32_16x16x32_bf16 v[78:81], v[168:171], v[202:205], v[78:81]
	v_mfma_f32_16x16x32_bf16 v[70:73], v[146:149], v[210:213], v[70:73]
	v_mfma_f32_16x16x32_bf16 v[66:69], v[168:171], v[210:213], v[66:69]
	v_mfma_f32_16x16x32_bf16 v[118:121], v[164:167], v[180:183], v[118:121]
	v_mfma_f32_16x16x32_bf16 v[114:117], v[172:175], v[180:183], v[114:117]
	v_mfma_f32_16x16x32_bf16 v[102:105], v[164:167], v[190:193], v[102:105]
	v_mfma_f32_16x16x32_bf16 v[94:97], v[172:175], v[190:193], v[94:97]
	v_mfma_f32_16x16x32_bf16 v[86:89], v[164:167], v[206:209], v[86:89]
	v_mfma_f32_16x16x32_bf16 v[78:81], v[172:175], v[206:209], v[78:81]
	v_mfma_f32_16x16x32_bf16 v[70:73], v[164:167], v[214:217], v[70:73]
	v_mfma_f32_16x16x32_bf16 v[66:69], v[172:175], v[214:217], v[66:69]
	s_barrier
	s_setprio 0
	ds_read_b128 v[176:179], v189 offset:49152
	ds_read_b128 v[180:183], v189 offset:50176
	ds_read_b128 v[184:187], v189 offset:51200
	ds_read_b128 v[190:193], v189 offset:52224
	ds_read_b128 v[202:205], v189 offset:53248
	ds_read_b128 v[206:209], v189 offset:54272
	ds_read_b128 v[210:213], v189 offset:55296
	ds_read_b128 v[214:217], v189 offset:56320
	s_add_i32 s0, s0, s26
	s_mov_b32 m0, s0
	s_nop 0
	global_load_lds_dwordx4 v196, s[98:99]
	s_add_i32 m0, s0, 0x2000
	s_add_u32 s48, s50, 0x158080
	s_addc_u32 s49, s51, 0
	s_add_i32 s0, s1, s26
	global_load_lds_dwordx4 v154, s[98:99]
	s_mov_b32 m0, s0
	s_nop 0
	global_load_lds_dwordx4 v196, s[48:49]
	s_add_i32 m0, s0, 0x2000
	s_nop 0
	global_load_lds_dwordx4 v154, s[48:49]
	s_mov_b32 m0, s35
	s_nop 0
	global_load_lds_dwordx4 v150, s[78:79]
	s_mov_b32 m0, s58
	s_nop 0
	global_load_lds_dwordx4 v152, s[78:79]
	s_waitcnt vmcnt(8)
	s_waitcnt lgkmcnt(0)
	s_setprio 1
	s_barrier
	v_mfma_f32_16x16x32_bf16 v[62:65], v[130:133], v[176:179], v[62:65]
	v_mfma_f32_16x16x32_bf16 v[58:61], v[138:141], v[176:179], v[58:61]
	v_mfma_f32_16x16x32_bf16 v[50:53], v[130:133], v[184:187], v[50:53]
	v_mfma_f32_16x16x32_bf16 v[42:45], v[138:141], v[184:187], v[42:45]
	v_mfma_f32_16x16x32_bf16 v[34:37], v[130:133], v[202:205], v[34:37]
	v_mfma_f32_16x16x32_bf16 v[26:29], v[138:141], v[202:205], v[26:29]
	v_mfma_f32_16x16x32_bf16 v[18:21], v[130:133], v[210:213], v[18:21]
	v_mfma_f32_16x16x32_bf16 v[10:13], v[138:141], v[210:213], v[10:13]
	v_mfma_f32_16x16x32_bf16 v[62:65], v[134:137], v[180:183], v[62:65]
	v_mfma_f32_16x16x32_bf16 v[58:61], v[142:145], v[180:183], v[58:61]
	v_mfma_f32_16x16x32_bf16 v[50:53], v[134:137], v[190:193], v[50:53]
	v_mfma_f32_16x16x32_bf16 v[42:45], v[142:145], v[190:193], v[42:45]
	v_mfma_f32_16x16x32_bf16 v[34:37], v[134:137], v[206:209], v[34:37]
	v_mfma_f32_16x16x32_bf16 v[26:29], v[142:145], v[206:209], v[26:29]
	v_mfma_f32_16x16x32_bf16 v[18:21], v[134:137], v[214:217], v[18:21]
	v_mfma_f32_16x16x32_bf16 v[10:13], v[142:145], v[214:217], v[10:13]
	v_mfma_f32_16x16x32_bf16 v[54:57], v[146:149], v[176:179], v[54:57]
	v_mfma_f32_16x16x32_bf16 v[46:49], v[168:171], v[176:179], v[46:49]
	v_mfma_f32_16x16x32_bf16 v[38:41], v[146:149], v[184:187], v[38:41]
	v_mfma_f32_16x16x32_bf16 v[30:33], v[168:171], v[184:187], v[30:33]
	v_mfma_f32_16x16x32_bf16 v[22:25], v[146:149], v[202:205], v[22:25]
	v_mfma_f32_16x16x32_bf16 v[14:17], v[168:171], v[202:205], v[14:17]
	v_mfma_f32_16x16x32_bf16 v[6:9], v[146:149], v[210:213], v[6:9]
	v_mfma_f32_16x16x32_bf16 v[2:5], v[168:171], v[210:213], v[2:5]
	v_mfma_f32_16x16x32_bf16 v[54:57], v[164:167], v[180:183], v[54:57]
	v_mfma_f32_16x16x32_bf16 v[46:49], v[172:175], v[180:183], v[46:49]
	v_mfma_f32_16x16x32_bf16 v[38:41], v[164:167], v[190:193], v[38:41]
	v_mfma_f32_16x16x32_bf16 v[30:33], v[172:175], v[190:193], v[30:33]
	v_mfma_f32_16x16x32_bf16 v[22:25], v[164:167], v[206:209], v[22:25]
	v_mfma_f32_16x16x32_bf16 v[14:17], v[172:175], v[206:209], v[14:17]
	v_mfma_f32_16x16x32_bf16 v[6:9], v[164:167], v[214:217], v[6:9]
	v_mfma_f32_16x16x32_bf16 v[2:5], v[172:175], v[214:217], v[2:5]
	s_barrier
	s_setprio 0
	s_add_u32 s70, s70, 0x100
	s_addc_u32 s71, s71, 0
	s_cmp_ge_i32 s72, s69
	s_mov_b64 s[48:49], s[8:9]
	s_mov_b32 s50, s72
	s_cbranch_scc0 .LBB0_987
	s_and_b64 vcc, exec, s[38:39]
	s_cbranch_vccz .LBB0_990
	s_barrier

.Ldefbar_skip_2:
	v_add_u32_e32 v250, 0x10000, v149
	ds_read_b128 v[142:145], v250
	ds_read_b128 v[152:155], v250 offset:1024
	ds_read_b128 v[156:159], v250 offset:2048
	ds_read_b128 v[160:163], v250 offset:3072
	ds_read_b128 v[164:167], v250 offset:16384
	ds_read_b128 v[168:171], v250 offset:17408
	ds_read_b128 v[172:175], v250 offset:18432
	ds_read_b128 v[176:179], v250 offset:19456
	ds_read_b128 v[180:183], v151
	ds_read_b128 v[184:187], v151 offset:1024
	ds_read_b128 v[188:191], v151 offset:2048
	ds_read_b128 v[192:195], v151 offset:3072
	ds_read_b128 v[202:205], v151 offset:4096
	ds_read_b128 v[206:209], v151 offset:5120
	ds_read_b128 v[210:213], v151 offset:6144
	ds_read_b128 v[214:217], v151 offset:7168
	s_add_i32 s71, s8, 2
	s_add_u32 s0, s58, 0xfff80080
	s_addc_u32 s1, s59, -1
	s_add_i32 s72, 0, 0x10000
	s_cmp_eq_u32 s68, s8
	s_cselect_b32 s63, s43, s1
	s_cselect_b32 s62, s47, s0
	s_cselect_b32 s9, s45, s70
	s_cselect_b32 s8, s67, s69
	s_add_i32 s0, 0, 0x14000
	s_add_i32 m0, s27, 0xc000
	s_nop 0
	global_load_lds_dwordx4 v140, s[58:59]
	s_add_i32 m0, s27, 0xe000
	s_nop 0
	global_load_lds_dwordx4 v138, s[58:59]
	s_waitcnt vmcnt(8)
	s_waitcnt lgkmcnt(0)
	s_setprio 1
	s_barrier
	v_mfma_f32_16x16x32_bf16 v[126:129], v[142:145], v[180:183], 0
	v_mfma_f32_16x16x32_bf16 v[122:125], v[156:159], v[180:183], 0
	v_mfma_f32_16x16x32_bf16 v[118:121], v[142:145], v[188:191], 0
	v_mfma_f32_16x16x32_bf16 v[110:113], v[156:159], v[188:191], 0
	v_mfma_f32_16x16x32_bf16 v[102:105], v[142:145], v[202:205], 0
	v_mfma_f32_16x16x32_bf16 v[94:97], v[156:159], v[202:205], 0
	v_mfma_f32_16x16x32_bf16 v[86:89], v[142:145], v[210:213], 0
	v_mfma_f32_16x16x32_bf16 v[78:81], v[156:159], v[210:213], 0
	v_mfma_f32_16x16x32_bf16 v[126:129], v[152:155], v[184:187], v[126:129]
	v_mfma_f32_16x16x32_bf16 v[122:125], v[160:163], v[184:187], v[122:125]
	v_mfma_f32_16x16x32_bf16 v[118:121], v[152:155], v[192:195], v[118:121]
	v_mfma_f32_16x16x32_bf16 v[110:113], v[160:163], v[192:195], v[110:113]
	v_mfma_f32_16x16x32_bf16 v[102:105], v[152:155], v[206:209], v[102:105]
	v_mfma_f32_16x16x32_bf16 v[94:97], v[160:163], v[206:209], v[94:97]
	v_mfma_f32_16x16x32_bf16 v[86:89], v[152:155], v[214:217], v[86:89]
	v_mfma_f32_16x16x32_bf16 v[78:81], v[160:163], v[214:217], v[78:81]
	v_mfma_f32_16x16x32_bf16 v[114:117], v[164:167], v[180:183], 0
	v_mfma_f32_16x16x32_bf16 v[106:109], v[172:175], v[180:183], 0
	v_mfma_f32_16x16x32_bf16 v[98:101], v[164:167], v[188:191], 0
	v_mfma_f32_16x16x32_bf16 v[90:93], v[172:175], v[188:191], 0
	v_mfma_f32_16x16x32_bf16 v[82:85], v[164:167], v[202:205], 0
	v_mfma_f32_16x16x32_bf16 v[74:77], v[172:175], v[202:205], 0
	v_mfma_f32_16x16x32_bf16 v[70:73], v[164:167], v[210:213], 0
	v_mfma_f32_16x16x32_bf16 v[66:69], v[172:175], v[210:213], 0
	v_mfma_f32_16x16x32_bf16 v[114:117], v[168:171], v[184:187], v[114:117]
	v_mfma_f32_16x16x32_bf16 v[106:109], v[176:179], v[184:187], v[106:109]
	v_mfma_f32_16x16x32_bf16 v[98:101], v[168:171], v[192:195], v[98:101]
	v_mfma_f32_16x16x32_bf16 v[90:93], v[176:179], v[192:195], v[90:93]
	v_mfma_f32_16x16x32_bf16 v[82:85], v[168:171], v[206:209], v[82:85]
	v_mfma_f32_16x16x32_bf16 v[74:77], v[176:179], v[206:209], v[74:77]
	v_mfma_f32_16x16x32_bf16 v[70:73], v[168:171], v[214:217], v[70:73]
	v_mfma_f32_16x16x32_bf16 v[66:69], v[176:179], v[214:217], v[66:69]
	s_barrier
	s_setprio 0
	ds_read_b128 v[180:183], v151 offset:16384
	ds_read_b128 v[184:187], v151 offset:17408
	ds_read_b128 v[188:191], v151 offset:18432
	ds_read_b128 v[192:195], v151 offset:19456
	ds_read_b128 v[202:205], v151 offset:20480
	ds_read_b128 v[206:209], v151 offset:21504
	ds_read_b128 v[210:213], v151 offset:22528
	ds_read_b128 v[214:217], v151 offset:23552
	s_add_i32 s1, s72, s26
	s_add_u32 s98, s8, s16
	s_addc_u32 s99, s9, s17
	s_mov_b32 m0, s1
	s_nop 0
	global_load_lds_dwordx4 v196, s[8:9]
	s_add_i32 m0, s1, 0x2000
	s_add_u32 s72, s8, 0x80000
	s_addc_u32 s73, s9, 0
	s_add_i32 s0, s0, s26
	global_load_lds_dwordx4 v130, s[8:9]
	s_mov_b32 m0, s0
	s_nop 0
	global_load_lds_dwordx4 v196, s[72:73]
	s_add_i32 m0, s0, 0x2000
	s_nop 0
	global_load_lds_dwordx4 v130, s[72:73]
	s_add_u32 s78, s62, s16
	s_addc_u32 s79, s63, s17
	s_mov_b32 m0, s27
	s_nop 0
	global_load_lds_dwordx4 v134, s[62:63]
	s_mov_b32 m0, s28
	s_nop 0
	global_load_lds_dwordx4 v132, s[62:63]
	s_waitcnt vmcnt(8)
	s_waitcnt lgkmcnt(0)
	s_setprio 1
	s_barrier
	v_mfma_f32_16x16x32_bf16 v[62:65], v[142:145], v[180:183], 0
	v_mfma_f32_16x16x32_bf16 v[58:61], v[156:159], v[180:183], 0
	v_mfma_f32_16x16x32_bf16 v[54:57], v[142:145], v[188:191], 0
	v_mfma_f32_16x16x32_bf16 v[46:49], v[156:159], v[188:191], 0
	v_mfma_f32_16x16x32_bf16 v[38:41], v[142:145], v[202:205], 0
	v_mfma_f32_16x16x32_bf16 v[30:33], v[156:159], v[202:205], 0
	v_mfma_f32_16x16x32_bf16 v[22:25], v[142:145], v[210:213], 0
	v_mfma_f32_16x16x32_bf16 v[14:17], v[156:159], v[210:213], 0
	v_mfma_f32_16x16x32_bf16 v[62:65], v[152:155], v[184:187], v[62:65]
	v_mfma_f32_16x16x32_bf16 v[58:61], v[160:163], v[184:187], v[58:61]
	v_mfma_f32_16x16x32_bf16 v[54:57], v[152:155], v[192:195], v[54:57]
	v_mfma_f32_16x16x32_bf16 v[46:49], v[160:163], v[192:195], v[46:49]
	v_mfma_f32_16x16x32_bf16 v[38:41], v[152:155], v[206:209], v[38:41]
	v_mfma_f32_16x16x32_bf16 v[30:33], v[160:163], v[206:209], v[30:33]
	v_mfma_f32_16x16x32_bf16 v[22:25], v[152:155], v[214:217], v[22:25]
	v_mfma_f32_16x16x32_bf16 v[14:17], v[160:163], v[214:217], v[14:17]
	v_mfma_f32_16x16x32_bf16 v[50:53], v[164:167], v[180:183], 0
	v_mfma_f32_16x16x32_bf16 v[42:45], v[172:175], v[180:183], 0
	v_mfma_f32_16x16x32_bf16 v[34:37], v[164:167], v[188:191], 0
	v_mfma_f32_16x16x32_bf16 v[26:29], v[172:175], v[188:191], 0
	v_mfma_f32_16x16x32_bf16 v[18:21], v[164:167], v[202:205], 0
	v_mfma_f32_16x16x32_bf16 v[10:13], v[172:175], v[202:205], 0
	v_mfma_f32_16x16x32_bf16 v[6:9], v[164:167], v[210:213], 0
	v_mfma_f32_16x16x32_bf16 v[2:5], v[172:175], v[210:213], 0
	v_mfma_f32_16x16x32_bf16 v[50:53], v[168:171], v[184:187], v[50:53]
	v_mfma_f32_16x16x32_bf16 v[42:45], v[176:179], v[184:187], v[42:45]
	v_mfma_f32_16x16x32_bf16 v[34:37], v[168:171], v[192:195], v[34:37]
	v_mfma_f32_16x16x32_bf16 v[26:29], v[176:179], v[192:195], v[26:29]
	v_mfma_f32_16x16x32_bf16 v[18:21], v[168:171], v[206:209], v[18:21]
	v_mfma_f32_16x16x32_bf16 v[10:13], v[176:179], v[206:209], v[10:13]
	v_mfma_f32_16x16x32_bf16 v[6:9], v[168:171], v[214:217], v[6:9]
	v_mfma_f32_16x16x32_bf16 v[2:5], v[176:179], v[214:217], v[2:5]
	s_barrier
	s_setprio 0
	s_branch .Lkmid_2
.LBB0_1135:
	ds_read_b128 v[142:145], v250
	ds_read_b128 v[152:155], v250 offset:1024
	ds_read_b128 v[156:159], v250 offset:2048
	ds_read_b128 v[160:163], v250 offset:3072
	ds_read_b128 v[164:167], v250 offset:16384
	ds_read_b128 v[168:171], v250 offset:17408
	ds_read_b128 v[172:175], v250 offset:18432
	ds_read_b128 v[176:179], v250 offset:19456
	ds_read_b128 v[180:183], v151
	ds_read_b128 v[184:187], v151 offset:1024
	ds_read_b128 v[188:191], v151 offset:2048
	ds_read_b128 v[192:195], v151 offset:3072
	ds_read_b128 v[202:205], v151 offset:4096
	ds_read_b128 v[206:209], v151 offset:5120
	ds_read_b128 v[210:213], v151 offset:6144
	ds_read_b128 v[214:217], v151 offset:7168
	s_add_i32 s71, s8, 2
	s_add_u32 s0, s58, 0xfff80080
	s_addc_u32 s1, s59, -1
	s_add_i32 s72, 0, 0x10000
	s_cmp_eq_u32 s68, s8
	s_cselect_b32 s63, s43, s1
	s_cselect_b32 s62, s47, s0
	s_cselect_b32 s9, s45, s70
	s_cselect_b32 s8, s67, s69
	s_add_i32 s0, 0, 0x14000
	s_add_i32 m0, s27, 0xc000
	s_nop 0
	global_load_lds_dwordx4 v140, s[58:59]
	s_add_i32 m0, s27, 0xe000
	s_nop 0
	global_load_lds_dwordx4 v138, s[58:59]
	s_waitcnt vmcnt(8)
	s_waitcnt lgkmcnt(0)
	s_setprio 1
	s_barrier
	v_mfma_f32_16x16x32_bf16 v[126:129], v[142:145], v[180:183], v[126:129]
	v_mfma_f32_16x16x32_bf16 v[122:125], v[156:159], v[180:183], v[122:125]
	v_mfma_f32_16x16x32_bf16 v[118:121], v[142:145], v[188:191], v[118:121]
	v_mfma_f32_16x16x32_bf16 v[110:113], v[156:159], v[188:191], v[110:113]
	v_mfma_f32_16x16x32_bf16 v[102:105], v[142:145], v[202:205], v[102:105]
	v_mfma_f32_16x16x32_bf16 v[94:97], v[156:159], v[202:205], v[94:97]
	v_mfma_f32_16x16x32_bf16 v[86:89], v[142:145], v[210:213], v[86:89]
	v_mfma_f32_16x16x32_bf16 v[78:81], v[156:159], v[210:213], v[78:81]
	v_mfma_f32_16x16x32_bf16 v[126:129], v[152:155], v[184:187], v[126:129]
	v_mfma_f32_16x16x32_bf16 v[122:125], v[160:163], v[184:187], v[122:125]
	v_mfma_f32_16x16x32_bf16 v[118:121], v[152:155], v[192:195], v[118:121]
	v_mfma_f32_16x16x32_bf16 v[110:113], v[160:163], v[192:195], v[110:113]
	v_mfma_f32_16x16x32_bf16 v[102:105], v[152:155], v[206:209], v[102:105]
	v_mfma_f32_16x16x32_bf16 v[94:97], v[160:163], v[206:209], v[94:97]
	v_mfma_f32_16x16x32_bf16 v[86:89], v[152:155], v[214:217], v[86:89]
	v_mfma_f32_16x16x32_bf16 v[78:81], v[160:163], v[214:217], v[78:81]
	v_mfma_f32_16x16x32_bf16 v[114:117], v[164:167], v[180:183], v[114:117]
	v_mfma_f32_16x16x32_bf16 v[106:109], v[172:175], v[180:183], v[106:109]
	v_mfma_f32_16x16x32_bf16 v[98:101], v[164:167], v[188:191], v[98:101]
	v_mfma_f32_16x16x32_bf16 v[90:93], v[172:175], v[188:191], v[90:93]
	v_mfma_f32_16x16x32_bf16 v[82:85], v[164:167], v[202:205], v[82:85]
	v_mfma_f32_16x16x32_bf16 v[74:77], v[172:175], v[202:205], v[74:77]
	v_mfma_f32_16x16x32_bf16 v[70:73], v[164:167], v[210:213], v[70:73]
	v_mfma_f32_16x16x32_bf16 v[66:69], v[172:175], v[210:213], v[66:69]
	v_mfma_f32_16x16x32_bf16 v[114:117], v[168:171], v[184:187], v[114:117]
	v_mfma_f32_16x16x32_bf16 v[106:109], v[176:179], v[184:187], v[106:109]
	v_mfma_f32_16x16x32_bf16 v[98:101], v[168:171], v[192:195], v[98:101]
	v_mfma_f32_16x16x32_bf16 v[90:93], v[176:179], v[192:195], v[90:93]
	v_mfma_f32_16x16x32_bf16 v[82:85], v[168:171], v[206:209], v[82:85]
	v_mfma_f32_16x16x32_bf16 v[74:77], v[176:179], v[206:209], v[74:77]
	v_mfma_f32_16x16x32_bf16 v[70:73], v[168:171], v[214:217], v[70:73]
	v_mfma_f32_16x16x32_bf16 v[66:69], v[176:179], v[214:217], v[66:69]
	s_barrier
	s_setprio 0
	ds_read_b128 v[180:183], v151 offset:16384
	ds_read_b128 v[184:187], v151 offset:17408
	ds_read_b128 v[188:191], v151 offset:18432
	ds_read_b128 v[192:195], v151 offset:19456
	ds_read_b128 v[202:205], v151 offset:20480
	ds_read_b128 v[206:209], v151 offset:21504
	ds_read_b128 v[210:213], v151 offset:22528
	ds_read_b128 v[214:217], v151 offset:23552
	s_add_i32 s1, s72, s26
	s_add_u32 s98, s8, s16
	s_addc_u32 s99, s9, s17
	s_mov_b32 m0, s1
	s_nop 0
	global_load_lds_dwordx4 v196, s[8:9]
	s_add_i32 m0, s1, 0x2000
	s_add_u32 s72, s8, 0x80000
	s_addc_u32 s73, s9, 0
	s_add_i32 s0, s0, s26
	global_load_lds_dwordx4 v130, s[8:9]
	s_mov_b32 m0, s0
	s_nop 0
	global_load_lds_dwordx4 v196, s[72:73]
	s_add_i32 m0, s0, 0x2000
	s_nop 0
	global_load_lds_dwordx4 v130, s[72:73]
	s_add_u32 s78, s62, s16
	s_addc_u32 s79, s63, s17
	s_mov_b32 m0, s27
	s_nop 0
	global_load_lds_dwordx4 v134, s[62:63]
	s_mov_b32 m0, s28
	s_nop 0
	global_load_lds_dwordx4 v132, s[62:63]
	s_waitcnt vmcnt(8)
	s_waitcnt lgkmcnt(0)
	s_setprio 1
	s_barrier
	v_mfma_f32_16x16x32_bf16 v[62:65], v[142:145], v[180:183], v[62:65]
	v_mfma_f32_16x16x32_bf16 v[58:61], v[156:159], v[180:183], v[58:61]
	v_mfma_f32_16x16x32_bf16 v[54:57], v[142:145], v[188:191], v[54:57]
	v_mfma_f32_16x16x32_bf16 v[46:49], v[156:159], v[188:191], v[46:49]
	v_mfma_f32_16x16x32_bf16 v[38:41], v[142:145], v[202:205], v[38:41]
	v_mfma_f32_16x16x32_bf16 v[30:33], v[156:159], v[202:205], v[30:33]
	v_mfma_f32_16x16x32_bf16 v[22:25], v[142:145], v[210:213], v[22:25]
	v_mfma_f32_16x16x32_bf16 v[14:17], v[156:159], v[210:213], v[14:17]
	v_mfma_f32_16x16x32_bf16 v[62:65], v[152:155], v[184:187], v[62:65]
	v_mfma_f32_16x16x32_bf16 v[58:61], v[160:163], v[184:187], v[58:61]
	v_mfma_f32_16x16x32_bf16 v[54:57], v[152:155], v[192:195], v[54:57]
	v_mfma_f32_16x16x32_bf16 v[46:49], v[160:163], v[192:195], v[46:49]
	v_mfma_f32_16x16x32_bf16 v[38:41], v[152:155], v[206:209], v[38:41]
	v_mfma_f32_16x16x32_bf16 v[30:33], v[160:163], v[206:209], v[30:33]
	v_mfma_f32_16x16x32_bf16 v[22:25], v[152:155], v[214:217], v[22:25]
	v_mfma_f32_16x16x32_bf16 v[14:17], v[160:163], v[214:217], v[14:17]
	v_mfma_f32_16x16x32_bf16 v[50:53], v[164:167], v[180:183], v[50:53]
	v_mfma_f32_16x16x32_bf16 v[42:45], v[172:175], v[180:183], v[42:45]
	v_mfma_f32_16x16x32_bf16 v[34:37], v[164:167], v[188:191], v[34:37]
	v_mfma_f32_16x16x32_bf16 v[26:29], v[172:175], v[188:191], v[26:29]
	v_mfma_f32_16x16x32_bf16 v[18:21], v[164:167], v[202:205], v[18:21]
	v_mfma_f32_16x16x32_bf16 v[10:13], v[172:175], v[202:205], v[10:13]
	v_mfma_f32_16x16x32_bf16 v[6:9], v[164:167], v[210:213], v[6:9]
	v_mfma_f32_16x16x32_bf16 v[2:5], v[172:175], v[210:213], v[2:5]
	v_mfma_f32_16x16x32_bf16 v[50:53], v[168:171], v[184:187], v[50:53]
	v_mfma_f32_16x16x32_bf16 v[42:45], v[176:179], v[184:187], v[42:45]
	v_mfma_f32_16x16x32_bf16 v[34:37], v[168:171], v[192:195], v[34:37]
	v_mfma_f32_16x16x32_bf16 v[26:29], v[176:179], v[192:195], v[26:29]
	v_mfma_f32_16x16x32_bf16 v[18:21], v[168:171], v[206:209], v[18:21]
	v_mfma_f32_16x16x32_bf16 v[10:13], v[176:179], v[206:209], v[10:13]
	v_mfma_f32_16x16x32_bf16 v[6:9], v[168:171], v[214:217], v[6:9]
	v_mfma_f32_16x16x32_bf16 v[2:5], v[176:179], v[214:217], v[2:5]
	s_barrier
	s_setprio 0
.Lkmid_2:
	ds_read_b128 v[142:145], v250 offset:32768
	ds_read_b128 v[152:155], v250 offset:33792
	ds_read_b128 v[156:159], v250 offset:34816
	ds_read_b128 v[160:163], v250 offset:35840
	ds_read_b128 v[164:167], v250 offset:49152
	ds_read_b128 v[168:171], v250 offset:50176
	ds_read_b128 v[172:175], v250 offset:51200
	ds_read_b128 v[176:179], v250 offset:52224
	ds_read_b128 v[180:183], v151 offset:32768
	ds_read_b128 v[184:187], v151 offset:33792
	ds_read_b128 v[188:191], v151 offset:34816
	ds_read_b128 v[192:195], v151 offset:35840
	ds_read_b128 v[202:205], v151 offset:36864
	ds_read_b128 v[206:209], v151 offset:37888
	ds_read_b128 v[210:213], v151 offset:38912
	ds_read_b128 v[214:217], v151 offset:39936
	s_add_i32 s0, 0, 0x18000
	s_add_i32 s1, 0, 0x1c000
	s_add_u32 s62, s62, 0x80000
	s_addc_u32 s63, s63, 0
	s_mov_b32 m0, s29
	s_nop 0
	global_load_lds_dwordx4 v134, s[62:63]
	s_mov_b32 m0, s30
	s_nop 0
	global_load_lds_dwordx4 v132, s[62:63]
	s_waitcnt vmcnt(8)
	s_waitcnt lgkmcnt(0)
	s_setprio 1
	s_barrier
	v_mfma_f32_16x16x32_bf16 v[126:129], v[142:145], v[180:183], v[126:129]
	v_mfma_f32_16x16x32_bf16 v[122:125], v[156:159], v[180:183], v[122:125]
	v_mfma_f32_16x16x32_bf16 v[118:121], v[142:145], v[188:191], v[118:121]
	v_mfma_f32_16x16x32_bf16 v[110:113], v[156:159], v[188:191], v[110:113]
	v_mfma_f32_16x16x32_bf16 v[102:105], v[142:145], v[202:205], v[102:105]
	v_mfma_f32_16x16x32_bf16 v[94:97], v[156:159], v[202:205], v[94:97]
	v_mfma_f32_16x16x32_bf16 v[86:89], v[142:145], v[210:213], v[86:89]
	v_mfma_f32_16x16x32_bf16 v[78:81], v[156:159], v[210:213], v[78:81]
	v_mfma_f32_16x16x32_bf16 v[126:129], v[152:155], v[184:187], v[126:129]
	v_mfma_f32_16x16x32_bf16 v[122:125], v[160:163], v[184:187], v[122:125]
	v_mfma_f32_16x16x32_bf16 v[118:121], v[152:155], v[192:195], v[118:121]
	v_mfma_f32_16x16x32_bf16 v[110:113], v[160:163], v[192:195], v[110:113]
	v_mfma_f32_16x16x32_bf16 v[102:105], v[152:155], v[206:209], v[102:105]
	v_mfma_f32_16x16x32_bf16 v[94:97], v[160:163], v[206:209], v[94:97]
	v_mfma_f32_16x16x32_bf16 v[86:89], v[152:155], v[214:217], v[86:89]
	v_mfma_f32_16x16x32_bf16 v[78:81], v[160:163], v[214:217], v[78:81]
	v_mfma_f32_16x16x32_bf16 v[114:117], v[164:167], v[180:183], v[114:117]
	v_mfma_f32_16x16x32_bf16 v[106:109], v[172:175], v[180:183], v[106:109]
	v_mfma_f32_16x16x32_bf16 v[98:101], v[164:167], v[188:191], v[98:101]
	v_mfma_f32_16x16x32_bf16 v[90:93], v[172:175], v[188:191], v[90:93]
	v_mfma_f32_16x16x32_bf16 v[82:85], v[164:167], v[202:205], v[82:85]
	v_mfma_f32_16x16x32_bf16 v[74:77], v[172:175], v[202:205], v[74:77]
	v_mfma_f32_16x16x32_bf16 v[70:73], v[164:167], v[210:213], v[70:73]
	v_mfma_f32_16x16x32_bf16 v[66:69], v[172:175], v[210:213], v[66:69]
	v_mfma_f32_16x16x32_bf16 v[114:117], v[168:171], v[184:187], v[114:117]
	v_mfma_f32_16x16x32_bf16 v[106:109], v[176:179], v[184:187], v[106:109]
	v_mfma_f32_16x16x32_bf16 v[98:101], v[168:171], v[192:195], v[98:101]
	v_mfma_f32_16x16x32_bf16 v[90:93], v[176:179], v[192:195], v[90:93]
	v_mfma_f32_16x16x32_bf16 v[82:85], v[168:171], v[206:209], v[82:85]
	v_mfma_f32_16x16x32_bf16 v[74:77], v[176:179], v[206:209], v[74:77]
	v_mfma_f32_16x16x32_bf16 v[70:73], v[168:171], v[214:217], v[70:73]
	v_mfma_f32_16x16x32_bf16 v[66:69], v[176:179], v[214:217], v[66:69]
	s_barrier
	s_setprio 0
	ds_read_b128 v[180:183], v151 offset:49152
	ds_read_b128 v[184:187], v151 offset:50176
	ds_read_b128 v[188:191], v151 offset:51200
	ds_read_b128 v[192:195], v151 offset:52224
	ds_read_b128 v[202:205], v151 offset:53248
	ds_read_b128 v[206:209], v151 offset:54272
	ds_read_b128 v[210:213], v151 offset:55296
	ds_read_b128 v[214:217], v151 offset:56320
	s_add_i32 s0, s0, s26
	s_mov_b32 m0, s0
	s_nop 0
	global_load_lds_dwordx4 v196, s[98:99]
	s_add_i32 m0, s0, 0x2000
	s_add_u32 s8, s8, 0x80080
	s_addc_u32 s9, s9, 0
	s_add_i32 s0, s1, s26
	global_load_lds_dwordx4 v130, s[98:99]
	s_mov_b32 m0, s0
	s_nop 0
	global_load_lds_dwordx4 v196, s[8:9]
	s_add_i32 m0, s0, 0x2000
	s_nop 0
	global_load_lds_dwordx4 v130, s[8:9]
	s_mov_b32 m0, s31
	s_nop 0
	global_load_lds_dwordx4 v134, s[78:79]
	s_mov_b32 m0, s34
	s_nop 0
	global_load_lds_dwordx4 v132, s[78:79]
	s_waitcnt vmcnt(8)
	s_waitcnt lgkmcnt(0)
	s_setprio 1
	s_barrier
	v_mfma_f32_16x16x32_bf16 v[62:65], v[142:145], v[180:183], v[62:65]
	v_mfma_f32_16x16x32_bf16 v[58:61], v[156:159], v[180:183], v[58:61]
	v_mfma_f32_16x16x32_bf16 v[54:57], v[142:145], v[188:191], v[54:57]
	v_mfma_f32_16x16x32_bf16 v[46:49], v[156:159], v[188:191], v[46:49]
	v_mfma_f32_16x16x32_bf16 v[38:41], v[142:145], v[202:205], v[38:41]
	v_mfma_f32_16x16x32_bf16 v[30:33], v[156:159], v[202:205], v[30:33]
	v_mfma_f32_16x16x32_bf16 v[22:25], v[142:145], v[210:213], v[22:25]
	v_mfma_f32_16x16x32_bf16 v[14:17], v[156:159], v[210:213], v[14:17]
	v_mfma_f32_16x16x32_bf16 v[62:65], v[152:155], v[184:187], v[62:65]
	v_mfma_f32_16x16x32_bf16 v[58:61], v[160:163], v[184:187], v[58:61]
	v_mfma_f32_16x16x32_bf16 v[54:57], v[152:155], v[192:195], v[54:57]
	v_mfma_f32_16x16x32_bf16 v[46:49], v[160:163], v[192:195], v[46:49]
	v_mfma_f32_16x16x32_bf16 v[38:41], v[152:155], v[206:209], v[38:41]
	v_mfma_f32_16x16x32_bf16 v[30:33], v[160:163], v[206:209], v[30:33]
	v_mfma_f32_16x16x32_bf16 v[22:25], v[152:155], v[214:217], v[22:25]
	v_mfma_f32_16x16x32_bf16 v[14:17], v[160:163], v[214:217], v[14:17]
	v_mfma_f32_16x16x32_bf16 v[50:53], v[164:167], v[180:183], v[50:53]
	v_mfma_f32_16x16x32_bf16 v[42:45], v[172:175], v[180:183], v[42:45]
	v_mfma_f32_16x16x32_bf16 v[34:37], v[164:167], v[188:191], v[34:37]
	v_mfma_f32_16x16x32_bf16 v[26:29], v[172:175], v[188:191], v[26:29]
	v_mfma_f32_16x16x32_bf16 v[18:21], v[164:167], v[202:205], v[18:21]
	v_mfma_f32_16x16x32_bf16 v[10:13], v[172:175], v[202:205], v[10:13]
	v_mfma_f32_16x16x32_bf16 v[6:9], v[164:167], v[210:213], v[6:9]
	v_mfma_f32_16x16x32_bf16 v[2:5], v[172:175], v[210:213], v[2:5]
	v_mfma_f32_16x16x32_bf16 v[50:53], v[168:171], v[184:187], v[50:53]
	v_mfma_f32_16x16x32_bf16 v[42:45], v[176:179], v[184:187], v[42:45]
	v_mfma_f32_16x16x32_bf16 v[34:37], v[168:171], v[192:195], v[34:37]
	v_mfma_f32_16x16x32_bf16 v[26:29], v[176:179], v[192:195], v[26:29]
	v_mfma_f32_16x16x32_bf16 v[18:21], v[168:171], v[206:209], v[18:21]
	v_mfma_f32_16x16x32_bf16 v[10:13], v[176:179], v[206:209], v[10:13]
	v_mfma_f32_16x16x32_bf16 v[6:9], v[168:171], v[214:217], v[6:9]
	v_mfma_f32_16x16x32_bf16 v[2:5], v[176:179], v[214:217], v[2:5]
	s_barrier
	s_setprio 0
	s_add_u32 s69, s69, 0x100
	s_addc_u32 s70, s70, 0
	s_add_u32 s58, s58, 0x100
	s_addc_u32 s59, s59, 0
	s_cmp_ge_i32 s71, s64
	s_mov_b32 s8, s71
	s_cbranch_scc0 .LBB0_1135
	s_and_b64 vcc, exec, s[38:39]
	s_cbranch_vccz .LBB0_1138
	s_barrier

.Ldefbar_skip_3:
	v_add_u32_e32 v250, 0x10000, v244
	ds_read_b128 v[130:133], v250
	ds_read_b128 v[134:137], v250 offset:1024
	ds_read_b128 v[138:141], v250 offset:2048
	ds_read_b128 v[142:145], v250 offset:3072
	ds_read_b128 v[146:149], v250 offset:16384
	ds_read_b128 v[150:153], v250 offset:17408
	ds_read_b128 v[154:157], v250 offset:18432
	ds_read_b128 v[158:161], v250 offset:19456
	ds_read_b128 v[162:165], v246
	ds_read_b128 v[166:169], v246 offset:1024
	ds_read_b128 v[170:173], v246 offset:2048
	ds_read_b128 v[174:177], v246 offset:3072
	ds_read_b128 v[178:181], v246 offset:4096
	ds_read_b128 v[182:185], v246 offset:5120
	ds_read_b128 v[186:189], v246 offset:6144
	ds_read_b128 v[190:193], v246 offset:7168
	s_add_i32 s73, s8, 2
	s_add_u32 s0, s44, 0xfff00080
	s_addc_u32 s1, s45, -1
	s_add_i32 s77, 0, 0x10000
	s_cmp_eq_u32 s70, s8
	s_cselect_b32 s67, s51, s1
	s_cselect_b32 s66, s53, s0
	s_cselect_b32 s9, s49, s72
	s_cselect_b32 s8, s69, s71
	s_add_i32 s78, 0, 0x14000
	s_add_i32 m0, s3, 0xc000
	s_nop 0
	global_load_lds_dwordx4 v210, s[44:45]
	s_add_i32 m0, s3, 0xe000
	s_nop 0
	global_load_lds_dwordx4 v208, s[44:45]
	s_waitcnt vmcnt(8)
	s_waitcnt lgkmcnt(0)
	s_setprio 1
	s_barrier
	v_mfma_f32_16x16x32_bf16 v[126:129], v[130:133], v[162:165], 0
	v_mfma_f32_16x16x32_bf16 v[122:125], v[138:141], v[162:165], 0
	v_mfma_f32_16x16x32_bf16 v[110:113], v[130:133], v[170:173], 0
	v_mfma_f32_16x16x32_bf16 v[106:109], v[138:141], v[170:173], 0
	v_mfma_f32_16x16x32_bf16 v[94:97], v[130:133], v[178:181], 0
	v_mfma_f32_16x16x32_bf16 v[90:93], v[138:141], v[178:181], 0
	v_mfma_f32_16x16x32_bf16 v[78:81], v[130:133], v[186:189], 0
	v_mfma_f32_16x16x32_bf16 v[74:77], v[138:141], v[186:189], 0
	v_mfma_f32_16x16x32_bf16 v[126:129], v[134:137], v[166:169], v[126:129]
	v_mfma_f32_16x16x32_bf16 v[122:125], v[142:145], v[166:169], v[122:125]
	v_mfma_f32_16x16x32_bf16 v[110:113], v[134:137], v[174:177], v[110:113]
	v_mfma_f32_16x16x32_bf16 v[106:109], v[142:145], v[174:177], v[106:109]
	v_mfma_f32_16x16x32_bf16 v[94:97], v[134:137], v[182:185], v[94:97]
	v_mfma_f32_16x16x32_bf16 v[90:93], v[142:145], v[182:185], v[90:93]
	v_mfma_f32_16x16x32_bf16 v[78:81], v[134:137], v[190:193], v[78:81]
	v_mfma_f32_16x16x32_bf16 v[74:77], v[142:145], v[190:193], v[74:77]
	v_mfma_f32_16x16x32_bf16 v[118:121], v[146:149], v[162:165], 0
	v_mfma_f32_16x16x32_bf16 v[114:117], v[154:157], v[162:165], 0
	v_mfma_f32_16x16x32_bf16 v[102:105], v[146:149], v[170:173], 0
	v_mfma_f32_16x16x32_bf16 v[98:101], v[154:157], v[170:173], 0
	v_mfma_f32_16x16x32_bf16 v[86:89], v[146:149], v[178:181], 0
	v_mfma_f32_16x16x32_bf16 v[82:85], v[154:157], v[178:181], 0
	v_mfma_f32_16x16x32_bf16 v[70:73], v[146:149], v[186:189], 0
	v_mfma_f32_16x16x32_bf16 v[66:69], v[154:157], v[186:189], 0
	v_mfma_f32_16x16x32_bf16 v[118:121], v[150:153], v[166:169], v[118:121]
	v_mfma_f32_16x16x32_bf16 v[114:117], v[158:161], v[166:169], v[114:117]
	v_mfma_f32_16x16x32_bf16 v[102:105], v[150:153], v[174:177], v[102:105]
	v_mfma_f32_16x16x32_bf16 v[98:101], v[158:161], v[174:177], v[98:101]
	v_mfma_f32_16x16x32_bf16 v[86:89], v[150:153], v[182:185], v[86:89]
	v_mfma_f32_16x16x32_bf16 v[82:85], v[158:161], v[182:185], v[82:85]
	v_mfma_f32_16x16x32_bf16 v[70:73], v[150:153], v[190:193], v[70:73]
	v_mfma_f32_16x16x32_bf16 v[66:69], v[158:161], v[190:193], v[66:69]
	s_barrier
	s_setprio 0
	ds_read_b128 v[162:165], v246 offset:16384
	ds_read_b128 v[166:169], v246 offset:17408
	ds_read_b128 v[170:173], v246 offset:18432
	ds_read_b128 v[174:177], v246 offset:19456
	ds_read_b128 v[178:181], v246 offset:20480
	ds_read_b128 v[182:185], v246 offset:21504
	ds_read_b128 v[186:189], v246 offset:22528
	ds_read_b128 v[190:193], v246 offset:23552
	s_add_i32 s0, s77, s2
	s_add_u32 s98, s8, s16
	s_addc_u32 s99, s9, s17
	s_mov_b32 m0, s0
	s_nop 0
	global_load_lds_dwordx4 v196, s[8:9]
	s_add_i32 m0, s0, 0x2000
	s_add_u32 s0, s8, 0x100000
	s_addc_u32 s1, s9, 0
	s_add_i32 s77, s78, s2
	global_load_lds_dwordx4 v202, s[8:9]
	s_mov_b32 m0, s77
	v_lshl_add_u64 v[216:217], s[66:67], 0, v[204:205]
	global_load_lds_dwordx4 v196, s[0:1]
	s_add_i32 m0, s77, 0x2000
	s_nop 0
	global_load_lds_dwordx4 v202, s[0:1]
	v_lshl_add_u64 v[214:215], s[66:67], 0, v[206:207]
	s_mov_b32 m0, s3
	s_nop 0
	global_load_lds_dwordx4 v206, s[66:67]
	s_mov_b32 m0, s10
	s_nop 0
	global_load_lds_dwordx4 v204, s[66:67]
	s_waitcnt vmcnt(8)
	s_waitcnt lgkmcnt(0)
	s_setprio 1
	s_barrier
	v_mfma_f32_16x16x32_bf16 v[62:65], v[130:133], v[162:165], 0
	v_mfma_f32_16x16x32_bf16 v[58:61], v[138:141], v[162:165], 0
	v_mfma_f32_16x16x32_bf16 v[46:49], v[130:133], v[170:173], 0
	v_mfma_f32_16x16x32_bf16 v[42:45], v[138:141], v[170:173], 0
	v_mfma_f32_16x16x32_bf16 v[30:33], v[130:133], v[178:181], 0
	v_mfma_f32_16x16x32_bf16 v[26:29], v[138:141], v[178:181], 0
	v_mfma_f32_16x16x32_bf16 v[14:17], v[130:133], v[186:189], 0
	v_mfma_f32_16x16x32_bf16 v[10:13], v[138:141], v[186:189], 0
	v_mfma_f32_16x16x32_bf16 v[62:65], v[134:137], v[166:169], v[62:65]
	v_mfma_f32_16x16x32_bf16 v[58:61], v[142:145], v[166:169], v[58:61]
	v_mfma_f32_16x16x32_bf16 v[46:49], v[134:137], v[174:177], v[46:49]
	v_mfma_f32_16x16x32_bf16 v[42:45], v[142:145], v[174:177], v[42:45]
	v_mfma_f32_16x16x32_bf16 v[30:33], v[134:137], v[182:185], v[30:33]
	v_mfma_f32_16x16x32_bf16 v[26:29], v[142:145], v[182:185], v[26:29]
	v_mfma_f32_16x16x32_bf16 v[14:17], v[134:137], v[190:193], v[14:17]
	v_mfma_f32_16x16x32_bf16 v[10:13], v[142:145], v[190:193], v[10:13]
	v_mfma_f32_16x16x32_bf16 v[54:57], v[146:149], v[162:165], 0
	v_mfma_f32_16x16x32_bf16 v[50:53], v[154:157], v[162:165], 0
	v_mfma_f32_16x16x32_bf16 v[38:41], v[146:149], v[170:173], 0
	v_mfma_f32_16x16x32_bf16 v[34:37], v[154:157], v[170:173], 0
	v_mfma_f32_16x16x32_bf16 v[22:25], v[146:149], v[178:181], 0
	v_mfma_f32_16x16x32_bf16 v[18:21], v[154:157], v[178:181], 0
	v_mfma_f32_16x16x32_bf16 v[6:9], v[146:149], v[186:189], 0
	v_mfma_f32_16x16x32_bf16 v[2:5], v[154:157], v[186:189], 0
	v_mfma_f32_16x16x32_bf16 v[54:57], v[150:153], v[166:169], v[54:57]
	v_mfma_f32_16x16x32_bf16 v[50:53], v[158:161], v[166:169], v[50:53]
	v_mfma_f32_16x16x32_bf16 v[38:41], v[150:153], v[174:177], v[38:41]
	v_mfma_f32_16x16x32_bf16 v[34:37], v[158:161], v[174:177], v[34:37]
	v_mfma_f32_16x16x32_bf16 v[22:25], v[150:153], v[182:185], v[22:25]
	v_mfma_f32_16x16x32_bf16 v[18:21], v[158:161], v[182:185], v[18:21]
	v_mfma_f32_16x16x32_bf16 v[6:9], v[150:153], v[190:193], v[6:9]
	v_mfma_f32_16x16x32_bf16 v[2:5], v[158:161], v[190:193], v[2:5]
	s_barrier
	s_setprio 0
	s_branch .Lkmid_3
.LBB0_2239:
	ds_read_b128 v[130:133], v250
	ds_read_b128 v[134:137], v250 offset:1024
	ds_read_b128 v[138:141], v250 offset:2048
	ds_read_b128 v[142:145], v250 offset:3072
	ds_read_b128 v[146:149], v250 offset:16384
	ds_read_b128 v[150:153], v250 offset:17408
	ds_read_b128 v[154:157], v250 offset:18432
	ds_read_b128 v[158:161], v250 offset:19456
	ds_read_b128 v[162:165], v246
	ds_read_b128 v[166:169], v246 offset:1024
	ds_read_b128 v[170:173], v246 offset:2048
	ds_read_b128 v[174:177], v246 offset:3072
	ds_read_b128 v[178:181], v246 offset:4096
	ds_read_b128 v[182:185], v246 offset:5120
	ds_read_b128 v[186:189], v246 offset:6144
	ds_read_b128 v[190:193], v246 offset:7168
	s_add_i32 s73, s8, 2
	s_add_u32 s0, s44, 0xfff00080
	s_addc_u32 s1, s45, -1
	s_add_i32 s77, 0, 0x10000
	s_cmp_eq_u32 s70, s8
	s_cselect_b32 s67, s51, s1
	s_cselect_b32 s66, s53, s0
	s_cselect_b32 s9, s49, s72
	s_cselect_b32 s8, s69, s71
	s_add_i32 s78, 0, 0x14000
	s_add_i32 m0, s3, 0xc000
	s_nop 0
	global_load_lds_dwordx4 v210, s[44:45]
	s_add_i32 m0, s3, 0xe000
	s_nop 0
	global_load_lds_dwordx4 v208, s[44:45]
	s_waitcnt vmcnt(8)
	s_waitcnt lgkmcnt(0)
	s_setprio 1
	s_barrier
	v_mfma_f32_16x16x32_bf16 v[126:129], v[130:133], v[162:165], v[126:129]
	v_mfma_f32_16x16x32_bf16 v[122:125], v[138:141], v[162:165], v[122:125]
	v_mfma_f32_16x16x32_bf16 v[110:113], v[130:133], v[170:173], v[110:113]
	v_mfma_f32_16x16x32_bf16 v[106:109], v[138:141], v[170:173], v[106:109]
	v_mfma_f32_16x16x32_bf16 v[94:97], v[130:133], v[178:181], v[94:97]
	v_mfma_f32_16x16x32_bf16 v[90:93], v[138:141], v[178:181], v[90:93]
	v_mfma_f32_16x16x32_bf16 v[78:81], v[130:133], v[186:189], v[78:81]
	v_mfma_f32_16x16x32_bf16 v[74:77], v[138:141], v[186:189], v[74:77]
	v_mfma_f32_16x16x32_bf16 v[126:129], v[134:137], v[166:169], v[126:129]
	v_mfma_f32_16x16x32_bf16 v[122:125], v[142:145], v[166:169], v[122:125]
	v_mfma_f32_16x16x32_bf16 v[110:113], v[134:137], v[174:177], v[110:113]
	v_mfma_f32_16x16x32_bf16 v[106:109], v[142:145], v[174:177], v[106:109]
	v_mfma_f32_16x16x32_bf16 v[94:97], v[134:137], v[182:185], v[94:97]
	v_mfma_f32_16x16x32_bf16 v[90:93], v[142:145], v[182:185], v[90:93]
	v_mfma_f32_16x16x32_bf16 v[78:81], v[134:137], v[190:193], v[78:81]
	v_mfma_f32_16x16x32_bf16 v[74:77], v[142:145], v[190:193], v[74:77]
	v_mfma_f32_16x16x32_bf16 v[118:121], v[146:149], v[162:165], v[118:121]
	v_mfma_f32_16x16x32_bf16 v[114:117], v[154:157], v[162:165], v[114:117]
	v_mfma_f32_16x16x32_bf16 v[102:105], v[146:149], v[170:173], v[102:105]
	v_mfma_f32_16x16x32_bf16 v[98:101], v[154:157], v[170:173], v[98:101]
	v_mfma_f32_16x16x32_bf16 v[86:89], v[146:149], v[178:181], v[86:89]
	v_mfma_f32_16x16x32_bf16 v[82:85], v[154:157], v[178:181], v[82:85]
	v_mfma_f32_16x16x32_bf16 v[70:73], v[146:149], v[186:189], v[70:73]
	v_mfma_f32_16x16x32_bf16 v[66:69], v[154:157], v[186:189], v[66:69]
	v_mfma_f32_16x16x32_bf16 v[118:121], v[150:153], v[166:169], v[118:121]
	v_mfma_f32_16x16x32_bf16 v[114:117], v[158:161], v[166:169], v[114:117]
	v_mfma_f32_16x16x32_bf16 v[102:105], v[150:153], v[174:177], v[102:105]
	v_mfma_f32_16x16x32_bf16 v[98:101], v[158:161], v[174:177], v[98:101]
	v_mfma_f32_16x16x32_bf16 v[86:89], v[150:153], v[182:185], v[86:89]
	v_mfma_f32_16x16x32_bf16 v[82:85], v[158:161], v[182:185], v[82:85]
	v_mfma_f32_16x16x32_bf16 v[70:73], v[150:153], v[190:193], v[70:73]
	v_mfma_f32_16x16x32_bf16 v[66:69], v[158:161], v[190:193], v[66:69]
	s_barrier
	s_setprio 0
	ds_read_b128 v[162:165], v246 offset:16384
	ds_read_b128 v[166:169], v246 offset:17408
	ds_read_b128 v[170:173], v246 offset:18432
	ds_read_b128 v[174:177], v246 offset:19456
	ds_read_b128 v[178:181], v246 offset:20480
	ds_read_b128 v[182:185], v246 offset:21504
	ds_read_b128 v[186:189], v246 offset:22528
	ds_read_b128 v[190:193], v246 offset:23552
	s_add_i32 s0, s77, s2
	s_add_u32 s98, s8, s16
	s_addc_u32 s99, s9, s17
	s_mov_b32 m0, s0
	s_nop 0
	global_load_lds_dwordx4 v196, s[8:9]
	s_add_i32 m0, s0, 0x2000
	s_add_u32 s0, s8, 0x100000
	s_addc_u32 s1, s9, 0
	s_add_i32 s77, s78, s2
	global_load_lds_dwordx4 v202, s[8:9]
	s_mov_b32 m0, s77
	v_lshl_add_u64 v[216:217], s[66:67], 0, v[204:205]
	global_load_lds_dwordx4 v196, s[0:1]
	s_add_i32 m0, s77, 0x2000
	s_nop 0
	global_load_lds_dwordx4 v202, s[0:1]
	v_lshl_add_u64 v[214:215], s[66:67], 0, v[206:207]
	s_mov_b32 m0, s3
	s_nop 0
	global_load_lds_dwordx4 v206, s[66:67]
	s_mov_b32 m0, s10
	s_nop 0
	global_load_lds_dwordx4 v204, s[66:67]
	s_waitcnt vmcnt(8)
	s_waitcnt lgkmcnt(0)
	s_setprio 1
	s_barrier
	v_mfma_f32_16x16x32_bf16 v[62:65], v[130:133], v[162:165], v[62:65]
	v_mfma_f32_16x16x32_bf16 v[58:61], v[138:141], v[162:165], v[58:61]
	v_mfma_f32_16x16x32_bf16 v[46:49], v[130:133], v[170:173], v[46:49]
	v_mfma_f32_16x16x32_bf16 v[42:45], v[138:141], v[170:173], v[42:45]
	v_mfma_f32_16x16x32_bf16 v[30:33], v[130:133], v[178:181], v[30:33]
	v_mfma_f32_16x16x32_bf16 v[26:29], v[138:141], v[178:181], v[26:29]
	v_mfma_f32_16x16x32_bf16 v[14:17], v[130:133], v[186:189], v[14:17]
	v_mfma_f32_16x16x32_bf16 v[10:13], v[138:141], v[186:189], v[10:13]
	v_mfma_f32_16x16x32_bf16 v[62:65], v[134:137], v[166:169], v[62:65]
	v_mfma_f32_16x16x32_bf16 v[58:61], v[142:145], v[166:169], v[58:61]
	v_mfma_f32_16x16x32_bf16 v[46:49], v[134:137], v[174:177], v[46:49]
	v_mfma_f32_16x16x32_bf16 v[42:45], v[142:145], v[174:177], v[42:45]
	v_mfma_f32_16x16x32_bf16 v[30:33], v[134:137], v[182:185], v[30:33]
	v_mfma_f32_16x16x32_bf16 v[26:29], v[142:145], v[182:185], v[26:29]
	v_mfma_f32_16x16x32_bf16 v[14:17], v[134:137], v[190:193], v[14:17]
	v_mfma_f32_16x16x32_bf16 v[10:13], v[142:145], v[190:193], v[10:13]
	v_mfma_f32_16x16x32_bf16 v[54:57], v[146:149], v[162:165], v[54:57]
	v_mfma_f32_16x16x32_bf16 v[50:53], v[154:157], v[162:165], v[50:53]
	v_mfma_f32_16x16x32_bf16 v[38:41], v[146:149], v[170:173], v[38:41]
	v_mfma_f32_16x16x32_bf16 v[34:37], v[154:157], v[170:173], v[34:37]
	v_mfma_f32_16x16x32_bf16 v[22:25], v[146:149], v[178:181], v[22:25]
	v_mfma_f32_16x16x32_bf16 v[18:21], v[154:157], v[178:181], v[18:21]
	v_mfma_f32_16x16x32_bf16 v[6:9], v[146:149], v[186:189], v[6:9]
	v_mfma_f32_16x16x32_bf16 v[2:5], v[154:157], v[186:189], v[2:5]
	v_mfma_f32_16x16x32_bf16 v[54:57], v[150:153], v[166:169], v[54:57]
	v_mfma_f32_16x16x32_bf16 v[50:53], v[158:161], v[166:169], v[50:53]
	v_mfma_f32_16x16x32_bf16 v[38:41], v[150:153], v[174:177], v[38:41]
	v_mfma_f32_16x16x32_bf16 v[34:37], v[158:161], v[174:177], v[34:37]
	v_mfma_f32_16x16x32_bf16 v[22:25], v[150:153], v[182:185], v[22:25]
	v_mfma_f32_16x16x32_bf16 v[18:21], v[158:161], v[182:185], v[18:21]
	v_mfma_f32_16x16x32_bf16 v[6:9], v[150:153], v[190:193], v[6:9]
	v_mfma_f32_16x16x32_bf16 v[2:5], v[158:161], v[190:193], v[2:5]
	s_barrier
	s_setprio 0
.Lkmid_3:
	ds_read_b128 v[130:133], v250 offset:32768
	ds_read_b128 v[134:137], v250 offset:33792
	ds_read_b128 v[138:141], v250 offset:34816
	ds_read_b128 v[142:145], v250 offset:35840
	ds_read_b128 v[146:149], v250 offset:49152
	ds_read_b128 v[150:153], v250 offset:50176
	ds_read_b128 v[154:157], v250 offset:51200
	ds_read_b128 v[158:161], v250 offset:52224
	ds_read_b128 v[162:165], v246 offset:32768
	ds_read_b128 v[166:169], v246 offset:33792
	ds_read_b128 v[170:173], v246 offset:34816
	ds_read_b128 v[174:177], v246 offset:35840
	ds_read_b128 v[178:181], v246 offset:36864
	ds_read_b128 v[182:185], v246 offset:37888
	ds_read_b128 v[186:189], v246 offset:38912
	ds_read_b128 v[190:193], v246 offset:39936
	s_add_i32 s77, 0, 0x18000
	s_add_i32 s78, 0, 0x1c000
	s_add_u32 s0, s66, 0x100000
	s_addc_u32 s1, s67, 0
	s_mov_b32 m0, s11
	s_nop 0
	global_load_lds_dwordx4 v206, s[0:1]
	s_mov_b32 m0, s26
	s_nop 0
	global_load_lds_dwordx4 v204, s[0:1]
	s_waitcnt vmcnt(8)
	s_waitcnt lgkmcnt(0)
	s_setprio 1
	s_barrier
	v_mfma_f32_16x16x32_bf16 v[126:129], v[130:133], v[162:165], v[126:129]
	v_mfma_f32_16x16x32_bf16 v[122:125], v[138:141], v[162:165], v[122:125]
	v_mfma_f32_16x16x32_bf16 v[110:113], v[130:133], v[170:173], v[110:113]
	v_mfma_f32_16x16x32_bf16 v[106:109], v[138:141], v[170:173], v[106:109]
	v_mfma_f32_16x16x32_bf16 v[94:97], v[130:133], v[178:181], v[94:97]
	v_mfma_f32_16x16x32_bf16 v[90:93], v[138:141], v[178:181], v[90:93]
	v_mfma_f32_16x16x32_bf16 v[78:81], v[130:133], v[186:189], v[78:81]
	v_mfma_f32_16x16x32_bf16 v[74:77], v[138:141], v[186:189], v[74:77]
	v_mfma_f32_16x16x32_bf16 v[126:129], v[134:137], v[166:169], v[126:129]
	v_mfma_f32_16x16x32_bf16 v[122:125], v[142:145], v[166:169], v[122:125]
	v_mfma_f32_16x16x32_bf16 v[110:113], v[134:137], v[174:177], v[110:113]
	v_mfma_f32_16x16x32_bf16 v[106:109], v[142:145], v[174:177], v[106:109]
	v_mfma_f32_16x16x32_bf16 v[94:97], v[134:137], v[182:185], v[94:97]
	v_mfma_f32_16x16x32_bf16 v[90:93], v[142:145], v[182:185], v[90:93]
	v_mfma_f32_16x16x32_bf16 v[78:81], v[134:137], v[190:193], v[78:81]
	v_mfma_f32_16x16x32_bf16 v[74:77], v[142:145], v[190:193], v[74:77]
	v_mfma_f32_16x16x32_bf16 v[118:121], v[146:149], v[162:165], v[118:121]
	v_mfma_f32_16x16x32_bf16 v[114:117], v[154:157], v[162:165], v[114:117]
	v_mfma_f32_16x16x32_bf16 v[102:105], v[146:149], v[170:173], v[102:105]
	v_mfma_f32_16x16x32_bf16 v[98:101], v[154:157], v[170:173], v[98:101]
	v_mfma_f32_16x16x32_bf16 v[86:89], v[146:149], v[178:181], v[86:89]
	v_mfma_f32_16x16x32_bf16 v[82:85], v[154:157], v[178:181], v[82:85]
	v_mfma_f32_16x16x32_bf16 v[70:73], v[146:149], v[186:189], v[70:73]
	v_mfma_f32_16x16x32_bf16 v[66:69], v[154:157], v[186:189], v[66:69]
	v_mfma_f32_16x16x32_bf16 v[118:121], v[150:153], v[166:169], v[118:121]
	v_mfma_f32_16x16x32_bf16 v[114:117], v[158:161], v[166:169], v[114:117]
	v_mfma_f32_16x16x32_bf16 v[102:105], v[150:153], v[174:177], v[102:105]
	v_mfma_f32_16x16x32_bf16 v[98:101], v[158:161], v[174:177], v[98:101]
	v_mfma_f32_16x16x32_bf16 v[86:89], v[150:153], v[182:185], v[86:89]
	v_mfma_f32_16x16x32_bf16 v[82:85], v[158:161], v[182:185], v[82:85]
	v_mfma_f32_16x16x32_bf16 v[70:73], v[150:153], v[190:193], v[70:73]
	v_mfma_f32_16x16x32_bf16 v[66:69], v[158:161], v[190:193], v[66:69]
	s_barrier
	s_setprio 0
	ds_read_b128 v[162:165], v246 offset:49152
	ds_read_b128 v[166:169], v246 offset:50176
	ds_read_b128 v[170:173], v246 offset:51200
	ds_read_b128 v[174:177], v246 offset:52224
	ds_read_b128 v[178:181], v246 offset:53248
	ds_read_b128 v[182:185], v246 offset:54272
	ds_read_b128 v[186:189], v246 offset:55296
	ds_read_b128 v[190:193], v246 offset:56320
	s_add_i32 s0, s77, s2
	s_mov_b32 m0, s0
	s_nop 0
	global_load_lds_dwordx4 v196, s[98:99]
	s_add_i32 m0, s0, 0x2000
	s_add_u32 s0, s8, 0x100080
	s_addc_u32 s1, s9, 0
	s_add_i32 s8, s78, s2
	global_load_lds_dwordx4 v202, s[98:99]
	s_mov_b32 m0, s8
	s_nop 0
	global_load_lds_dwordx4 v196, s[0:1]
	s_add_i32 m0, s8, 0x2000
	s_nop 0
	global_load_lds_dwordx4 v202, s[0:1]
	v_lshl_add_u64 v[194:195], v[214:215], 0, s[16:17]
	s_mov_b32 m0, s27
	s_nop 0
	global_load_lds_dwordx4 v[194:195], off
	v_lshl_add_u64 v[194:195], v[216:217], 0, s[16:17]
	s_mov_b32 m0, s28
	s_nop 0
	global_load_lds_dwordx4 v[194:195], off
	s_waitcnt vmcnt(8)
	s_waitcnt lgkmcnt(0)
	s_setprio 1
	s_barrier
	v_mfma_f32_16x16x32_bf16 v[62:65], v[130:133], v[162:165], v[62:65]
	v_mfma_f32_16x16x32_bf16 v[58:61], v[138:141], v[162:165], v[58:61]
	v_mfma_f32_16x16x32_bf16 v[46:49], v[130:133], v[170:173], v[46:49]
	v_mfma_f32_16x16x32_bf16 v[42:45], v[138:141], v[170:173], v[42:45]
	v_mfma_f32_16x16x32_bf16 v[30:33], v[130:133], v[178:181], v[30:33]
	v_mfma_f32_16x16x32_bf16 v[26:29], v[138:141], v[178:181], v[26:29]
	v_mfma_f32_16x16x32_bf16 v[14:17], v[130:133], v[186:189], v[14:17]
	v_mfma_f32_16x16x32_bf16 v[10:13], v[138:141], v[186:189], v[10:13]
	v_mfma_f32_16x16x32_bf16 v[62:65], v[134:137], v[166:169], v[62:65]
	v_mfma_f32_16x16x32_bf16 v[58:61], v[142:145], v[166:169], v[58:61]
	v_mfma_f32_16x16x32_bf16 v[46:49], v[134:137], v[174:177], v[46:49]
	v_mfma_f32_16x16x32_bf16 v[42:45], v[142:145], v[174:177], v[42:45]
	v_mfma_f32_16x16x32_bf16 v[30:33], v[134:137], v[182:185], v[30:33]
	v_mfma_f32_16x16x32_bf16 v[26:29], v[142:145], v[182:185], v[26:29]
	v_mfma_f32_16x16x32_bf16 v[14:17], v[134:137], v[190:193], v[14:17]
	v_mfma_f32_16x16x32_bf16 v[10:13], v[142:145], v[190:193], v[10:13]
	v_mfma_f32_16x16x32_bf16 v[54:57], v[146:149], v[162:165], v[54:57]
	v_mfma_f32_16x16x32_bf16 v[50:53], v[154:157], v[162:165], v[50:53]
	v_mfma_f32_16x16x32_bf16 v[38:41], v[146:149], v[170:173], v[38:41]
	v_mfma_f32_16x16x32_bf16 v[34:37], v[154:157], v[170:173], v[34:37]
	v_mfma_f32_16x16x32_bf16 v[22:25], v[146:149], v[178:181], v[22:25]
	v_mfma_f32_16x16x32_bf16 v[18:21], v[154:157], v[178:181], v[18:21]
	v_mfma_f32_16x16x32_bf16 v[6:9], v[146:149], v[186:189], v[6:9]
	v_mfma_f32_16x16x32_bf16 v[2:5], v[154:157], v[186:189], v[2:5]
	v_mfma_f32_16x16x32_bf16 v[54:57], v[150:153], v[166:169], v[54:57]
	v_mfma_f32_16x16x32_bf16 v[50:53], v[158:161], v[166:169], v[50:53]
	v_mfma_f32_16x16x32_bf16 v[38:41], v[150:153], v[174:177], v[38:41]
	v_mfma_f32_16x16x32_bf16 v[34:37], v[158:161], v[174:177], v[34:37]
	v_mfma_f32_16x16x32_bf16 v[22:25], v[150:153], v[182:185], v[22:25]
	v_mfma_f32_16x16x32_bf16 v[18:21], v[158:161], v[182:185], v[18:21]
	v_mfma_f32_16x16x32_bf16 v[6:9], v[150:153], v[190:193], v[6:9]
	v_mfma_f32_16x16x32_bf16 v[2:5], v[158:161], v[190:193], v[2:5]
	s_barrier
	s_setprio 0
	s_add_u32 s71, s71, 0x100
	s_addc_u32 s72, s72, 0
	s_add_u32 s44, s44, 0x100
	s_addc_u32 s45, s45, 0
	s_cmp_ge_i32 s73, s35
	s_mov_b32 s8, s73
	s_cbranch_scc0 .LBB0_2239
	s_and_b64 vcc, exec, s[46:47]
	s_cbranch_vccz .LBB0_2242
	s_barrier

.Ldefbar_skip_4:
	v_add_u32_e32 v250, 0x10000, v188
	ds_read_b128 v[130:133], v250
	ds_read_b128 v[134:137], v250 offset:1024
	ds_read_b128 v[138:141], v250 offset:2048
	ds_read_b128 v[142:145], v250 offset:3072
	ds_read_b128 v[146:149], v250 offset:16384
	ds_read_b128 v[150:153], v250 offset:17408
	ds_read_b128 v[154:157], v250 offset:18432
	ds_read_b128 v[158:161], v250 offset:19456
	ds_read_b128 v[162:165], v189
	ds_read_b128 v[180:183], v189 offset:1024
	ds_read_b128 v[184:187], v189 offset:2048
	ds_read_b128 v[190:193], v189 offset:3072
	ds_read_b128 v[202:205], v189 offset:4096
	ds_read_b128 v[206:209], v189 offset:5120
	ds_read_b128 v[210:213], v189 offset:6144
	ds_read_b128 v[214:217], v189 offset:7168
	s_add_i32 s77, s8, 2
	s_add_u32 s0, s62, 0xfff80080
	s_addc_u32 s1, s63, -1
	s_add_i32 s78, 0, 0x10000
	s_cmp_eq_u32 s71, s8
	s_cselect_b32 s65, s41, s1
	s_cselect_b32 s64, s45, s0
	s_cselect_b32 s9, s43, s73
	s_cselect_b32 s8, s70, s72
	s_add_i32 s79, 0, 0x14000
	s_add_i32 m0, s27, 0xc000
	s_nop 0
	global_load_lds_dwordx4 v178, s[62:63]
	s_add_i32 m0, s27, 0xe000
	s_nop 0
	global_load_lds_dwordx4 v176, s[62:63]
	s_waitcnt vmcnt(8)
	s_waitcnt lgkmcnt(0)
	s_setprio 1
	s_barrier
	v_mfma_f32_16x16x32_bf16 v[126:129], v[130:133], v[162:165], 0
	v_mfma_f32_16x16x32_bf16 v[122:125], v[138:141], v[162:165], 0
	v_mfma_f32_16x16x32_bf16 v[110:113], v[130:133], v[184:187], 0
	v_mfma_f32_16x16x32_bf16 v[106:109], v[138:141], v[184:187], 0
	v_mfma_f32_16x16x32_bf16 v[98:101], v[130:133], v[202:205], 0
	v_mfma_f32_16x16x32_bf16 v[90:93], v[138:141], v[202:205], 0
	v_mfma_f32_16x16x32_bf16 v[82:85], v[130:133], v[210:213], 0
	v_mfma_f32_16x16x32_bf16 v[74:77], v[138:141], v[210:213], 0
	v_mfma_f32_16x16x32_bf16 v[126:129], v[134:137], v[180:183], v[126:129]
	v_mfma_f32_16x16x32_bf16 v[122:125], v[142:145], v[180:183], v[122:125]
	v_mfma_f32_16x16x32_bf16 v[110:113], v[134:137], v[190:193], v[110:113]
	v_mfma_f32_16x16x32_bf16 v[106:109], v[142:145], v[190:193], v[106:109]
	v_mfma_f32_16x16x32_bf16 v[98:101], v[134:137], v[206:209], v[98:101]
	v_mfma_f32_16x16x32_bf16 v[90:93], v[142:145], v[206:209], v[90:93]
	v_mfma_f32_16x16x32_bf16 v[82:85], v[134:137], v[214:217], v[82:85]
	v_mfma_f32_16x16x32_bf16 v[74:77], v[142:145], v[214:217], v[74:77]
	v_mfma_f32_16x16x32_bf16 v[118:121], v[146:149], v[162:165], 0
	v_mfma_f32_16x16x32_bf16 v[114:117], v[154:157], v[162:165], 0
	v_mfma_f32_16x16x32_bf16 v[102:105], v[146:149], v[184:187], 0
	v_mfma_f32_16x16x32_bf16 v[94:97], v[154:157], v[184:187], 0
	v_mfma_f32_16x16x32_bf16 v[86:89], v[146:149], v[202:205], 0
	v_mfma_f32_16x16x32_bf16 v[78:81], v[154:157], v[202:205], 0
	v_mfma_f32_16x16x32_bf16 v[70:73], v[146:149], v[210:213], 0
	v_mfma_f32_16x16x32_bf16 v[66:69], v[154:157], v[210:213], 0
	v_mfma_f32_16x16x32_bf16 v[118:121], v[150:153], v[180:183], v[118:121]
	v_mfma_f32_16x16x32_bf16 v[114:117], v[158:161], v[180:183], v[114:117]
	v_mfma_f32_16x16x32_bf16 v[102:105], v[150:153], v[190:193], v[102:105]
	v_mfma_f32_16x16x32_bf16 v[94:97], v[158:161], v[190:193], v[94:97]
	v_mfma_f32_16x16x32_bf16 v[86:89], v[150:153], v[206:209], v[86:89]
	v_mfma_f32_16x16x32_bf16 v[78:81], v[158:161], v[206:209], v[78:81]
	v_mfma_f32_16x16x32_bf16 v[70:73], v[150:153], v[214:217], v[70:73]
	v_mfma_f32_16x16x32_bf16 v[66:69], v[158:161], v[214:217], v[66:69]
	s_barrier
	s_setprio 0
	ds_read_b128 v[162:165], v189 offset:16384
	ds_read_b128 v[180:183], v189 offset:17408
	ds_read_b128 v[184:187], v189 offset:18432
	ds_read_b128 v[190:193], v189 offset:19456
	ds_read_b128 v[202:205], v189 offset:20480
	ds_read_b128 v[206:209], v189 offset:21504
	ds_read_b128 v[210:213], v189 offset:22528
	ds_read_b128 v[214:217], v189 offset:23552
	s_add_i32 s0, s78, s26
	s_add_u32 s98, s8, s16
	s_addc_u32 s99, s9, s17
	s_mov_b32 m0, s0
	s_nop 0
	global_load_lds_dwordx4 v196, s[8:9]
	s_add_i32 m0, s0, 0x2000
	s_add_u32 s0, s8, 0x80000
	s_addc_u32 s1, s9, 0
	s_add_i32 s78, s79, s26
	global_load_lds_dwordx4 v170, s[8:9]
	s_mov_b32 m0, s78
	v_lshl_add_u64 v[222:223], s[64:65], 0, v[168:169]
	global_load_lds_dwordx4 v196, s[0:1]
	s_add_i32 m0, s78, 0x2000
	s_nop 0
	global_load_lds_dwordx4 v170, s[0:1]
	v_lshl_add_u64 v[220:221], s[64:65], 0, v[166:167]
	s_mov_b32 m0, s27
	s_nop 0
	global_load_lds_dwordx4 v166, s[64:65]
	s_mov_b32 m0, s28
	s_nop 0
	global_load_lds_dwordx4 v168, s[64:65]
	s_waitcnt vmcnt(8)
	s_waitcnt lgkmcnt(0)
	s_setprio 1
	s_barrier
	v_mfma_f32_16x16x32_bf16 v[62:65], v[130:133], v[162:165], 0
	v_mfma_f32_16x16x32_bf16 v[58:61], v[138:141], v[162:165], 0
	v_mfma_f32_16x16x32_bf16 v[50:53], v[130:133], v[184:187], 0
	v_mfma_f32_16x16x32_bf16 v[42:45], v[138:141], v[184:187], 0
	v_mfma_f32_16x16x32_bf16 v[34:37], v[130:133], v[202:205], 0
	v_mfma_f32_16x16x32_bf16 v[26:29], v[138:141], v[202:205], 0
	v_mfma_f32_16x16x32_bf16 v[18:21], v[130:133], v[210:213], 0
	v_mfma_f32_16x16x32_bf16 v[10:13], v[138:141], v[210:213], 0
	v_mfma_f32_16x16x32_bf16 v[62:65], v[134:137], v[180:183], v[62:65]
	v_mfma_f32_16x16x32_bf16 v[58:61], v[142:145], v[180:183], v[58:61]
	v_mfma_f32_16x16x32_bf16 v[50:53], v[134:137], v[190:193], v[50:53]
	v_mfma_f32_16x16x32_bf16 v[42:45], v[142:145], v[190:193], v[42:45]
	v_mfma_f32_16x16x32_bf16 v[34:37], v[134:137], v[206:209], v[34:37]
	v_mfma_f32_16x16x32_bf16 v[26:29], v[142:145], v[206:209], v[26:29]
	v_mfma_f32_16x16x32_bf16 v[18:21], v[134:137], v[214:217], v[18:21]
	v_mfma_f32_16x16x32_bf16 v[10:13], v[142:145], v[214:217], v[10:13]
	v_mfma_f32_16x16x32_bf16 v[54:57], v[146:149], v[162:165], 0
	v_mfma_f32_16x16x32_bf16 v[46:49], v[154:157], v[162:165], 0
	v_mfma_f32_16x16x32_bf16 v[38:41], v[146:149], v[184:187], 0
	v_mfma_f32_16x16x32_bf16 v[30:33], v[154:157], v[184:187], 0
	v_mfma_f32_16x16x32_bf16 v[22:25], v[146:149], v[202:205], 0
	v_mfma_f32_16x16x32_bf16 v[14:17], v[154:157], v[202:205], 0
	v_mfma_f32_16x16x32_bf16 v[6:9], v[146:149], v[210:213], 0
	v_mfma_f32_16x16x32_bf16 v[2:5], v[154:157], v[210:213], 0
	v_mfma_f32_16x16x32_bf16 v[54:57], v[150:153], v[180:183], v[54:57]
	v_mfma_f32_16x16x32_bf16 v[46:49], v[158:161], v[180:183], v[46:49]
	v_mfma_f32_16x16x32_bf16 v[38:41], v[150:153], v[190:193], v[38:41]
	v_mfma_f32_16x16x32_bf16 v[30:33], v[158:161], v[190:193], v[30:33]
	v_mfma_f32_16x16x32_bf16 v[22:25], v[150:153], v[206:209], v[22:25]
	v_mfma_f32_16x16x32_bf16 v[14:17], v[158:161], v[206:209], v[14:17]
	v_mfma_f32_16x16x32_bf16 v[6:9], v[150:153], v[214:217], v[6:9]
	v_mfma_f32_16x16x32_bf16 v[2:5], v[158:161], v[214:217], v[2:5]
	s_barrier
	s_setprio 0
	s_branch .Lkmid_4
.LBB0_2357:
	ds_read_b128 v[130:133], v250
	ds_read_b128 v[134:137], v250 offset:1024
	ds_read_b128 v[138:141], v250 offset:2048
	ds_read_b128 v[142:145], v250 offset:3072
	ds_read_b128 v[146:149], v250 offset:16384
	ds_read_b128 v[150:153], v250 offset:17408
	ds_read_b128 v[154:157], v250 offset:18432
	ds_read_b128 v[158:161], v250 offset:19456
	ds_read_b128 v[162:165], v189
	ds_read_b128 v[180:183], v189 offset:1024
	ds_read_b128 v[184:187], v189 offset:2048
	ds_read_b128 v[190:193], v189 offset:3072
	ds_read_b128 v[202:205], v189 offset:4096
	ds_read_b128 v[206:209], v189 offset:5120
	ds_read_b128 v[210:213], v189 offset:6144
	ds_read_b128 v[214:217], v189 offset:7168
	s_add_i32 s77, s8, 2
	s_add_u32 s0, s62, 0xfff80080
	s_addc_u32 s1, s63, -1
	s_add_i32 s78, 0, 0x10000
	s_cmp_eq_u32 s71, s8
	s_cselect_b32 s65, s41, s1
	s_cselect_b32 s64, s45, s0
	s_cselect_b32 s9, s43, s73
	s_cselect_b32 s8, s70, s72
	s_add_i32 s79, 0, 0x14000
	s_add_i32 m0, s27, 0xc000
	s_nop 0
	global_load_lds_dwordx4 v178, s[62:63]
	s_add_i32 m0, s27, 0xe000
	s_nop 0
	global_load_lds_dwordx4 v176, s[62:63]
	s_waitcnt vmcnt(8)
	s_waitcnt lgkmcnt(0)
	s_setprio 1
	s_barrier
	v_mfma_f32_16x16x32_bf16 v[126:129], v[130:133], v[162:165], v[126:129]
	v_mfma_f32_16x16x32_bf16 v[122:125], v[138:141], v[162:165], v[122:125]
	v_mfma_f32_16x16x32_bf16 v[110:113], v[130:133], v[184:187], v[110:113]
	v_mfma_f32_16x16x32_bf16 v[106:109], v[138:141], v[184:187], v[106:109]
	v_mfma_f32_16x16x32_bf16 v[98:101], v[130:133], v[202:205], v[98:101]
	v_mfma_f32_16x16x32_bf16 v[90:93], v[138:141], v[202:205], v[90:93]
	v_mfma_f32_16x16x32_bf16 v[82:85], v[130:133], v[210:213], v[82:85]
	v_mfma_f32_16x16x32_bf16 v[74:77], v[138:141], v[210:213], v[74:77]
	v_mfma_f32_16x16x32_bf16 v[126:129], v[134:137], v[180:183], v[126:129]
	v_mfma_f32_16x16x32_bf16 v[122:125], v[142:145], v[180:183], v[122:125]
	v_mfma_f32_16x16x32_bf16 v[110:113], v[134:137], v[190:193], v[110:113]
	v_mfma_f32_16x16x32_bf16 v[106:109], v[142:145], v[190:193], v[106:109]
	v_mfma_f32_16x16x32_bf16 v[98:101], v[134:137], v[206:209], v[98:101]
	v_mfma_f32_16x16x32_bf16 v[90:93], v[142:145], v[206:209], v[90:93]
	v_mfma_f32_16x16x32_bf16 v[82:85], v[134:137], v[214:217], v[82:85]
	v_mfma_f32_16x16x32_bf16 v[74:77], v[142:145], v[214:217], v[74:77]
	v_mfma_f32_16x16x32_bf16 v[118:121], v[146:149], v[162:165], v[118:121]
	v_mfma_f32_16x16x32_bf16 v[114:117], v[154:157], v[162:165], v[114:117]
	v_mfma_f32_16x16x32_bf16 v[102:105], v[146:149], v[184:187], v[102:105]
	v_mfma_f32_16x16x32_bf16 v[94:97], v[154:157], v[184:187], v[94:97]
	v_mfma_f32_16x16x32_bf16 v[86:89], v[146:149], v[202:205], v[86:89]
	v_mfma_f32_16x16x32_bf16 v[78:81], v[154:157], v[202:205], v[78:81]
	v_mfma_f32_16x16x32_bf16 v[70:73], v[146:149], v[210:213], v[70:73]
	v_mfma_f32_16x16x32_bf16 v[66:69], v[154:157], v[210:213], v[66:69]
	v_mfma_f32_16x16x32_bf16 v[118:121], v[150:153], v[180:183], v[118:121]
	v_mfma_f32_16x16x32_bf16 v[114:117], v[158:161], v[180:183], v[114:117]
	v_mfma_f32_16x16x32_bf16 v[102:105], v[150:153], v[190:193], v[102:105]
	v_mfma_f32_16x16x32_bf16 v[94:97], v[158:161], v[190:193], v[94:97]
	v_mfma_f32_16x16x32_bf16 v[86:89], v[150:153], v[206:209], v[86:89]
	v_mfma_f32_16x16x32_bf16 v[78:81], v[158:161], v[206:209], v[78:81]
	v_mfma_f32_16x16x32_bf16 v[70:73], v[150:153], v[214:217], v[70:73]
	v_mfma_f32_16x16x32_bf16 v[66:69], v[158:161], v[214:217], v[66:69]
	s_barrier
	s_setprio 0
	ds_read_b128 v[162:165], v189 offset:16384
	ds_read_b128 v[180:183], v189 offset:17408
	ds_read_b128 v[184:187], v189 offset:18432
	ds_read_b128 v[190:193], v189 offset:19456
	ds_read_b128 v[202:205], v189 offset:20480
	ds_read_b128 v[206:209], v189 offset:21504
	ds_read_b128 v[210:213], v189 offset:22528
	ds_read_b128 v[214:217], v189 offset:23552
	s_add_i32 s0, s78, s26
	s_add_u32 s98, s8, s16
	s_addc_u32 s99, s9, s17
	s_mov_b32 m0, s0
	s_nop 0
	global_load_lds_dwordx4 v196, s[8:9]
	s_add_i32 m0, s0, 0x2000
	s_add_u32 s0, s8, 0x80000
	s_addc_u32 s1, s9, 0
	s_add_i32 s78, s79, s26
	global_load_lds_dwordx4 v170, s[8:9]
	s_mov_b32 m0, s78
	v_lshl_add_u64 v[222:223], s[64:65], 0, v[168:169]
	global_load_lds_dwordx4 v196, s[0:1]
	s_add_i32 m0, s78, 0x2000
	s_nop 0
	global_load_lds_dwordx4 v170, s[0:1]
	v_lshl_add_u64 v[220:221], s[64:65], 0, v[166:167]
	s_mov_b32 m0, s27
	s_nop 0
	global_load_lds_dwordx4 v166, s[64:65]
	s_mov_b32 m0, s28
	s_nop 0
	global_load_lds_dwordx4 v168, s[64:65]
	s_waitcnt vmcnt(8)
	s_waitcnt lgkmcnt(0)
	s_setprio 1
	s_barrier
	v_mfma_f32_16x16x32_bf16 v[62:65], v[130:133], v[162:165], v[62:65]
	v_mfma_f32_16x16x32_bf16 v[58:61], v[138:141], v[162:165], v[58:61]
	v_mfma_f32_16x16x32_bf16 v[50:53], v[130:133], v[184:187], v[50:53]
	v_mfma_f32_16x16x32_bf16 v[42:45], v[138:141], v[184:187], v[42:45]
	v_mfma_f32_16x16x32_bf16 v[34:37], v[130:133], v[202:205], v[34:37]
	v_mfma_f32_16x16x32_bf16 v[26:29], v[138:141], v[202:205], v[26:29]
	v_mfma_f32_16x16x32_bf16 v[18:21], v[130:133], v[210:213], v[18:21]
	v_mfma_f32_16x16x32_bf16 v[10:13], v[138:141], v[210:213], v[10:13]
	v_mfma_f32_16x16x32_bf16 v[62:65], v[134:137], v[180:183], v[62:65]
	v_mfma_f32_16x16x32_bf16 v[58:61], v[142:145], v[180:183], v[58:61]
	v_mfma_f32_16x16x32_bf16 v[50:53], v[134:137], v[190:193], v[50:53]
	v_mfma_f32_16x16x32_bf16 v[42:45], v[142:145], v[190:193], v[42:45]
	v_mfma_f32_16x16x32_bf16 v[34:37], v[134:137], v[206:209], v[34:37]
	v_mfma_f32_16x16x32_bf16 v[26:29], v[142:145], v[206:209], v[26:29]
	v_mfma_f32_16x16x32_bf16 v[18:21], v[134:137], v[214:217], v[18:21]
	v_mfma_f32_16x16x32_bf16 v[10:13], v[142:145], v[214:217], v[10:13]
	v_mfma_f32_16x16x32_bf16 v[54:57], v[146:149], v[162:165], v[54:57]
	v_mfma_f32_16x16x32_bf16 v[46:49], v[154:157], v[162:165], v[46:49]
	v_mfma_f32_16x16x32_bf16 v[38:41], v[146:149], v[184:187], v[38:41]
	v_mfma_f32_16x16x32_bf16 v[30:33], v[154:157], v[184:187], v[30:33]
	v_mfma_f32_16x16x32_bf16 v[22:25], v[146:149], v[202:205], v[22:25]
	v_mfma_f32_16x16x32_bf16 v[14:17], v[154:157], v[202:205], v[14:17]
	v_mfma_f32_16x16x32_bf16 v[6:9], v[146:149], v[210:213], v[6:9]
	v_mfma_f32_16x16x32_bf16 v[2:5], v[154:157], v[210:213], v[2:5]
	v_mfma_f32_16x16x32_bf16 v[54:57], v[150:153], v[180:183], v[54:57]
	v_mfma_f32_16x16x32_bf16 v[46:49], v[158:161], v[180:183], v[46:49]
	v_mfma_f32_16x16x32_bf16 v[38:41], v[150:153], v[190:193], v[38:41]
	v_mfma_f32_16x16x32_bf16 v[30:33], v[158:161], v[190:193], v[30:33]
	v_mfma_f32_16x16x32_bf16 v[22:25], v[150:153], v[206:209], v[22:25]
	v_mfma_f32_16x16x32_bf16 v[14:17], v[158:161], v[206:209], v[14:17]
	v_mfma_f32_16x16x32_bf16 v[6:9], v[150:153], v[214:217], v[6:9]
	v_mfma_f32_16x16x32_bf16 v[2:5], v[158:161], v[214:217], v[2:5]
	s_barrier
	s_setprio 0
.Lkmid_4:
	ds_read_b128 v[130:133], v250 offset:32768
	ds_read_b128 v[134:137], v250 offset:33792
	ds_read_b128 v[138:141], v250 offset:34816
	ds_read_b128 v[142:145], v250 offset:35840
	ds_read_b128 v[146:149], v250 offset:49152
	ds_read_b128 v[150:153], v250 offset:50176
	ds_read_b128 v[154:157], v250 offset:51200
	ds_read_b128 v[158:161], v250 offset:52224
	ds_read_b128 v[162:165], v189 offset:32768
	ds_read_b128 v[180:183], v189 offset:33792
	ds_read_b128 v[184:187], v189 offset:34816
	ds_read_b128 v[190:193], v189 offset:35840
	ds_read_b128 v[202:205], v189 offset:36864
	ds_read_b128 v[206:209], v189 offset:37888
	ds_read_b128 v[210:213], v189 offset:38912
	ds_read_b128 v[214:217], v189 offset:39936
	s_add_i32 s78, 0, 0x18000
	s_add_i32 s79, 0, 0x1c000
	s_add_u32 s0, s64, 0x80000
	s_addc_u32 s1, s65, 0
	s_mov_b32 m0, s29
	s_nop 0
	global_load_lds_dwordx4 v166, s[0:1]
	s_mov_b32 m0, s30
	s_nop 0
	global_load_lds_dwordx4 v168, s[0:1]
	s_waitcnt vmcnt(8)
	s_waitcnt lgkmcnt(0)
	s_setprio 1
	s_barrier
	v_mfma_f32_16x16x32_bf16 v[126:129], v[130:133], v[162:165], v[126:129]
	v_mfma_f32_16x16x32_bf16 v[122:125], v[138:141], v[162:165], v[122:125]
	v_mfma_f32_16x16x32_bf16 v[110:113], v[130:133], v[184:187], v[110:113]
	v_mfma_f32_16x16x32_bf16 v[106:109], v[138:141], v[184:187], v[106:109]
	v_mfma_f32_16x16x32_bf16 v[98:101], v[130:133], v[202:205], v[98:101]
	v_mfma_f32_16x16x32_bf16 v[90:93], v[138:141], v[202:205], v[90:93]
	v_mfma_f32_16x16x32_bf16 v[82:85], v[130:133], v[210:213], v[82:85]
	v_mfma_f32_16x16x32_bf16 v[74:77], v[138:141], v[210:213], v[74:77]
	v_mfma_f32_16x16x32_bf16 v[126:129], v[134:137], v[180:183], v[126:129]
	v_mfma_f32_16x16x32_bf16 v[122:125], v[142:145], v[180:183], v[122:125]
	v_mfma_f32_16x16x32_bf16 v[110:113], v[134:137], v[190:193], v[110:113]
	v_mfma_f32_16x16x32_bf16 v[106:109], v[142:145], v[190:193], v[106:109]
	v_mfma_f32_16x16x32_bf16 v[98:101], v[134:137], v[206:209], v[98:101]
	v_mfma_f32_16x16x32_bf16 v[90:93], v[142:145], v[206:209], v[90:93]
	v_mfma_f32_16x16x32_bf16 v[82:85], v[134:137], v[214:217], v[82:85]
	v_mfma_f32_16x16x32_bf16 v[74:77], v[142:145], v[214:217], v[74:77]
	v_mfma_f32_16x16x32_bf16 v[118:121], v[146:149], v[162:165], v[118:121]
	v_mfma_f32_16x16x32_bf16 v[114:117], v[154:157], v[162:165], v[114:117]
	v_mfma_f32_16x16x32_bf16 v[102:105], v[146:149], v[184:187], v[102:105]
	v_mfma_f32_16x16x32_bf16 v[94:97], v[154:157], v[184:187], v[94:97]
	v_mfma_f32_16x16x32_bf16 v[86:89], v[146:149], v[202:205], v[86:89]
	v_mfma_f32_16x16x32_bf16 v[78:81], v[154:157], v[202:205], v[78:81]
	v_mfma_f32_16x16x32_bf16 v[70:73], v[146:149], v[210:213], v[70:73]
	v_mfma_f32_16x16x32_bf16 v[66:69], v[154:157], v[210:213], v[66:69]
	v_mfma_f32_16x16x32_bf16 v[118:121], v[150:153], v[180:183], v[118:121]
	v_mfma_f32_16x16x32_bf16 v[114:117], v[158:161], v[180:183], v[114:117]
	v_mfma_f32_16x16x32_bf16 v[102:105], v[150:153], v[190:193], v[102:105]
	v_mfma_f32_16x16x32_bf16 v[94:97], v[158:161], v[190:193], v[94:97]
	v_mfma_f32_16x16x32_bf16 v[86:89], v[150:153], v[206:209], v[86:89]
	v_mfma_f32_16x16x32_bf16 v[78:81], v[158:161], v[206:209], v[78:81]
	v_mfma_f32_16x16x32_bf16 v[70:73], v[150:153], v[214:217], v[70:73]
	v_mfma_f32_16x16x32_bf16 v[66:69], v[158:161], v[214:217], v[66:69]
	s_barrier
	s_setprio 0
	ds_read_b128 v[162:165], v189 offset:49152
	ds_read_b128 v[180:183], v189 offset:50176
	ds_read_b128 v[184:187], v189 offset:51200
	ds_read_b128 v[190:193], v189 offset:52224
	ds_read_b128 v[202:205], v189 offset:53248
	ds_read_b128 v[206:209], v189 offset:54272
	ds_read_b128 v[210:213], v189 offset:55296
	ds_read_b128 v[214:217], v189 offset:56320
	s_add_i32 s0, s78, s26
	s_mov_b32 m0, s0
	s_nop 0
	global_load_lds_dwordx4 v196, s[98:99]
	s_add_i32 m0, s0, 0x2000
	s_add_u32 s0, s8, 0x80080
	s_addc_u32 s1, s9, 0
	s_add_i32 s8, s79, s26
	global_load_lds_dwordx4 v170, s[98:99]
	s_mov_b32 m0, s8
	s_nop 0
	global_load_lds_dwordx4 v196, s[0:1]
	s_add_i32 m0, s8, 0x2000
	s_nop 0
	global_load_lds_dwordx4 v170, s[0:1]
	v_lshl_add_u64 v[194:195], v[220:221], 0, s[16:17]
	s_mov_b32 m0, s35
	s_nop 0
	global_load_lds_dwordx4 v[194:195], off
	v_lshl_add_u64 v[194:195], v[222:223], 0, s[16:17]
	s_mov_b32 m0, s53
	s_nop 0
	global_load_lds_dwordx4 v[194:195], off
	s_waitcnt vmcnt(8)
	s_waitcnt lgkmcnt(0)
	s_setprio 1
	s_barrier
	v_mfma_f32_16x16x32_bf16 v[62:65], v[130:133], v[162:165], v[62:65]
	v_mfma_f32_16x16x32_bf16 v[58:61], v[138:141], v[162:165], v[58:61]
	v_mfma_f32_16x16x32_bf16 v[50:53], v[130:133], v[184:187], v[50:53]
	v_mfma_f32_16x16x32_bf16 v[42:45], v[138:141], v[184:187], v[42:45]
	v_mfma_f32_16x16x32_bf16 v[34:37], v[130:133], v[202:205], v[34:37]
	v_mfma_f32_16x16x32_bf16 v[26:29], v[138:141], v[202:205], v[26:29]
	v_mfma_f32_16x16x32_bf16 v[18:21], v[130:133], v[210:213], v[18:21]
	v_mfma_f32_16x16x32_bf16 v[10:13], v[138:141], v[210:213], v[10:13]
	v_mfma_f32_16x16x32_bf16 v[62:65], v[134:137], v[180:183], v[62:65]
	v_mfma_f32_16x16x32_bf16 v[58:61], v[142:145], v[180:183], v[58:61]
	v_mfma_f32_16x16x32_bf16 v[50:53], v[134:137], v[190:193], v[50:53]
	v_mfma_f32_16x16x32_bf16 v[42:45], v[142:145], v[190:193], v[42:45]
	v_mfma_f32_16x16x32_bf16 v[34:37], v[134:137], v[206:209], v[34:37]
	v_mfma_f32_16x16x32_bf16 v[26:29], v[142:145], v[206:209], v[26:29]
	v_mfma_f32_16x16x32_bf16 v[18:21], v[134:137], v[214:217], v[18:21]
	v_mfma_f32_16x16x32_bf16 v[10:13], v[142:145], v[214:217], v[10:13]
	v_mfma_f32_16x16x32_bf16 v[54:57], v[146:149], v[162:165], v[54:57]
	v_mfma_f32_16x16x32_bf16 v[46:49], v[154:157], v[162:165], v[46:49]
	v_mfma_f32_16x16x32_bf16 v[38:41], v[146:149], v[184:187], v[38:41]
	v_mfma_f32_16x16x32_bf16 v[30:33], v[154:157], v[184:187], v[30:33]
	v_mfma_f32_16x16x32_bf16 v[22:25], v[146:149], v[202:205], v[22:25]
	v_mfma_f32_16x16x32_bf16 v[14:17], v[154:157], v[202:205], v[14:17]
	v_mfma_f32_16x16x32_bf16 v[6:9], v[146:149], v[210:213], v[6:9]
	v_mfma_f32_16x16x32_bf16 v[2:5], v[154:157], v[210:213], v[2:5]
	v_mfma_f32_16x16x32_bf16 v[54:57], v[150:153], v[180:183], v[54:57]
	v_mfma_f32_16x16x32_bf16 v[46:49], v[158:161], v[180:183], v[46:49]
	v_mfma_f32_16x16x32_bf16 v[38:41], v[150:153], v[190:193], v[38:41]
	v_mfma_f32_16x16x32_bf16 v[30:33], v[158:161], v[190:193], v[30:33]
	v_mfma_f32_16x16x32_bf16 v[22:25], v[150:153], v[206:209], v[22:25]
	v_mfma_f32_16x16x32_bf16 v[14:17], v[158:161], v[206:209], v[14:17]
	v_mfma_f32_16x16x32_bf16 v[6:9], v[150:153], v[214:217], v[6:9]
	v_mfma_f32_16x16x32_bf16 v[2:5], v[158:161], v[214:217], v[2:5]
	s_barrier
	s_setprio 0
	s_add_u32 s72, s72, 0x100
	s_addc_u32 s73, s73, 0
	s_add_u32 s62, s62, 0x100
	s_addc_u32 s63, s63, 0
	s_cmp_ge_i32 s77, s69
	s_mov_b32 s8, s77
	s_cbranch_scc0 .LBB0_2357
	s_and_b64 vcc, exec, s[38:39]
	s_cbranch_vccz .LBB0_2360
	s_barrier

.Ldefbar_skip_5:
	v_add_u32_e32 v250, 0x10000, v141
	ds_read_b128 v[144:147], v250
	ds_read_b128 v[148:151], v250 offset:1024
	ds_read_b128 v[152:155], v250 offset:2048
	ds_read_b128 v[156:159], v250 offset:3072
	ds_read_b128 v[160:163], v250 offset:16384
	ds_read_b128 v[164:167], v250 offset:17408
	ds_read_b128 v[168:171], v250 offset:18432
	ds_read_b128 v[172:175], v250 offset:19456
	ds_read_b128 v[176:179], v143
	ds_read_b128 v[180:183], v143 offset:1024
	ds_read_b128 v[184:187], v143 offset:2048
	ds_read_b128 v[188:191], v143 offset:3072
	ds_read_b128 v[192:195], v143 offset:4096
	ds_read_b128 v[202:205], v143 offset:5120
	ds_read_b128 v[206:209], v143 offset:6144
	ds_read_b128 v[210:213], v143 offset:7168
	s_add_i32 s69, s8, 2
	s_add_u32 s0, s52, 0xfff80080
	s_addc_u32 s1, s53, -1
	s_add_i32 s70, 0, 0x10000
	s_cmp_eq_u32 s66, s8
	s_cselect_b32 s59, s41, s1
	s_cselect_b32 s58, s45, s0
	s_cselect_b32 s9, s43, s68
	s_cselect_b32 s8, s65, s67
	s_add_i32 s71, 0, 0x14000
	s_add_i32 m0, s27, 0xc000
	s_nop 0
	global_load_lds_dwordx4 v138, s[52:53]
	s_add_i32 m0, s27, 0xe000
	s_nop 0
	global_load_lds_dwordx4 v136, s[52:53]
	s_waitcnt vmcnt(8)
	s_waitcnt lgkmcnt(0)
	s_setprio 1
	s_barrier
	v_mfma_f32_16x16x32_bf16 v[126:129], v[144:147], v[176:179], 0
	v_mfma_f32_16x16x32_bf16 v[118:121], v[152:155], v[176:179], 0
	v_mfma_f32_16x16x32_bf16 v[110:113], v[144:147], v[184:187], 0
	v_mfma_f32_16x16x32_bf16 v[102:105], v[152:155], v[184:187], 0
	v_mfma_f32_16x16x32_bf16 v[94:97], v[144:147], v[192:195], 0
	v_mfma_f32_16x16x32_bf16 v[86:89], v[152:155], v[192:195], 0
	v_mfma_f32_16x16x32_bf16 v[78:81], v[144:147], v[206:209], 0
	v_mfma_f32_16x16x32_bf16 v[70:73], v[152:155], v[206:209], 0
	v_mfma_f32_16x16x32_bf16 v[126:129], v[148:151], v[180:183], v[126:129]
	v_mfma_f32_16x16x32_bf16 v[118:121], v[156:159], v[180:183], v[118:121]
	v_mfma_f32_16x16x32_bf16 v[110:113], v[148:151], v[188:191], v[110:113]
	v_mfma_f32_16x16x32_bf16 v[102:105], v[156:159], v[188:191], v[102:105]
	v_mfma_f32_16x16x32_bf16 v[94:97], v[148:151], v[202:205], v[94:97]
	v_mfma_f32_16x16x32_bf16 v[86:89], v[156:159], v[202:205], v[86:89]
	v_mfma_f32_16x16x32_bf16 v[78:81], v[148:151], v[210:213], v[78:81]
	v_mfma_f32_16x16x32_bf16 v[70:73], v[156:159], v[210:213], v[70:73]
	v_mfma_f32_16x16x32_bf16 v[122:125], v[160:163], v[176:179], 0
	v_mfma_f32_16x16x32_bf16 v[114:117], v[168:171], v[176:179], 0
	v_mfma_f32_16x16x32_bf16 v[106:109], v[160:163], v[184:187], 0
	v_mfma_f32_16x16x32_bf16 v[98:101], v[168:171], v[184:187], 0
	v_mfma_f32_16x16x32_bf16 v[90:93], v[160:163], v[192:195], 0
	v_mfma_f32_16x16x32_bf16 v[82:85], v[168:171], v[192:195], 0
	v_mfma_f32_16x16x32_bf16 v[74:77], v[160:163], v[206:209], 0
	v_mfma_f32_16x16x32_bf16 v[66:69], v[168:171], v[206:209], 0
	v_mfma_f32_16x16x32_bf16 v[122:125], v[164:167], v[180:183], v[122:125]
	v_mfma_f32_16x16x32_bf16 v[114:117], v[172:175], v[180:183], v[114:117]
	v_mfma_f32_16x16x32_bf16 v[106:109], v[164:167], v[188:191], v[106:109]
	v_mfma_f32_16x16x32_bf16 v[98:101], v[172:175], v[188:191], v[98:101]
	v_mfma_f32_16x16x32_bf16 v[90:93], v[164:167], v[202:205], v[90:93]
	v_mfma_f32_16x16x32_bf16 v[82:85], v[172:175], v[202:205], v[82:85]
	v_mfma_f32_16x16x32_bf16 v[74:77], v[164:167], v[210:213], v[74:77]
	v_mfma_f32_16x16x32_bf16 v[66:69], v[172:175], v[210:213], v[66:69]
	s_barrier
	s_setprio 0
	ds_read_b128 v[176:179], v143 offset:16384
	ds_read_b128 v[180:183], v143 offset:17408
	ds_read_b128 v[184:187], v143 offset:18432
	ds_read_b128 v[188:191], v143 offset:19456
	ds_read_b128 v[192:195], v143 offset:20480
	ds_read_b128 v[202:205], v143 offset:21504
	ds_read_b128 v[206:209], v143 offset:22528
	ds_read_b128 v[210:213], v143 offset:23552
	s_add_i32 s0, s70, s26
	s_add_u32 s98, s8, s16
	s_addc_u32 s99, s9, s17
	s_mov_b32 m0, s0
	s_nop 0
	global_load_lds_dwordx4 v196, s[8:9]
	s_add_i32 m0, s0, 0x2000
	s_add_u32 s0, s8, 0x80000
	s_addc_u32 s1, s9, 0
	s_add_i32 s70, s71, s26
	global_load_lds_dwordx4 v130, s[8:9]
	s_mov_b32 m0, s70
	s_nop 0
	global_load_lds_dwordx4 v196, s[0:1]
	s_add_i32 m0, s70, 0x2000
	s_nop 0
	global_load_lds_dwordx4 v130, s[0:1]
	s_add_u32 s78, s58, s16
	s_addc_u32 s79, s59, s17
	s_mov_b32 m0, s27
	s_nop 0
	global_load_lds_dwordx4 v134, s[58:59]
	s_mov_b32 m0, s28
	s_nop 0
	global_load_lds_dwordx4 v132, s[58:59]
	s_waitcnt vmcnt(8)
	s_waitcnt lgkmcnt(0)
	s_setprio 1
	s_barrier
	v_mfma_f32_16x16x32_bf16 v[62:65], v[144:147], v[176:179], 0
	v_mfma_f32_16x16x32_bf16 v[54:57], v[152:155], v[176:179], 0
	v_mfma_f32_16x16x32_bf16 v[46:49], v[144:147], v[184:187], 0
	v_mfma_f32_16x16x32_bf16 v[38:41], v[152:155], v[184:187], 0
	v_mfma_f32_16x16x32_bf16 v[30:33], v[144:147], v[192:195], 0
	v_mfma_f32_16x16x32_bf16 v[22:25], v[152:155], v[192:195], 0
	v_mfma_f32_16x16x32_bf16 v[14:17], v[144:147], v[206:209], 0
	v_mfma_f32_16x16x32_bf16 v[6:9], v[152:155], v[206:209], 0
	v_mfma_f32_16x16x32_bf16 v[62:65], v[148:151], v[180:183], v[62:65]
	v_mfma_f32_16x16x32_bf16 v[54:57], v[156:159], v[180:183], v[54:57]
	v_mfma_f32_16x16x32_bf16 v[46:49], v[148:151], v[188:191], v[46:49]
	v_mfma_f32_16x16x32_bf16 v[38:41], v[156:159], v[188:191], v[38:41]
	v_mfma_f32_16x16x32_bf16 v[30:33], v[148:151], v[202:205], v[30:33]
	v_mfma_f32_16x16x32_bf16 v[22:25], v[156:159], v[202:205], v[22:25]
	v_mfma_f32_16x16x32_bf16 v[14:17], v[148:151], v[210:213], v[14:17]
	v_mfma_f32_16x16x32_bf16 v[6:9], v[156:159], v[210:213], v[6:9]
	v_mfma_f32_16x16x32_bf16 v[58:61], v[160:163], v[176:179], 0
	v_mfma_f32_16x16x32_bf16 v[50:53], v[168:171], v[176:179], 0
	v_mfma_f32_16x16x32_bf16 v[42:45], v[160:163], v[184:187], 0
	v_mfma_f32_16x16x32_bf16 v[34:37], v[168:171], v[184:187], 0
	v_mfma_f32_16x16x32_bf16 v[26:29], v[160:163], v[192:195], 0
	v_mfma_f32_16x16x32_bf16 v[18:21], v[168:171], v[192:195], 0
	v_mfma_f32_16x16x32_bf16 v[10:13], v[160:163], v[206:209], 0
	v_mfma_f32_16x16x32_bf16 v[2:5], v[168:171], v[206:209], 0
	v_mfma_f32_16x16x32_bf16 v[58:61], v[164:167], v[180:183], v[58:61]
	v_mfma_f32_16x16x32_bf16 v[50:53], v[172:175], v[180:183], v[50:53]
	v_mfma_f32_16x16x32_bf16 v[42:45], v[164:167], v[188:191], v[42:45]
	v_mfma_f32_16x16x32_bf16 v[34:37], v[172:175], v[188:191], v[34:37]
	v_mfma_f32_16x16x32_bf16 v[26:29], v[164:167], v[202:205], v[26:29]
	v_mfma_f32_16x16x32_bf16 v[18:21], v[172:175], v[202:205], v[18:21]
	v_mfma_f32_16x16x32_bf16 v[10:13], v[164:167], v[210:213], v[10:13]
	v_mfma_f32_16x16x32_bf16 v[2:5], v[172:175], v[210:213], v[2:5]
	s_barrier
	s_setprio 0
	s_branch .Lkmid_5
.LBB0_2507:
	ds_read_b128 v[144:147], v250
	ds_read_b128 v[148:151], v250 offset:1024
	ds_read_b128 v[152:155], v250 offset:2048
	ds_read_b128 v[156:159], v250 offset:3072
	ds_read_b128 v[160:163], v250 offset:16384
	ds_read_b128 v[164:167], v250 offset:17408
	ds_read_b128 v[168:171], v250 offset:18432
	ds_read_b128 v[172:175], v250 offset:19456
	ds_read_b128 v[176:179], v143
	ds_read_b128 v[180:183], v143 offset:1024
	ds_read_b128 v[184:187], v143 offset:2048
	ds_read_b128 v[188:191], v143 offset:3072
	ds_read_b128 v[192:195], v143 offset:4096
	ds_read_b128 v[202:205], v143 offset:5120
	ds_read_b128 v[206:209], v143 offset:6144
	ds_read_b128 v[210:213], v143 offset:7168
	s_add_i32 s69, s8, 2
	s_add_u32 s0, s52, 0xfff80080
	s_addc_u32 s1, s53, -1
	s_add_i32 s70, 0, 0x10000
	s_cmp_eq_u32 s66, s8
	s_cselect_b32 s59, s41, s1
	s_cselect_b32 s58, s45, s0
	s_cselect_b32 s9, s43, s68
	s_cselect_b32 s8, s65, s67
	s_add_i32 s71, 0, 0x14000
	s_add_i32 m0, s27, 0xc000
	s_nop 0
	global_load_lds_dwordx4 v138, s[52:53]
	s_add_i32 m0, s27, 0xe000
	s_nop 0
	global_load_lds_dwordx4 v136, s[52:53]
	s_waitcnt vmcnt(8)
	s_waitcnt lgkmcnt(0)
	s_setprio 1
	s_barrier
	v_mfma_f32_16x16x32_bf16 v[126:129], v[144:147], v[176:179], v[126:129]
	v_mfma_f32_16x16x32_bf16 v[118:121], v[152:155], v[176:179], v[118:121]
	v_mfma_f32_16x16x32_bf16 v[110:113], v[144:147], v[184:187], v[110:113]
	v_mfma_f32_16x16x32_bf16 v[102:105], v[152:155], v[184:187], v[102:105]
	v_mfma_f32_16x16x32_bf16 v[94:97], v[144:147], v[192:195], v[94:97]
	v_mfma_f32_16x16x32_bf16 v[86:89], v[152:155], v[192:195], v[86:89]
	v_mfma_f32_16x16x32_bf16 v[78:81], v[144:147], v[206:209], v[78:81]
	v_mfma_f32_16x16x32_bf16 v[70:73], v[152:155], v[206:209], v[70:73]
	v_mfma_f32_16x16x32_bf16 v[126:129], v[148:151], v[180:183], v[126:129]
	v_mfma_f32_16x16x32_bf16 v[118:121], v[156:159], v[180:183], v[118:121]
	v_mfma_f32_16x16x32_bf16 v[110:113], v[148:151], v[188:191], v[110:113]
	v_mfma_f32_16x16x32_bf16 v[102:105], v[156:159], v[188:191], v[102:105]
	v_mfma_f32_16x16x32_bf16 v[94:97], v[148:151], v[202:205], v[94:97]
	v_mfma_f32_16x16x32_bf16 v[86:89], v[156:159], v[202:205], v[86:89]
	v_mfma_f32_16x16x32_bf16 v[78:81], v[148:151], v[210:213], v[78:81]
	v_mfma_f32_16x16x32_bf16 v[70:73], v[156:159], v[210:213], v[70:73]
	v_mfma_f32_16x16x32_bf16 v[122:125], v[160:163], v[176:179], v[122:125]
	v_mfma_f32_16x16x32_bf16 v[114:117], v[168:171], v[176:179], v[114:117]
	v_mfma_f32_16x16x32_bf16 v[106:109], v[160:163], v[184:187], v[106:109]
	v_mfma_f32_16x16x32_bf16 v[98:101], v[168:171], v[184:187], v[98:101]
	v_mfma_f32_16x16x32_bf16 v[90:93], v[160:163], v[192:195], v[90:93]
	v_mfma_f32_16x16x32_bf16 v[82:85], v[168:171], v[192:195], v[82:85]
	v_mfma_f32_16x16x32_bf16 v[74:77], v[160:163], v[206:209], v[74:77]
	v_mfma_f32_16x16x32_bf16 v[66:69], v[168:171], v[206:209], v[66:69]
	v_mfma_f32_16x16x32_bf16 v[122:125], v[164:167], v[180:183], v[122:125]
	v_mfma_f32_16x16x32_bf16 v[114:117], v[172:175], v[180:183], v[114:117]
	v_mfma_f32_16x16x32_bf16 v[106:109], v[164:167], v[188:191], v[106:109]
	v_mfma_f32_16x16x32_bf16 v[98:101], v[172:175], v[188:191], v[98:101]
	v_mfma_f32_16x16x32_bf16 v[90:93], v[164:167], v[202:205], v[90:93]
	v_mfma_f32_16x16x32_bf16 v[82:85], v[172:175], v[202:205], v[82:85]
	v_mfma_f32_16x16x32_bf16 v[74:77], v[164:167], v[210:213], v[74:77]
	v_mfma_f32_16x16x32_bf16 v[66:69], v[172:175], v[210:213], v[66:69]
	s_barrier
	s_setprio 0
	ds_read_b128 v[176:179], v143 offset:16384
	ds_read_b128 v[180:183], v143 offset:17408
	ds_read_b128 v[184:187], v143 offset:18432
	ds_read_b128 v[188:191], v143 offset:19456
	ds_read_b128 v[192:195], v143 offset:20480
	ds_read_b128 v[202:205], v143 offset:21504
	ds_read_b128 v[206:209], v143 offset:22528
	ds_read_b128 v[210:213], v143 offset:23552
	s_add_i32 s0, s70, s26
	s_add_u32 s98, s8, s16
	s_addc_u32 s99, s9, s17
	s_mov_b32 m0, s0
	s_nop 0
	global_load_lds_dwordx4 v196, s[8:9]
	s_add_i32 m0, s0, 0x2000
	s_add_u32 s0, s8, 0x80000
	s_addc_u32 s1, s9, 0
	s_add_i32 s70, s71, s26
	global_load_lds_dwordx4 v130, s[8:9]
	s_mov_b32 m0, s70
	s_nop 0
	global_load_lds_dwordx4 v196, s[0:1]
	s_add_i32 m0, s70, 0x2000
	s_nop 0
	global_load_lds_dwordx4 v130, s[0:1]
	s_add_u32 s78, s58, s16
	s_addc_u32 s79, s59, s17
	s_mov_b32 m0, s27
	s_nop 0
	global_load_lds_dwordx4 v134, s[58:59]
	s_mov_b32 m0, s28
	s_nop 0
	global_load_lds_dwordx4 v132, s[58:59]
	s_waitcnt vmcnt(8)
	s_waitcnt lgkmcnt(0)
	s_setprio 1
	s_barrier
	v_mfma_f32_16x16x32_bf16 v[62:65], v[144:147], v[176:179], v[62:65]
	v_mfma_f32_16x16x32_bf16 v[54:57], v[152:155], v[176:179], v[54:57]
	v_mfma_f32_16x16x32_bf16 v[46:49], v[144:147], v[184:187], v[46:49]
	v_mfma_f32_16x16x32_bf16 v[38:41], v[152:155], v[184:187], v[38:41]
	v_mfma_f32_16x16x32_bf16 v[30:33], v[144:147], v[192:195], v[30:33]
	v_mfma_f32_16x16x32_bf16 v[22:25], v[152:155], v[192:195], v[22:25]
	v_mfma_f32_16x16x32_bf16 v[14:17], v[144:147], v[206:209], v[14:17]
	v_mfma_f32_16x16x32_bf16 v[6:9], v[152:155], v[206:209], v[6:9]
	v_mfma_f32_16x16x32_bf16 v[62:65], v[148:151], v[180:183], v[62:65]
	v_mfma_f32_16x16x32_bf16 v[54:57], v[156:159], v[180:183], v[54:57]
	v_mfma_f32_16x16x32_bf16 v[46:49], v[148:151], v[188:191], v[46:49]
	v_mfma_f32_16x16x32_bf16 v[38:41], v[156:159], v[188:191], v[38:41]
	v_mfma_f32_16x16x32_bf16 v[30:33], v[148:151], v[202:205], v[30:33]
	v_mfma_f32_16x16x32_bf16 v[22:25], v[156:159], v[202:205], v[22:25]
	v_mfma_f32_16x16x32_bf16 v[14:17], v[148:151], v[210:213], v[14:17]
	v_mfma_f32_16x16x32_bf16 v[6:9], v[156:159], v[210:213], v[6:9]
	v_mfma_f32_16x16x32_bf16 v[58:61], v[160:163], v[176:179], v[58:61]
	v_mfma_f32_16x16x32_bf16 v[50:53], v[168:171], v[176:179], v[50:53]
	v_mfma_f32_16x16x32_bf16 v[42:45], v[160:163], v[184:187], v[42:45]
	v_mfma_f32_16x16x32_bf16 v[34:37], v[168:171], v[184:187], v[34:37]
	v_mfma_f32_16x16x32_bf16 v[26:29], v[160:163], v[192:195], v[26:29]
	v_mfma_f32_16x16x32_bf16 v[18:21], v[168:171], v[192:195], v[18:21]
	v_mfma_f32_16x16x32_bf16 v[10:13], v[160:163], v[206:209], v[10:13]
	v_mfma_f32_16x16x32_bf16 v[2:5], v[168:171], v[206:209], v[2:5]
	v_mfma_f32_16x16x32_bf16 v[58:61], v[164:167], v[180:183], v[58:61]
	v_mfma_f32_16x16x32_bf16 v[50:53], v[172:175], v[180:183], v[50:53]
	v_mfma_f32_16x16x32_bf16 v[42:45], v[164:167], v[188:191], v[42:45]
	v_mfma_f32_16x16x32_bf16 v[34:37], v[172:175], v[188:191], v[34:37]
	v_mfma_f32_16x16x32_bf16 v[26:29], v[164:167], v[202:205], v[26:29]
	v_mfma_f32_16x16x32_bf16 v[18:21], v[172:175], v[202:205], v[18:21]
	v_mfma_f32_16x16x32_bf16 v[10:13], v[164:167], v[210:213], v[10:13]
	v_mfma_f32_16x16x32_bf16 v[2:5], v[172:175], v[210:213], v[2:5]
	s_barrier
	s_setprio 0
.Lkmid_5:
	ds_read_b128 v[144:147], v250 offset:32768
	ds_read_b128 v[148:151], v250 offset:33792
	ds_read_b128 v[152:155], v250 offset:34816
	ds_read_b128 v[156:159], v250 offset:35840
	ds_read_b128 v[160:163], v250 offset:49152
	ds_read_b128 v[164:167], v250 offset:50176
	ds_read_b128 v[168:171], v250 offset:51200
	ds_read_b128 v[172:175], v250 offset:52224
	ds_read_b128 v[176:179], v143 offset:32768
	ds_read_b128 v[180:183], v143 offset:33792
	ds_read_b128 v[184:187], v143 offset:34816
	ds_read_b128 v[188:191], v143 offset:35840
	ds_read_b128 v[192:195], v143 offset:36864
	ds_read_b128 v[202:205], v143 offset:37888
	ds_read_b128 v[206:209], v143 offset:38912
	ds_read_b128 v[210:213], v143 offset:39936
	s_add_i32 s70, 0, 0x18000
	s_add_i32 s71, 0, 0x1c000
	s_add_u32 s0, s58, 0x80000
	s_addc_u32 s1, s59, 0
	s_mov_b32 m0, s29
	s_nop 0
	global_load_lds_dwordx4 v134, s[0:1]
	s_mov_b32 m0, s30
	s_nop 0
	global_load_lds_dwordx4 v132, s[0:1]
	s_waitcnt vmcnt(8)
	s_waitcnt lgkmcnt(0)
	s_setprio 1
	s_barrier
	v_mfma_f32_16x16x32_bf16 v[126:129], v[144:147], v[176:179], v[126:129]
	v_mfma_f32_16x16x32_bf16 v[118:121], v[152:155], v[176:179], v[118:121]
	v_mfma_f32_16x16x32_bf16 v[110:113], v[144:147], v[184:187], v[110:113]
	v_mfma_f32_16x16x32_bf16 v[102:105], v[152:155], v[184:187], v[102:105]
	v_mfma_f32_16x16x32_bf16 v[94:97], v[144:147], v[192:195], v[94:97]
	v_mfma_f32_16x16x32_bf16 v[86:89], v[152:155], v[192:195], v[86:89]
	v_mfma_f32_16x16x32_bf16 v[78:81], v[144:147], v[206:209], v[78:81]
	v_mfma_f32_16x16x32_bf16 v[70:73], v[152:155], v[206:209], v[70:73]
	v_mfma_f32_16x16x32_bf16 v[126:129], v[148:151], v[180:183], v[126:129]
	v_mfma_f32_16x16x32_bf16 v[118:121], v[156:159], v[180:183], v[118:121]
	v_mfma_f32_16x16x32_bf16 v[110:113], v[148:151], v[188:191], v[110:113]
	v_mfma_f32_16x16x32_bf16 v[102:105], v[156:159], v[188:191], v[102:105]
	v_mfma_f32_16x16x32_bf16 v[94:97], v[148:151], v[202:205], v[94:97]
	v_mfma_f32_16x16x32_bf16 v[86:89], v[156:159], v[202:205], v[86:89]
	v_mfma_f32_16x16x32_bf16 v[78:81], v[148:151], v[210:213], v[78:81]
	v_mfma_f32_16x16x32_bf16 v[70:73], v[156:159], v[210:213], v[70:73]
	v_mfma_f32_16x16x32_bf16 v[122:125], v[160:163], v[176:179], v[122:125]
	v_mfma_f32_16x16x32_bf16 v[114:117], v[168:171], v[176:179], v[114:117]
	v_mfma_f32_16x16x32_bf16 v[106:109], v[160:163], v[184:187], v[106:109]
	v_mfma_f32_16x16x32_bf16 v[98:101], v[168:171], v[184:187], v[98:101]
	v_mfma_f32_16x16x32_bf16 v[90:93], v[160:163], v[192:195], v[90:93]
	v_mfma_f32_16x16x32_bf16 v[82:85], v[168:171], v[192:195], v[82:85]
	v_mfma_f32_16x16x32_bf16 v[74:77], v[160:163], v[206:209], v[74:77]
	v_mfma_f32_16x16x32_bf16 v[66:69], v[168:171], v[206:209], v[66:69]
	v_mfma_f32_16x16x32_bf16 v[122:125], v[164:167], v[180:183], v[122:125]
	v_mfma_f32_16x16x32_bf16 v[114:117], v[172:175], v[180:183], v[114:117]
	v_mfma_f32_16x16x32_bf16 v[106:109], v[164:167], v[188:191], v[106:109]
	v_mfma_f32_16x16x32_bf16 v[98:101], v[172:175], v[188:191], v[98:101]
	v_mfma_f32_16x16x32_bf16 v[90:93], v[164:167], v[202:205], v[90:93]
	v_mfma_f32_16x16x32_bf16 v[82:85], v[172:175], v[202:205], v[82:85]
	v_mfma_f32_16x16x32_bf16 v[74:77], v[164:167], v[210:213], v[74:77]
	v_mfma_f32_16x16x32_bf16 v[66:69], v[172:175], v[210:213], v[66:69]
	s_barrier
	s_setprio 0
	ds_read_b128 v[176:179], v143 offset:49152
	ds_read_b128 v[180:183], v143 offset:50176
	ds_read_b128 v[184:187], v143 offset:51200
	ds_read_b128 v[188:191], v143 offset:52224
	ds_read_b128 v[192:195], v143 offset:53248
	ds_read_b128 v[202:205], v143 offset:54272
	ds_read_b128 v[206:209], v143 offset:55296
	ds_read_b128 v[210:213], v143 offset:56320
	s_add_i32 s0, s70, s26
	s_mov_b32 m0, s0
	s_nop 0
	global_load_lds_dwordx4 v196, s[98:99]
	s_add_i32 m0, s0, 0x2000
	s_add_u32 s0, s8, 0x80080
	s_addc_u32 s1, s9, 0
	s_add_i32 s8, s71, s26
	global_load_lds_dwordx4 v130, s[98:99]
	s_mov_b32 m0, s8
	s_nop 0
	global_load_lds_dwordx4 v196, s[0:1]
	s_add_i32 m0, s8, 0x2000
	s_nop 0
	global_load_lds_dwordx4 v130, s[0:1]
	s_mov_b32 m0, s31
	s_nop 0
	global_load_lds_dwordx4 v134, s[78:79]
	s_mov_b32 m0, s34
	s_nop 0
	global_load_lds_dwordx4 v132, s[78:79]
	s_waitcnt vmcnt(8)
	s_waitcnt lgkmcnt(0)
	s_setprio 1
	s_barrier
	v_mfma_f32_16x16x32_bf16 v[62:65], v[144:147], v[176:179], v[62:65]
	v_mfma_f32_16x16x32_bf16 v[54:57], v[152:155], v[176:179], v[54:57]
	v_mfma_f32_16x16x32_bf16 v[46:49], v[144:147], v[184:187], v[46:49]
	v_mfma_f32_16x16x32_bf16 v[38:41], v[152:155], v[184:187], v[38:41]
	v_mfma_f32_16x16x32_bf16 v[30:33], v[144:147], v[192:195], v[30:33]
	v_mfma_f32_16x16x32_bf16 v[22:25], v[152:155], v[192:195], v[22:25]
	v_mfma_f32_16x16x32_bf16 v[14:17], v[144:147], v[206:209], v[14:17]
	v_mfma_f32_16x16x32_bf16 v[6:9], v[152:155], v[206:209], v[6:9]
	v_mfma_f32_16x16x32_bf16 v[62:65], v[148:151], v[180:183], v[62:65]
	v_mfma_f32_16x16x32_bf16 v[54:57], v[156:159], v[180:183], v[54:57]
	v_mfma_f32_16x16x32_bf16 v[46:49], v[148:151], v[188:191], v[46:49]
	v_mfma_f32_16x16x32_bf16 v[38:41], v[156:159], v[188:191], v[38:41]
	v_mfma_f32_16x16x32_bf16 v[30:33], v[148:151], v[202:205], v[30:33]
	v_mfma_f32_16x16x32_bf16 v[22:25], v[156:159], v[202:205], v[22:25]
	v_mfma_f32_16x16x32_bf16 v[14:17], v[148:151], v[210:213], v[14:17]
	v_mfma_f32_16x16x32_bf16 v[6:9], v[156:159], v[210:213], v[6:9]
	v_mfma_f32_16x16x32_bf16 v[58:61], v[160:163], v[176:179], v[58:61]
	v_mfma_f32_16x16x32_bf16 v[50:53], v[168:171], v[176:179], v[50:53]
	v_mfma_f32_16x16x32_bf16 v[42:45], v[160:163], v[184:187], v[42:45]
	v_mfma_f32_16x16x32_bf16 v[34:37], v[168:171], v[184:187], v[34:37]
	v_mfma_f32_16x16x32_bf16 v[26:29], v[160:163], v[192:195], v[26:29]
	v_mfma_f32_16x16x32_bf16 v[18:21], v[168:171], v[192:195], v[18:21]
	v_mfma_f32_16x16x32_bf16 v[10:13], v[160:163], v[206:209], v[10:13]
	v_mfma_f32_16x16x32_bf16 v[2:5], v[168:171], v[206:209], v[2:5]
	v_mfma_f32_16x16x32_bf16 v[58:61], v[164:167], v[180:183], v[58:61]
	v_mfma_f32_16x16x32_bf16 v[50:53], v[172:175], v[180:183], v[50:53]
	v_mfma_f32_16x16x32_bf16 v[42:45], v[164:167], v[188:191], v[42:45]
	v_mfma_f32_16x16x32_bf16 v[34:37], v[172:175], v[188:191], v[34:37]
	v_mfma_f32_16x16x32_bf16 v[26:29], v[164:167], v[202:205], v[26:29]
	v_mfma_f32_16x16x32_bf16 v[18:21], v[172:175], v[202:205], v[18:21]
	v_mfma_f32_16x16x32_bf16 v[10:13], v[164:167], v[210:213], v[10:13]
	v_mfma_f32_16x16x32_bf16 v[2:5], v[172:175], v[210:213], v[2:5]
	s_barrier
	s_setprio 0
	s_add_u32 s67, s67, 0x100
	s_addc_u32 s68, s68, 0
	s_add_u32 s52, s52, 0x100
	s_addc_u32 s53, s53, 0
	s_cmp_ge_i32 s69, s62
	s_mov_b32 s8, s69
	s_cbranch_scc0 .LBB0_2507
	s_and_b64 vcc, exec, s[38:39]
	s_cbranch_vccz .LBB0_2510
	s_barrier

.Ldefbar_skip_6:
	v_add_u32_e32 v250, 0x10000, v188
	ds_read_b128 v[130:133], v250
	ds_read_b128 v[134:137], v250 offset:1024
	ds_read_b128 v[138:141], v250 offset:2048
	ds_read_b128 v[142:145], v250 offset:3072
	ds_read_b128 v[146:149], v250 offset:16384
	ds_read_b128 v[164:167], v250 offset:17408
	ds_read_b128 v[168:171], v250 offset:18432
	ds_read_b128 v[172:175], v250 offset:19456
	ds_read_b128 v[176:179], v189
	ds_read_b128 v[180:183], v189 offset:1024
	ds_read_b128 v[184:187], v189 offset:2048
	ds_read_b128 v[190:193], v189 offset:3072
	ds_read_b128 v[202:205], v189 offset:4096
	ds_read_b128 v[206:209], v189 offset:5120
	ds_read_b128 v[210:213], v189 offset:6144
	ds_read_b128 v[214:217], v189 offset:7168
	s_add_i32 s72, s48, 2
	s_add_u32 s8, s46, 0x100
	s_addc_u32 s9, s47, 0
	s_add_i32 s0, 0, 0x10000
	s_cmp_eq_u32 s41, s48
	s_cselect_b32 s51, s43, s9
	s_cselect_b32 s50, s42, s8
	s_cselect_b32 s49, s45, s71
	s_cselect_b32 s48, s44, s70
	s_add_i32 s73, 0, 0x14000
	v_lshl_add_u64 v[194:195], s[46:47], 0, v[162:163]
	s_add_i32 m0, s27, 0xc000
	s_nop 0
	global_load_lds_dwordx4 v[194:195], off
	v_lshl_add_u64 v[194:195], s[46:47], 0, v[160:161]
	s_add_i32 m0, s27, 0xe000
	s_nop 0
	global_load_lds_dwordx4 v[194:195], off
	s_waitcnt vmcnt(8)
	s_waitcnt lgkmcnt(0)
	s_setprio 1
	s_barrier
	v_mfma_f32_16x16x32_bf16 v[126:129], v[130:133], v[176:179], 0
	v_mfma_f32_16x16x32_bf16 v[122:125], v[138:141], v[176:179], 0
	v_mfma_f32_16x16x32_bf16 v[110:113], v[130:133], v[184:187], 0
	v_mfma_f32_16x16x32_bf16 v[106:109], v[138:141], v[184:187], 0
	v_mfma_f32_16x16x32_bf16 v[98:101], v[130:133], v[202:205], 0
	v_mfma_f32_16x16x32_bf16 v[90:93], v[138:141], v[202:205], 0
	v_mfma_f32_16x16x32_bf16 v[82:85], v[130:133], v[210:213], 0
	v_mfma_f32_16x16x32_bf16 v[74:77], v[138:141], v[210:213], 0
	v_mfma_f32_16x16x32_bf16 v[126:129], v[134:137], v[180:183], v[126:129]
	v_mfma_f32_16x16x32_bf16 v[122:125], v[142:145], v[180:183], v[122:125]
	v_mfma_f32_16x16x32_bf16 v[110:113], v[134:137], v[190:193], v[110:113]
	v_mfma_f32_16x16x32_bf16 v[106:109], v[142:145], v[190:193], v[106:109]
	v_mfma_f32_16x16x32_bf16 v[98:101], v[134:137], v[206:209], v[98:101]
	v_mfma_f32_16x16x32_bf16 v[90:93], v[142:145], v[206:209], v[90:93]
	v_mfma_f32_16x16x32_bf16 v[82:85], v[134:137], v[214:217], v[82:85]
	v_mfma_f32_16x16x32_bf16 v[74:77], v[142:145], v[214:217], v[74:77]
	v_mfma_f32_16x16x32_bf16 v[118:121], v[146:149], v[176:179], 0
	v_mfma_f32_16x16x32_bf16 v[114:117], v[168:171], v[176:179], 0
	v_mfma_f32_16x16x32_bf16 v[102:105], v[146:149], v[184:187], 0
	v_mfma_f32_16x16x32_bf16 v[94:97], v[168:171], v[184:187], 0
	v_mfma_f32_16x16x32_bf16 v[86:89], v[146:149], v[202:205], 0
	v_mfma_f32_16x16x32_bf16 v[78:81], v[168:171], v[202:205], 0
	v_mfma_f32_16x16x32_bf16 v[70:73], v[146:149], v[210:213], 0
	v_mfma_f32_16x16x32_bf16 v[66:69], v[168:171], v[210:213], 0
	v_mfma_f32_16x16x32_bf16 v[118:121], v[164:167], v[180:183], v[118:121]
	v_mfma_f32_16x16x32_bf16 v[114:117], v[172:175], v[180:183], v[114:117]
	v_mfma_f32_16x16x32_bf16 v[102:105], v[164:167], v[190:193], v[102:105]
	v_mfma_f32_16x16x32_bf16 v[94:97], v[172:175], v[190:193], v[94:97]
	v_mfma_f32_16x16x32_bf16 v[86:89], v[164:167], v[206:209], v[86:89]
	v_mfma_f32_16x16x32_bf16 v[78:81], v[172:175], v[206:209], v[78:81]
	v_mfma_f32_16x16x32_bf16 v[70:73], v[164:167], v[214:217], v[70:73]
	v_mfma_f32_16x16x32_bf16 v[66:69], v[172:175], v[214:217], v[66:69]
	s_barrier
	s_setprio 0
	ds_read_b128 v[176:179], v189 offset:16384
	ds_read_b128 v[180:183], v189 offset:17408
	ds_read_b128 v[184:187], v189 offset:18432
	ds_read_b128 v[190:193], v189 offset:19456
	ds_read_b128 v[202:205], v189 offset:20480
	ds_read_b128 v[206:209], v189 offset:21504
	ds_read_b128 v[210:213], v189 offset:22528
	ds_read_b128 v[214:217], v189 offset:23552
	s_add_i32 s0, s0, s26
	s_add_u32 s98, s48, s16
	s_addc_u32 s99, s49, s17
	s_mov_b32 m0, s0
	s_nop 0
	global_load_lds_dwordx4 v196, s[48:49]
	s_add_i32 m0, s0, 0x2000
	s_add_u32 s0, s48, 0x158000
	s_addc_u32 s1, s49, 0
	s_add_i32 s46, s73, s26
	global_load_lds_dwordx4 v154, s[48:49]
	s_mov_b32 m0, s46
	s_nop 0
	global_load_lds_dwordx4 v196, s[0:1]
	s_add_i32 m0, s46, 0x2000
	s_nop 0
	global_load_lds_dwordx4 v154, s[0:1]
	s_add_u32 s78, s50, s16
	s_addc_u32 s79, s51, s17
	s_mov_b32 m0, s27
	s_nop 0
	global_load_lds_dwordx4 v150, s[50:51]
	s_mov_b32 m0, s30
	s_nop 0
	global_load_lds_dwordx4 v152, s[50:51]
	s_waitcnt vmcnt(8)
	s_waitcnt lgkmcnt(0)
	s_setprio 1
	s_barrier
	v_mfma_f32_16x16x32_bf16 v[62:65], v[130:133], v[176:179], 0
	v_mfma_f32_16x16x32_bf16 v[58:61], v[138:141], v[176:179], 0
	v_mfma_f32_16x16x32_bf16 v[50:53], v[130:133], v[184:187], 0
	v_mfma_f32_16x16x32_bf16 v[42:45], v[138:141], v[184:187], 0
	v_mfma_f32_16x16x32_bf16 v[34:37], v[130:133], v[202:205], 0
	v_mfma_f32_16x16x32_bf16 v[26:29], v[138:141], v[202:205], 0
	v_mfma_f32_16x16x32_bf16 v[18:21], v[130:133], v[210:213], 0
	v_mfma_f32_16x16x32_bf16 v[10:13], v[138:141], v[210:213], 0
	v_mfma_f32_16x16x32_bf16 v[62:65], v[134:137], v[180:183], v[62:65]
	v_mfma_f32_16x16x32_bf16 v[58:61], v[142:145], v[180:183], v[58:61]
	v_mfma_f32_16x16x32_bf16 v[50:53], v[134:137], v[190:193], v[50:53]
	v_mfma_f32_16x16x32_bf16 v[42:45], v[142:145], v[190:193], v[42:45]
	v_mfma_f32_16x16x32_bf16 v[34:37], v[134:137], v[206:209], v[34:37]
	v_mfma_f32_16x16x32_bf16 v[26:29], v[142:145], v[206:209], v[26:29]
	v_mfma_f32_16x16x32_bf16 v[18:21], v[134:137], v[214:217], v[18:21]
	v_mfma_f32_16x16x32_bf16 v[10:13], v[142:145], v[214:217], v[10:13]
	v_mfma_f32_16x16x32_bf16 v[54:57], v[146:149], v[176:179], 0
	v_mfma_f32_16x16x32_bf16 v[46:49], v[168:171], v[176:179], 0
	v_mfma_f32_16x16x32_bf16 v[38:41], v[146:149], v[184:187], 0
	v_mfma_f32_16x16x32_bf16 v[30:33], v[168:171], v[184:187], 0
	v_mfma_f32_16x16x32_bf16 v[22:25], v[146:149], v[202:205], 0
	v_mfma_f32_16x16x32_bf16 v[14:17], v[168:171], v[202:205], 0
	v_mfma_f32_16x16x32_bf16 v[6:9], v[146:149], v[210:213], 0
	v_mfma_f32_16x16x32_bf16 v[2:5], v[168:171], v[210:213], 0
	v_mfma_f32_16x16x32_bf16 v[54:57], v[164:167], v[180:183], v[54:57]
	v_mfma_f32_16x16x32_bf16 v[46:49], v[172:175], v[180:183], v[46:49]
	v_mfma_f32_16x16x32_bf16 v[38:41], v[164:167], v[190:193], v[38:41]
	v_mfma_f32_16x16x32_bf16 v[30:33], v[172:175], v[190:193], v[30:33]
	v_mfma_f32_16x16x32_bf16 v[22:25], v[164:167], v[206:209], v[22:25]
	v_mfma_f32_16x16x32_bf16 v[14:17], v[172:175], v[206:209], v[14:17]
	v_mfma_f32_16x16x32_bf16 v[6:9], v[164:167], v[214:217], v[6:9]
	v_mfma_f32_16x16x32_bf16 v[2:5], v[172:175], v[214:217], v[2:5]
	s_barrier
	s_setprio 0
	s_branch .Lkmid_6
.LBB0_2588:
	ds_read_b128 v[130:133], v250
	ds_read_b128 v[134:137], v250 offset:1024
	ds_read_b128 v[138:141], v250 offset:2048
	ds_read_b128 v[142:145], v250 offset:3072
	ds_read_b128 v[146:149], v250 offset:16384
	ds_read_b128 v[164:167], v250 offset:17408
	ds_read_b128 v[168:171], v250 offset:18432
	ds_read_b128 v[172:175], v250 offset:19456
	ds_read_b128 v[176:179], v189
	ds_read_b128 v[180:183], v189 offset:1024
	ds_read_b128 v[184:187], v189 offset:2048
	ds_read_b128 v[190:193], v189 offset:3072
	ds_read_b128 v[202:205], v189 offset:4096
	ds_read_b128 v[206:209], v189 offset:5120
	ds_read_b128 v[210:213], v189 offset:6144
	ds_read_b128 v[214:217], v189 offset:7168
	s_add_i32 s72, s48, 2
	s_add_u32 s8, s46, 0x100
	s_addc_u32 s9, s47, 0
	s_add_i32 s0, 0, 0x10000
	s_cmp_eq_u32 s41, s48
	s_cselect_b32 s51, s43, s9
	s_cselect_b32 s50, s42, s8
	s_cselect_b32 s49, s45, s71
	s_cselect_b32 s48, s44, s70
	s_add_i32 s73, 0, 0x14000
	v_lshl_add_u64 v[194:195], s[46:47], 0, v[162:163]
	s_add_i32 m0, s27, 0xc000
	s_nop 0
	global_load_lds_dwordx4 v[194:195], off
	v_lshl_add_u64 v[194:195], s[46:47], 0, v[160:161]
	s_add_i32 m0, s27, 0xe000
	s_nop 0
	global_load_lds_dwordx4 v[194:195], off
	s_waitcnt vmcnt(8)
	s_waitcnt lgkmcnt(0)
	s_setprio 1
	s_barrier
	v_mfma_f32_16x16x32_bf16 v[126:129], v[130:133], v[176:179], v[126:129]
	v_mfma_f32_16x16x32_bf16 v[122:125], v[138:141], v[176:179], v[122:125]
	v_mfma_f32_16x16x32_bf16 v[110:113], v[130:133], v[184:187], v[110:113]
	v_mfma_f32_16x16x32_bf16 v[106:109], v[138:141], v[184:187], v[106:109]
	v_mfma_f32_16x16x32_bf16 v[98:101], v[130:133], v[202:205], v[98:101]
	v_mfma_f32_16x16x32_bf16 v[90:93], v[138:141], v[202:205], v[90:93]
	v_mfma_f32_16x16x32_bf16 v[82:85], v[130:133], v[210:213], v[82:85]
	v_mfma_f32_16x16x32_bf16 v[74:77], v[138:141], v[210:213], v[74:77]
	v_mfma_f32_16x16x32_bf16 v[126:129], v[134:137], v[180:183], v[126:129]
	v_mfma_f32_16x16x32_bf16 v[122:125], v[142:145], v[180:183], v[122:125]
	v_mfma_f32_16x16x32_bf16 v[110:113], v[134:137], v[190:193], v[110:113]
	v_mfma_f32_16x16x32_bf16 v[106:109], v[142:145], v[190:193], v[106:109]
	v_mfma_f32_16x16x32_bf16 v[98:101], v[134:137], v[206:209], v[98:101]
	v_mfma_f32_16x16x32_bf16 v[90:93], v[142:145], v[206:209], v[90:93]
	v_mfma_f32_16x16x32_bf16 v[82:85], v[134:137], v[214:217], v[82:85]
	v_mfma_f32_16x16x32_bf16 v[74:77], v[142:145], v[214:217], v[74:77]
	v_mfma_f32_16x16x32_bf16 v[118:121], v[146:149], v[176:179], v[118:121]
	v_mfma_f32_16x16x32_bf16 v[114:117], v[168:171], v[176:179], v[114:117]
	v_mfma_f32_16x16x32_bf16 v[102:105], v[146:149], v[184:187], v[102:105]
	v_mfma_f32_16x16x32_bf16 v[94:97], v[168:171], v[184:187], v[94:97]
	v_mfma_f32_16x16x32_bf16 v[86:89], v[146:149], v[202:205], v[86:89]
	v_mfma_f32_16x16x32_bf16 v[78:81], v[168:171], v[202:205], v[78:81]
	v_mfma_f32_16x16x32_bf16 v[70:73], v[146:149], v[210:213], v[70:73]
	v_mfma_f32_16x16x32_bf16 v[66:69], v[168:171], v[210:213], v[66:69]
	v_mfma_f32_16x16x32_bf16 v[118:121], v[164:167], v[180:183], v[118:121]
	v_mfma_f32_16x16x32_bf16 v[114:117], v[172:175], v[180:183], v[114:117]
	v_mfma_f32_16x16x32_bf16 v[102:105], v[164:167], v[190:193], v[102:105]
	v_mfma_f32_16x16x32_bf16 v[94:97], v[172:175], v[190:193], v[94:97]
	v_mfma_f32_16x16x32_bf16 v[86:89], v[164:167], v[206:209], v[86:89]
	v_mfma_f32_16x16x32_bf16 v[78:81], v[172:175], v[206:209], v[78:81]
	v_mfma_f32_16x16x32_bf16 v[70:73], v[164:167], v[214:217], v[70:73]
	v_mfma_f32_16x16x32_bf16 v[66:69], v[172:175], v[214:217], v[66:69]
	s_barrier
	s_setprio 0
	ds_read_b128 v[176:179], v189 offset:16384
	ds_read_b128 v[180:183], v189 offset:17408
	ds_read_b128 v[184:187], v189 offset:18432
	ds_read_b128 v[190:193], v189 offset:19456
	ds_read_b128 v[202:205], v189 offset:20480
	ds_read_b128 v[206:209], v189 offset:21504
	ds_read_b128 v[210:213], v189 offset:22528
	ds_read_b128 v[214:217], v189 offset:23552
	s_add_i32 s0, s0, s26
	s_add_u32 s98, s48, s16
	s_addc_u32 s99, s49, s17
	s_mov_b32 m0, s0
	s_nop 0
	global_load_lds_dwordx4 v196, s[48:49]
	s_add_i32 m0, s0, 0x2000
	s_add_u32 s0, s48, 0x158000
	s_addc_u32 s1, s49, 0
	s_add_i32 s46, s73, s26
	global_load_lds_dwordx4 v154, s[48:49]
	s_mov_b32 m0, s46
	s_nop 0
	global_load_lds_dwordx4 v196, s[0:1]
	s_add_i32 m0, s46, 0x2000
	s_nop 0
	global_load_lds_dwordx4 v154, s[0:1]
	s_add_u32 s78, s50, s16
	s_addc_u32 s79, s51, s17
	s_mov_b32 m0, s27
	s_nop 0
	global_load_lds_dwordx4 v150, s[50:51]
	s_mov_b32 m0, s30
	s_nop 0
	global_load_lds_dwordx4 v152, s[50:51]
	s_waitcnt vmcnt(8)
	s_waitcnt lgkmcnt(0)
	s_setprio 1
	s_barrier
	v_mfma_f32_16x16x32_bf16 v[62:65], v[130:133], v[176:179], v[62:65]
	v_mfma_f32_16x16x32_bf16 v[58:61], v[138:141], v[176:179], v[58:61]
	v_mfma_f32_16x16x32_bf16 v[50:53], v[130:133], v[184:187], v[50:53]
	v_mfma_f32_16x16x32_bf16 v[42:45], v[138:141], v[184:187], v[42:45]
	v_mfma_f32_16x16x32_bf16 v[34:37], v[130:133], v[202:205], v[34:37]
	v_mfma_f32_16x16x32_bf16 v[26:29], v[138:141], v[202:205], v[26:29]
	v_mfma_f32_16x16x32_bf16 v[18:21], v[130:133], v[210:213], v[18:21]
	v_mfma_f32_16x16x32_bf16 v[10:13], v[138:141], v[210:213], v[10:13]
	v_mfma_f32_16x16x32_bf16 v[62:65], v[134:137], v[180:183], v[62:65]
	v_mfma_f32_16x16x32_bf16 v[58:61], v[142:145], v[180:183], v[58:61]
	v_mfma_f32_16x16x32_bf16 v[50:53], v[134:137], v[190:193], v[50:53]
	v_mfma_f32_16x16x32_bf16 v[42:45], v[142:145], v[190:193], v[42:45]
	v_mfma_f32_16x16x32_bf16 v[34:37], v[134:137], v[206:209], v[34:37]
	v_mfma_f32_16x16x32_bf16 v[26:29], v[142:145], v[206:209], v[26:29]
	v_mfma_f32_16x16x32_bf16 v[18:21], v[134:137], v[214:217], v[18:21]
	v_mfma_f32_16x16x32_bf16 v[10:13], v[142:145], v[214:217], v[10:13]
	v_mfma_f32_16x16x32_bf16 v[54:57], v[146:149], v[176:179], v[54:57]
	v_mfma_f32_16x16x32_bf16 v[46:49], v[168:171], v[176:179], v[46:49]
	v_mfma_f32_16x16x32_bf16 v[38:41], v[146:149], v[184:187], v[38:41]
	v_mfma_f32_16x16x32_bf16 v[30:33], v[168:171], v[184:187], v[30:33]
	v_mfma_f32_16x16x32_bf16 v[22:25], v[146:149], v[202:205], v[22:25]
	v_mfma_f32_16x16x32_bf16 v[14:17], v[168:171], v[202:205], v[14:17]
	v_mfma_f32_16x16x32_bf16 v[6:9], v[146:149], v[210:213], v[6:9]
	v_mfma_f32_16x16x32_bf16 v[2:5], v[168:171], v[210:213], v[2:5]
	v_mfma_f32_16x16x32_bf16 v[54:57], v[164:167], v[180:183], v[54:57]
	v_mfma_f32_16x16x32_bf16 v[46:49], v[172:175], v[180:183], v[46:49]
	v_mfma_f32_16x16x32_bf16 v[38:41], v[164:167], v[190:193], v[38:41]
	v_mfma_f32_16x16x32_bf16 v[30:33], v[172:175], v[190:193], v[30:33]
	v_mfma_f32_16x16x32_bf16 v[22:25], v[164:167], v[206:209], v[22:25]
	v_mfma_f32_16x16x32_bf16 v[14:17], v[172:175], v[206:209], v[14:17]
	v_mfma_f32_16x16x32_bf16 v[6:9], v[164:167], v[214:217], v[6:9]
	v_mfma_f32_16x16x32_bf16 v[2:5], v[172:175], v[214:217], v[2:5]
	s_barrier
	s_setprio 0
.Lkmid_6:
	ds_read_b128 v[130:133], v250 offset:32768
	ds_read_b128 v[134:137], v250 offset:33792
	ds_read_b128 v[138:141], v250 offset:34816
	ds_read_b128 v[142:145], v250 offset:35840
	ds_read_b128 v[146:149], v250 offset:49152
	ds_read_b128 v[164:167], v250 offset:50176
	ds_read_b128 v[168:171], v250 offset:51200
	ds_read_b128 v[172:175], v250 offset:52224
	ds_read_b128 v[176:179], v189 offset:32768
	ds_read_b128 v[180:183], v189 offset:33792
	ds_read_b128 v[184:187], v189 offset:34816
	ds_read_b128 v[190:193], v189 offset:35840
	ds_read_b128 v[202:205], v189 offset:36864
	ds_read_b128 v[206:209], v189 offset:37888
	ds_read_b128 v[210:213], v189 offset:38912
	ds_read_b128 v[214:217], v189 offset:39936
	s_add_i32 s46, 0, 0x18000
	s_add_i32 s47, 0, 0x1c000
	s_add_u32 s0, s50, 0x158000
	s_addc_u32 s1, s51, 0
	s_mov_b32 m0, s31
	s_nop 0
	global_load_lds_dwordx4 v150, s[0:1]
	s_mov_b32 m0, s34
	s_nop 0
	global_load_lds_dwordx4 v152, s[0:1]
	s_waitcnt vmcnt(8)
	s_waitcnt lgkmcnt(0)
	s_setprio 1
	s_barrier
	v_mfma_f32_16x16x32_bf16 v[126:129], v[130:133], v[176:179], v[126:129]
	v_mfma_f32_16x16x32_bf16 v[122:125], v[138:141], v[176:179], v[122:125]
	v_mfma_f32_16x16x32_bf16 v[110:113], v[130:133], v[184:187], v[110:113]
	v_mfma_f32_16x16x32_bf16 v[106:109], v[138:141], v[184:187], v[106:109]
	v_mfma_f32_16x16x32_bf16 v[98:101], v[130:133], v[202:205], v[98:101]
	v_mfma_f32_16x16x32_bf16 v[90:93], v[138:141], v[202:205], v[90:93]
	v_mfma_f32_16x16x32_bf16 v[82:85], v[130:133], v[210:213], v[82:85]
	v_mfma_f32_16x16x32_bf16 v[74:77], v[138:141], v[210:213], v[74:77]
	v_mfma_f32_16x16x32_bf16 v[126:129], v[134:137], v[180:183], v[126:129]
	v_mfma_f32_16x16x32_bf16 v[122:125], v[142:145], v[180:183], v[122:125]
	v_mfma_f32_16x16x32_bf16 v[110:113], v[134:137], v[190:193], v[110:113]
	v_mfma_f32_16x16x32_bf16 v[106:109], v[142:145], v[190:193], v[106:109]
	v_mfma_f32_16x16x32_bf16 v[98:101], v[134:137], v[206:209], v[98:101]
	v_mfma_f32_16x16x32_bf16 v[90:93], v[142:145], v[206:209], v[90:93]
	v_mfma_f32_16x16x32_bf16 v[82:85], v[134:137], v[214:217], v[82:85]
	v_mfma_f32_16x16x32_bf16 v[74:77], v[142:145], v[214:217], v[74:77]
	v_mfma_f32_16x16x32_bf16 v[118:121], v[146:149], v[176:179], v[118:121]
	v_mfma_f32_16x16x32_bf16 v[114:117], v[168:171], v[176:179], v[114:117]
	v_mfma_f32_16x16x32_bf16 v[102:105], v[146:149], v[184:187], v[102:105]
	v_mfma_f32_16x16x32_bf16 v[94:97], v[168:171], v[184:187], v[94:97]
	v_mfma_f32_16x16x32_bf16 v[86:89], v[146:149], v[202:205], v[86:89]
	v_mfma_f32_16x16x32_bf16 v[78:81], v[168:171], v[202:205], v[78:81]
	v_mfma_f32_16x16x32_bf16 v[70:73], v[146:149], v[210:213], v[70:73]
	v_mfma_f32_16x16x32_bf16 v[66:69], v[168:171], v[210:213], v[66:69]
	v_mfma_f32_16x16x32_bf16 v[118:121], v[164:167], v[180:183], v[118:121]
	v_mfma_f32_16x16x32_bf16 v[114:117], v[172:175], v[180:183], v[114:117]
	v_mfma_f32_16x16x32_bf16 v[102:105], v[164:167], v[190:193], v[102:105]
	v_mfma_f32_16x16x32_bf16 v[94:97], v[172:175], v[190:193], v[94:97]
	v_mfma_f32_16x16x32_bf16 v[86:89], v[164:167], v[206:209], v[86:89]
	v_mfma_f32_16x16x32_bf16 v[78:81], v[172:175], v[206:209], v[78:81]
	v_mfma_f32_16x16x32_bf16 v[70:73], v[164:167], v[214:217], v[70:73]
	v_mfma_f32_16x16x32_bf16 v[66:69], v[172:175], v[214:217], v[66:69]
	s_barrier
	s_setprio 0
	ds_read_b128 v[176:179], v189 offset:49152
	ds_read_b128 v[180:183], v189 offset:50176
	ds_read_b128 v[184:187], v189 offset:51200
	ds_read_b128 v[190:193], v189 offset:52224
	ds_read_b128 v[202:205], v189 offset:53248
	ds_read_b128 v[206:209], v189 offset:54272
	ds_read_b128 v[210:213], v189 offset:55296
	ds_read_b128 v[214:217], v189 offset:56320
	s_add_i32 s0, s46, s26
	s_mov_b32 m0, s0
	s_nop 0
	global_load_lds_dwordx4 v196, s[98:99]
	s_add_i32 m0, s0, 0x2000
	s_add_u32 s0, s48, 0x158080
	s_addc_u32 s1, s49, 0
	s_add_i32 s46, s47, s26
	global_load_lds_dwordx4 v154, s[98:99]
	s_mov_b32 m0, s46
	s_nop 0
	global_load_lds_dwordx4 v196, s[0:1]
	s_add_i32 m0, s46, 0x2000
	s_nop 0
	global_load_lds_dwordx4 v154, s[0:1]
	s_mov_b32 m0, s53
	s_nop 0
	global_load_lds_dwordx4 v150, s[78:79]
	s_mov_b32 m0, s58
	s_nop 0
	global_load_lds_dwordx4 v152, s[78:79]
	s_waitcnt vmcnt(8)
	s_waitcnt lgkmcnt(0)
	s_setprio 1
	s_barrier
	v_mfma_f32_16x16x32_bf16 v[62:65], v[130:133], v[176:179], v[62:65]
	v_mfma_f32_16x16x32_bf16 v[58:61], v[138:141], v[176:179], v[58:61]
	v_mfma_f32_16x16x32_bf16 v[50:53], v[130:133], v[184:187], v[50:53]
	v_mfma_f32_16x16x32_bf16 v[42:45], v[138:141], v[184:187], v[42:45]
	v_mfma_f32_16x16x32_bf16 v[34:37], v[130:133], v[202:205], v[34:37]
	v_mfma_f32_16x16x32_bf16 v[26:29], v[138:141], v[202:205], v[26:29]
	v_mfma_f32_16x16x32_bf16 v[18:21], v[130:133], v[210:213], v[18:21]
	v_mfma_f32_16x16x32_bf16 v[10:13], v[138:141], v[210:213], v[10:13]
	v_mfma_f32_16x16x32_bf16 v[62:65], v[134:137], v[180:183], v[62:65]
	v_mfma_f32_16x16x32_bf16 v[58:61], v[142:145], v[180:183], v[58:61]
	v_mfma_f32_16x16x32_bf16 v[50:53], v[134:137], v[190:193], v[50:53]
	v_mfma_f32_16x16x32_bf16 v[42:45], v[142:145], v[190:193], v[42:45]
	v_mfma_f32_16x16x32_bf16 v[34:37], v[134:137], v[206:209], v[34:37]
	v_mfma_f32_16x16x32_bf16 v[26:29], v[142:145], v[206:209], v[26:29]
	v_mfma_f32_16x16x32_bf16 v[18:21], v[134:137], v[214:217], v[18:21]
	v_mfma_f32_16x16x32_bf16 v[10:13], v[142:145], v[214:217], v[10:13]
	v_mfma_f32_16x16x32_bf16 v[54:57], v[146:149], v[176:179], v[54:57]
	v_mfma_f32_16x16x32_bf16 v[46:49], v[168:171], v[176:179], v[46:49]
	v_mfma_f32_16x16x32_bf16 v[38:41], v[146:149], v[184:187], v[38:41]
	v_mfma_f32_16x16x32_bf16 v[30:33], v[168:171], v[184:187], v[30:33]
	v_mfma_f32_16x16x32_bf16 v[22:25], v[146:149], v[202:205], v[22:25]
	v_mfma_f32_16x16x32_bf16 v[14:17], v[168:171], v[202:205], v[14:17]
	v_mfma_f32_16x16x32_bf16 v[6:9], v[146:149], v[210:213], v[6:9]
	v_mfma_f32_16x16x32_bf16 v[2:5], v[168:171], v[210:213], v[2:5]
	v_mfma_f32_16x16x32_bf16 v[54:57], v[164:167], v[180:183], v[54:57]
	v_mfma_f32_16x16x32_bf16 v[46:49], v[172:175], v[180:183], v[46:49]
	v_mfma_f32_16x16x32_bf16 v[38:41], v[164:167], v[190:193], v[38:41]
	v_mfma_f32_16x16x32_bf16 v[30:33], v[172:175], v[190:193], v[30:33]
	v_mfma_f32_16x16x32_bf16 v[22:25], v[164:167], v[206:209], v[22:25]
	v_mfma_f32_16x16x32_bf16 v[14:17], v[172:175], v[206:209], v[14:17]
	v_mfma_f32_16x16x32_bf16 v[6:9], v[164:167], v[214:217], v[6:9]
	v_mfma_f32_16x16x32_bf16 v[2:5], v[172:175], v[214:217], v[2:5]
	s_barrier
	s_setprio 0
	s_add_u32 s70, s70, 0x100
	s_addc_u32 s71, s71, 0
	s_cmp_ge_i32 s72, s69
	s_mov_b64 s[46:47], s[8:9]
	s_mov_b32 s48, s72
	s_cbranch_scc0 .LBB0_2588
	s_and_b64 vcc, exec, s[28:29]
	s_cbranch_vccz .LBB0_2591
	s_barrier
